# adds: deferred generic GEMM1 epilogue stores into next tile phases, PEEL-lite staging, seg1 rotary table-load hoist, NSA first K-fragment LDS reads hoisted above DMA issue
# speedup vs baseline: 1.0083x; 1.0083x over previous
; #define LAS __attribute__((address_space(3)))
;   DI bool next(int i, GUnit& u) const { if (i != 0) return false; u.A = A; u.B = B; u.pm = pm; u.pn = pn; u.seg = 8; u.bmode = 1; return true; }
;   DI bool next(int i, GUnit& u) const {
;     int kind, mt, nt;
;     if (G == 256) {
;       if (i < 12) { const int xcd = b & 7, l = b >> 3; const int st = i * 8 + xcd; const int mg = st / 3, ng = st % 3; kind = 0; mt = mg * 4 + (l & 3); nt = ng * 8 + (l >> 2); }
;       else return false;
;     } else {
;       const int L = i * G + b;
;       if (L < 3072) { kind = 0; mt = L / 24; nt = L % 24; }
;       else return false;
;     }
;     u.pm = mt; u.pn = nt;
; DI void phase_gemm1(const Params& p, char* smem) {
;   Sched1 S; S.H = (const char*)p.out; S.W = p.ws + WS_WINT; S.MEMN = p.ws + WS_MEMN; S.WMEM = p.ws + WS_WMEMT; S.b = blockIdx.x; S.G = gridDim.x;
;   Epi1 E; E.Z = (f16*)(p.ws + WS_Z); E.KVM = (f16*)(p.ws + WS_KVM); E.GATES = (float*)(p.ws + WS_GATES); E.ROT = (const float*)(p.ws + WS_ROT);
;   gemm_stream<false>((LAS unsigned char*)smem, 1024, 2048, 2048, S, E);
.LBB0_165:
	s_or_b64 exec, exec, s[0:1]
	s_mov_b32 s100, 0
	s_add_u32 s3, s70, 0x18300000
	s_addc_u32 s25, s71, 0
	v_mov_b32_e32 v140, v0
	s_cmpk_lg_i32 s33, 0x100
	v_writelane_b32 v255, s56, 9
	s_waitcnt lgkmcnt(0)
	s_barrier
	s_cselect_b64 s[38:39], -1, 0
	v_and_b32_e32 v130, 0x1ff, v140
	v_writelane_b32 v255, s57, 10
	v_readfirstlane_b32 s50, v130
	s_and_b64 vcc, exec, s[38:39]
	s_cbranch_vccz .LBB0_171
	s_mov_b64 s[4:5], 0
	s_cmpk_lt_i32 s2, 0xc00
	s_mov_b64 s[0:1], 0
	s_cbranch_scc0 .LBB0_168
	s_mul_hi_i32 s0, s2, 0x2aaaaaab
	s_lshr_b32 s1, s0, 31
	s_ashr_i32 s0, s0, 2
	s_add_i32 s42, s0, s1
	s_mul_i32 s0, s42, 24
	s_sub_i32 s88, s2, s0
	s_mov_b64 s[0:1], -1
	s_and_b64 vcc, exec, s[4:5]
	s_cbranch_vccz .LBB0_172
	s_branch .LBB0_169

; DI unsigned pk2(float a, float b) { typedef _Float16 h2 __attribute__((ext_vector_type(2))); h2 v; v[0] = (f16)a; v[1] = (f16)b; return __builtin_bit_cast(unsigned, v); }
;   DI void operator()(const f32x4 (&acc)[2][2][4][2], const GUnit& u, int wr, int wc, int fr, int fq) const {
;     ...
; #pragma unroll
;     for (int ai = 0; ai < 2; ++ai)
; #pragma unroll
;       for (int m = 0; m < 4; ++m) {
;         f16* zp = base + (size_t)(row0 + ai * 128 + m * 16) * ld + u.pn * 256 + 32 * wc + 8 * fq;
; #pragma unroll
;         for (int bj = 0; bj < 2; ++bj) {
;           f32x4 v0 = acc[ai][bj][m][0], v1 = acc[ai][bj][m][1];
;           if (seg == 5) { v0 *= QSCALE; v1 *= QSCALE; }
;           u32x4_ w; w.x = pk2(v0[0], v0[1]); w.y = pk2(v0[2], v0[3]); w.z = pk2(v1[0], v1[1]); w.w = pk2(v1[2], v1[3]);
;           __builtin_nontemporal_store(w, (u32x4_*)(zp + bj * 128));
;         }
;       }
.LBB0_254:
	v_or_b32_e32 v130, 0x10000, v168
	v_add_u32_e32 v134, 0x10400, v168
	v_add_u32_e32 v138, 0x10800, v168
	v_add_u32_e32 v142, 0x10c00, v168
	ds_read_b128 v[130:133], v130
	ds_read_b128 v[134:137], v134
	ds_read_b128 v[138:141], v138
	ds_read_b128 v[142:145], v142
	s_add_u32 s94, s44, 0xfffc0080
	s_addc_u32 s95, s45, -1
	s_and_b64 s[46:47], s[46:47], exec
	s_cselect_b32 s95, s29, s95
	s_cselect_b32 s94, s43, s94
	s_cselect_b32 s47, s89, s92
	s_cselect_b32 s46, s90, s91
	s_mov_b32 m0, s79
	v_lshl_add_u64 v[162:163], s[44:45], 0, v[160:161]
	ds_read_b128 v[170:173], v165
	ds_read_b128 v[174:177], v165 offset:1024
	ds_read_b128 v[178:181], v165 offset:2048
	ds_read_b128 v[182:185], v165 offset:3072
	ds_read_b128 v[186:189], v165 offset:4096
	ds_read_b128 v[190:193], v165 offset:5120
	ds_read_b128 v[194:197], v165 offset:6144
	ds_read_b128 v[198:201], v165 offset:7168
	s_cmp_lg_u32 s93, -2
	s_cbranch_scc1 .Lpl_stage1
	s_cmp_gt_u32 s85, 1
	s_cbranch_scc1 .Lpl_skip1
.Lpl_stage1:
	global_load_lds_dwordx4 v[162:163], off
	v_lshl_add_u64 v[162:163], v[162:163], 0, s[0:1]
	s_mov_b32 m0, s80
	s_nop 0
	global_load_lds_dwordx4 v[162:163], off
.Lpl_skip1:
	s_waitcnt lgkmcnt(8)
	s_barrier
	s_waitcnt lgkmcnt(0)
	s_setprio 1
	s_waitcnt lgkmcnt(0)
	v_mfma_f32_16x16x32_f16 v[58:61], v[130:133], v[170:173], v[58:61]
	v_mfma_f32_16x16x32_f16 v[62:65], v[138:141], v[170:173], v[62:65]
	v_mfma_f32_16x16x32_f16 v[50:53], v[130:133], v[178:181], v[50:53]
	v_mfma_f32_16x16x32_f16 v[54:57], v[138:141], v[178:181], v[54:57]
	v_mfma_f32_16x16x32_f16 v[42:45], v[130:133], v[186:189], v[42:45]
	v_mfma_f32_16x16x32_f16 v[46:49], v[138:141], v[186:189], v[46:49]
	v_mfma_f32_16x16x32_f16 v[26:29], v[130:133], v[194:197], v[26:29]
	v_mfma_f32_16x16x32_f16 v[30:33], v[138:141], v[194:197], v[30:33]
	v_mfma_f32_16x16x32_f16 v[58:61], v[134:137], v[174:177], v[58:61]
	v_mfma_f32_16x16x32_f16 v[62:65], v[142:145], v[174:177], v[62:65]
	v_mfma_f32_16x16x32_f16 v[50:53], v[134:137], v[182:185], v[50:53]
	v_mfma_f32_16x16x32_f16 v[54:57], v[142:145], v[182:185], v[54:57]
	v_mfma_f32_16x16x32_f16 v[42:45], v[134:137], v[190:193], v[42:45]
	v_mfma_f32_16x16x32_f16 v[46:49], v[142:145], v[190:193], v[46:49]
	v_mfma_f32_16x16x32_f16 v[26:29], v[134:137], v[198:201], v[26:29]
	v_mfma_f32_16x16x32_f16 v[30:33], v[142:145], v[198:201], v[30:33]
	s_setprio 0
	s_barrier
	v_or_b32_e32 v162, 0x14000, v168
	s_mov_b32 m0, s54
	v_add_u32_e32 v163, 0x14400, v168
	ds_read_b128 v[202:205], v162
	ds_read_b128 v[206:209], v163
	v_add_u32_e32 v162, 0x14800, v168
	s_add_u32 s96, s46, s30
	v_add_u32_e32 v163, 0x14c00, v168
	ds_read_b128 v[210:213], v162
	ds_read_b128 v[214:217], v163
	global_load_lds_dwordx4 v148, s[46:47]
	s_addc_u32 s97, s47, s31
	s_mov_b32 m0, s55
	v_lshl_add_u64 v[162:163], s[46:47], 0, v[148:149]
	global_load_lds_dwordx4 v148, s[96:97]
	s_barrier
	s_waitcnt lgkmcnt(0)
	v_lshl_add_u64 v[166:167], s[96:97], 0, v[148:149]
	s_setprio 1
	s_waitcnt lgkmcnt(0)
	v_mfma_f32_16x16x32_f16 v[122:125], v[202:205], v[170:173], v[122:125]
	v_mfma_f32_16x16x32_f16 v[126:129], v[210:213], v[170:173], v[126:129]
	v_mfma_f32_16x16x32_f16 v[114:117], v[202:205], v[178:181], v[114:117]
	v_mfma_f32_16x16x32_f16 v[118:121], v[210:213], v[178:181], v[118:121]
	v_mfma_f32_16x16x32_f16 v[106:109], v[202:205], v[186:189], v[106:109]
	v_mfma_f32_16x16x32_f16 v[110:113], v[210:213], v[186:189], v[110:113]
	v_mfma_f32_16x16x32_f16 v[98:101], v[202:205], v[194:197], v[98:101]
	v_mfma_f32_16x16x32_f16 v[102:105], v[210:213], v[194:197], v[102:105]
	v_mfma_f32_16x16x32_f16 v[122:125], v[206:209], v[174:177], v[122:125]
	v_mfma_f32_16x16x32_f16 v[126:129], v[214:217], v[174:177], v[126:129]
	v_mfma_f32_16x16x32_f16 v[114:117], v[206:209], v[182:185], v[114:117]
	v_mfma_f32_16x16x32_f16 v[118:121], v[214:217], v[182:185], v[118:121]
	v_mfma_f32_16x16x32_f16 v[106:109], v[206:209], v[190:193], v[106:109]
	v_mfma_f32_16x16x32_f16 v[110:113], v[214:217], v[190:193], v[110:113]
	v_mfma_f32_16x16x32_f16 v[98:101], v[206:209], v[198:201], v[98:101]
	v_mfma_f32_16x16x32_f16 v[102:105], v[214:217], v[198:201], v[102:105]
	s_setprio 0
	s_mov_b32 m0, s51
	v_lshl_add_u64 v[218:219], s[94:95], 0, v[146:147]
	s_barrier
	s_cmp_lg_u32 s100, 1
	s_cbranch_scc1 .Ldef_A_skip
	s_mov_b64 vcc, 0x30000
	v_cvt_pk_f16_f32 v242, v34, v35
	v_cvt_pk_f16_f32 v243, v36, v37
	v_cvt_pk_f16_f32 v244, v38, v39
	v_cvt_pk_f16_f32 v245, v40, v41
	global_store_dwordx4 v[240:241], v[242:245], off nt
	v_cvt_pk_f16_f32 v246, v18, v19
	v_cvt_pk_f16_f32 v247, v20, v21
	v_cvt_pk_f16_f32 v248, v22, v23
	v_cvt_pk_f16_f32 v249, v24, v25
	v_lshl_add_u64 v[250:251], v[240:241], 0, vcc
	global_store_dwordx4 v[250:251], v[246:249], off nt
	v_cvt_pk_f16_f32 v242, v10, v11
	v_cvt_pk_f16_f32 v243, v12, v13
	v_cvt_pk_f16_f32 v244, v14, v15
	v_cvt_pk_f16_f32 v245, v16, v17
	v_lshl_add_u64 v[252:253], v[250:251], 0, vcc
	global_store_dwordx4 v[252:253], v[242:245], off nt
	v_cvt_pk_f16_f32 v246, v2, v3
	v_cvt_pk_f16_f32 v247, v4, v5
	v_cvt_pk_f16_f32 v248, v6, v7
	v_cvt_pk_f16_f32 v249, v8, v9
	v_lshl_add_u64 v[250:251], v[252:253], 0, vcc
	global_store_dwordx4 v[250:251], v[246:249], off nt
	v_mov_b64_e32 v[2:3], 0
	v_mov_b64_e32 v[4:5], 0
	v_mov_b64_e32 v[6:7], 0
	v_mov_b64_e32 v[8:9], 0
	v_mov_b64_e32 v[10:11], 0
	v_mov_b64_e32 v[12:13], 0
	v_mov_b64_e32 v[14:15], 0
	v_mov_b64_e32 v[16:17], 0
	v_mov_b64_e32 v[18:19], 0
	v_mov_b64_e32 v[20:21], 0
	v_mov_b64_e32 v[22:23], 0
	v_mov_b64_e32 v[24:25], 0
	v_mov_b64_e32 v[34:35], 0
	v_mov_b64_e32 v[36:37], 0
	v_mov_b64_e32 v[38:39], 0
	v_mov_b64_e32 v[40:41], 0
; DI unsigned pk2(float a, float b) { typedef _Float16 h2 __attribute__((ext_vector_type(2))); h2 v; v[0] = (f16)a; v[1] = (f16)b; return __builtin_bit_cast(unsigned, v); }
;   DI void operator()(const f32x4 (&acc)[2][2][4][2], const GUnit& u, int wr, int wc, int fr, int fq) const {
;     ...
; #pragma unroll
;     for (int ai = 0; ai < 2; ++ai)
; #pragma unroll
;       for (int m = 0; m < 4; ++m) {
;         f16* zp = base + (size_t)(row0 + ai * 128 + m * 16) * ld + u.pn * 256 + 32 * wc + 8 * fq;
; #pragma unroll
;         for (int bj = 0; bj < 2; ++bj) {
;           f32x4 v0 = acc[ai][bj][m][0], v1 = acc[ai][bj][m][1];
;           if (seg == 5) { v0 *= QSCALE; v1 *= QSCALE; }
;           u32x4_ w; w.x = pk2(v0[0], v0[1]); w.y = pk2(v0[2], v0[3]); w.z = pk2(v1[0], v1[1]); w.w = pk2(v1[2], v1[3]);
;           __builtin_nontemporal_store(w, (u32x4_*)(zp + bj * 128));
;         }
;       }
.Ldef_A_skip:
	ds_read_b128 v[170:173], v165 offset:16384
	ds_read_b128 v[174:177], v165 offset:17408
	ds_read_b128 v[178:181], v165 offset:18432
	ds_read_b128 v[182:185], v165 offset:19456
	ds_read_b128 v[186:189], v165 offset:20480
	ds_read_b128 v[190:193], v165 offset:21504
	ds_read_b128 v[194:197], v165 offset:22528
	ds_read_b128 v[198:201], v165 offset:23552
	global_load_lds_dwordx4 v[218:219], off
	v_lshl_add_u64 v[220:221], v[218:219], 0, s[0:1]
	s_mov_b32 m0, s56
	s_nop 0
	global_load_lds_dwordx4 v[220:221], off
	s_barrier
	s_waitcnt lgkmcnt(0)
	s_setprio 1
	s_waitcnt lgkmcnt(0)
	v_mfma_f32_16x16x32_f16 v[34:37], v[130:133], v[170:173], v[34:37]
	v_mfma_f32_16x16x32_f16 v[38:41], v[138:141], v[170:173], v[38:41]
	v_mfma_f32_16x16x32_f16 v[18:21], v[130:133], v[178:181], v[18:21]
	v_mfma_f32_16x16x32_f16 v[22:25], v[138:141], v[178:181], v[22:25]
	v_mfma_f32_16x16x32_f16 v[10:13], v[130:133], v[186:189], v[10:13]
	v_mfma_f32_16x16x32_f16 v[14:17], v[138:141], v[186:189], v[14:17]
	v_mfma_f32_16x16x32_f16 v[2:5], v[130:133], v[194:197], v[2:5]
	v_mfma_f32_16x16x32_f16 v[6:9], v[138:141], v[194:197], v[6:9]
	v_mfma_f32_16x16x32_f16 v[34:37], v[134:137], v[174:177], v[34:37]
	v_mfma_f32_16x16x32_f16 v[38:41], v[142:145], v[174:177], v[38:41]
	v_mfma_f32_16x16x32_f16 v[18:21], v[134:137], v[182:185], v[18:21]
	v_mfma_f32_16x16x32_f16 v[22:25], v[142:145], v[182:185], v[22:25]
	v_mfma_f32_16x16x32_f16 v[10:13], v[134:137], v[190:193], v[10:13]
	v_mfma_f32_16x16x32_f16 v[14:17], v[142:145], v[190:193], v[14:17]
	v_mfma_f32_16x16x32_f16 v[2:5], v[134:137], v[198:201], v[2:5]
	v_mfma_f32_16x16x32_f16 v[6:9], v[142:145], v[198:201], v[6:9]
	s_setprio 0
	s_barrier
	s_cmp_lg_u32 s100, 1
	s_cbranch_scc1 .Ldef_B_skip
	s_mov_b64 vcc, 0x30000
	v_cvt_pk_f16_f32 v242, v90, v91
	v_cvt_pk_f16_f32 v243, v92, v93
	v_cvt_pk_f16_f32 v244, v94, v95
	v_cvt_pk_f16_f32 v245, v96, v97
	global_store_dwordx4 v[240:241], v[242:245], off offset:256 nt
	v_cvt_pk_f16_f32 v246, v82, v83
	v_cvt_pk_f16_f32 v247, v84, v85
	v_cvt_pk_f16_f32 v248, v86, v87
	v_cvt_pk_f16_f32 v249, v88, v89
	v_lshl_add_u64 v[250:251], v[240:241], 0, vcc
	global_store_dwordx4 v[250:251], v[246:249], off offset:256 nt
	v_cvt_pk_f16_f32 v242, v74, v75
	v_cvt_pk_f16_f32 v243, v76, v77
	v_cvt_pk_f16_f32 v244, v78, v79
	v_cvt_pk_f16_f32 v245, v80, v81
	v_lshl_add_u64 v[252:253], v[250:251], 0, vcc
	global_store_dwordx4 v[252:253], v[242:245], off offset:256 nt
	v_cvt_pk_f16_f32 v246, v70, v71
	v_cvt_pk_f16_f32 v247, v72, v73
	v_cvt_pk_f16_f32 v248, v66, v67
	v_cvt_pk_f16_f32 v249, v68, v69
	v_lshl_add_u64 v[250:251], v[252:253], 0, vcc
	global_store_dwordx4 v[250:251], v[246:249], off offset:256 nt
	v_mov_b64_e32 v[66:67], 0
	v_mov_b64_e32 v[68:69], 0
	v_mov_b64_e32 v[70:71], 0
	v_mov_b64_e32 v[72:73], 0
	v_mov_b64_e32 v[74:75], 0
	v_mov_b64_e32 v[76:77], 0
	v_mov_b64_e32 v[78:79], 0
	v_mov_b64_e32 v[80:81], 0
	v_mov_b64_e32 v[82:83], 0
	v_mov_b64_e32 v[84:85], 0
	v_mov_b64_e32 v[86:87], 0
	v_mov_b64_e32 v[88:89], 0
	v_mov_b64_e32 v[90:91], 0
	v_mov_b64_e32 v[92:93], 0
	v_mov_b64_e32 v[94:95], 0
	v_mov_b64_e32 v[96:97], 0
	s_mov_b32 s100, 0
.Ldef_B_skip:
	s_add_u32 s46, s46, s18
	s_addc_u32 s47, s47, s19
	s_mov_b32 m0, s57
	v_lshl_add_u64 v[220:221], s[46:47], 0, v[148:149]
	global_load_lds_dwordx4 v148, s[46:47]
	s_add_u32 s46, s46, s30
	s_addc_u32 s47, s47, s31
	s_mov_b32 m0, s60
	v_lshl_add_u64 v[222:223], s[46:47], 0, v[148:149]
	global_load_lds_dwordx4 v148, s[46:47]
	s_cmp_lg_u32 s93, -2
	s_cbranch_scc1 .Lpl_w6
	s_cmp_gt_u32 s85, 1
	s_cbranch_scc0 .Lpl_w6
	s_waitcnt vmcnt(22)
	s_branch .Lpl_wdone
.Lpl_w6:
	s_waitcnt vmcnt(6)
.Lpl_wdone:
	s_barrier
	s_setprio 1
	v_mfma_f32_16x16x32_f16 v[90:93], v[202:205], v[170:173], v[90:93]
	v_mfma_f32_16x16x32_f16 v[94:97], v[210:213], v[170:173], v[94:97]
	v_mfma_f32_16x16x32_f16 v[82:85], v[202:205], v[178:181], v[82:85]
	v_mfma_f32_16x16x32_f16 v[86:89], v[210:213], v[178:181], v[86:89]
	v_mfma_f32_16x16x32_f16 v[74:77], v[202:205], v[186:189], v[74:77]
	v_mfma_f32_16x16x32_f16 v[78:81], v[210:213], v[186:189], v[78:81]
	v_mfma_f32_16x16x32_f16 v[70:73], v[202:205], v[194:197], v[70:73]
	v_mfma_f32_16x16x32_f16 v[66:69], v[210:213], v[194:197], v[66:69]
	v_mfma_f32_16x16x32_f16 v[90:93], v[206:209], v[174:177], v[90:93]
	v_mfma_f32_16x16x32_f16 v[94:97], v[214:217], v[174:177], v[94:97]
	v_mfma_f32_16x16x32_f16 v[82:85], v[206:209], v[182:185], v[82:85]
	v_mfma_f32_16x16x32_f16 v[86:89], v[214:217], v[182:185], v[86:89]
	v_mfma_f32_16x16x32_f16 v[74:77], v[206:209], v[190:193], v[74:77]
	v_mfma_f32_16x16x32_f16 v[78:81], v[214:217], v[190:193], v[78:81]
	v_mfma_f32_16x16x32_f16 v[70:73], v[206:209], v[198:201], v[70:73]
	v_mfma_f32_16x16x32_f16 v[66:69], v[214:217], v[198:201], v[66:69]
	s_setprio 0
	v_or_b32_e32 v130, 0x18000, v168
	v_add_u32_e32 v134, 0x18400, v168
	v_add_u32_e32 v138, 0x18800, v168
	v_add_u32_e32 v142, 0x18c00, v168
	s_barrier
	ds_read_b128 v[130:133], v130
	ds_read_b128 v[134:137], v134
	ds_read_b128 v[138:141], v138
	ds_read_b128 v[142:145], v142
	s_mov_b32 m0, s61
	v_lshl_add_u64 v[202:203], v[218:219], 0, s[8:9]
	ds_read_b128 v[170:173], v165 offset:32768
	ds_read_b128 v[174:177], v165 offset:33792
	ds_read_b128 v[178:181], v165 offset:34816
	ds_read_b128 v[182:185], v165 offset:35840
	ds_read_b128 v[186:189], v165 offset:36864
	ds_read_b128 v[190:193], v165 offset:37888
	ds_read_b128 v[194:197], v165 offset:38912
	ds_read_b128 v[198:201], v165 offset:39936
	global_load_lds_dwordx4 v[202:203], off
	v_lshl_add_u64 v[202:203], v[218:219], 0, s[12:13]
	s_mov_b32 m0, s62
	s_nop 0
	global_load_lds_dwordx4 v[202:203], off
	s_waitcnt lgkmcnt(8)
	s_barrier
; #define GS_STAGE(bufoff, gbase, voff, step) do { \
;     __builtin_amdgcn_global_load_lds((const unsigned*)((const char*)(gbase) + (voff)), (LAS unsigned*)(lds + (bufoff) + ldsw), 16, 0, 0); \
;     __builtin_amdgcn_global_load_lds((const unsigned*)((const char*)(gbase) + (step) + (voff)), (LAS unsigned*)(lds + (bufoff) + ldsw + 8192), 16, 0, 0); } while (0)
; #define GS_WAIT_V(n) asm volatile("s_waitcnt vmcnt(" #n ")" ::: "memory")
; template <bool PEEL, class Sched, class Epi>
; DI void gemm_stream(LAS unsigned char* lds, int K, long lda, long ldb, const Sched& S, const Epi& E) {
;     ...
;     if (PEEL) { GS_TRIP(0, 1); for (int t = 2; t < nt; t += 2) { GS_TRIP(t, 0); } }
;     ...
;     if (PEEL && has_next) {
;       GS_STAGE(GS_SA(1, 1), nA + kstep + hstepA, voffA, stepA);
;       GS_WAIT_V(0);
;     }
	s_waitcnt lgkmcnt(0)
	s_setprio 1
	s_waitcnt lgkmcnt(0)
	v_mfma_f32_16x16x32_f16 v[58:61], v[130:133], v[170:173], v[58:61]
	v_mfma_f32_16x16x32_f16 v[62:65], v[138:141], v[170:173], v[62:65]
	v_mfma_f32_16x16x32_f16 v[50:53], v[130:133], v[178:181], v[50:53]
	v_mfma_f32_16x16x32_f16 v[54:57], v[138:141], v[178:181], v[54:57]
	v_mfma_f32_16x16x32_f16 v[42:45], v[130:133], v[186:189], v[42:45]
	v_mfma_f32_16x16x32_f16 v[46:49], v[138:141], v[186:189], v[46:49]
	v_mfma_f32_16x16x32_f16 v[26:29], v[130:133], v[194:197], v[26:29]
	v_mfma_f32_16x16x32_f16 v[30:33], v[138:141], v[194:197], v[30:33]
	v_mfma_f32_16x16x32_f16 v[58:61], v[134:137], v[174:177], v[58:61]
	v_mfma_f32_16x16x32_f16 v[62:65], v[142:145], v[174:177], v[62:65]
	v_mfma_f32_16x16x32_f16 v[50:53], v[134:137], v[182:185], v[50:53]
	v_mfma_f32_16x16x32_f16 v[54:57], v[142:145], v[182:185], v[54:57]
	v_mfma_f32_16x16x32_f16 v[42:45], v[134:137], v[190:193], v[42:45]
	v_mfma_f32_16x16x32_f16 v[46:49], v[142:145], v[190:193], v[46:49]
	v_mfma_f32_16x16x32_f16 v[26:29], v[134:137], v[198:201], v[26:29]
	v_mfma_f32_16x16x32_f16 v[30:33], v[142:145], v[198:201], v[30:33]
	s_setprio 0
	s_barrier
	v_or_b32_e32 v164, 0x1c000, v168
	v_add_u32_e32 v206, 0x1c400, v168
	s_mov_b32 m0, s63
	ds_read_b128 v[202:205], v164
	ds_read_b128 v[206:209], v206
	v_add_u32_e32 v164, 0x1c800, v168
	v_add_u32_e32 v214, 0x1cc00, v168
	v_lshl_add_u64 v[162:163], v[162:163], 0, s[14:15]
	ds_read_b128 v[210:213], v164
	ds_read_b128 v[214:217], v214
	global_load_lds_dwordx4 v[162:163], off
	v_lshl_add_u64 v[162:163], v[166:167], 0, s[14:15]
	s_mov_b32 m0, s64
	s_nop 0
	global_load_lds_dwordx4 v[162:163], off
	s_barrier
	s_waitcnt lgkmcnt(0)
	s_setprio 1
	s_waitcnt lgkmcnt(0)
	v_mfma_f32_16x16x32_f16 v[122:125], v[202:205], v[170:173], v[122:125]
	v_mfma_f32_16x16x32_f16 v[126:129], v[210:213], v[170:173], v[126:129]
	v_mfma_f32_16x16x32_f16 v[114:117], v[202:205], v[178:181], v[114:117]
	v_mfma_f32_16x16x32_f16 v[118:121], v[210:213], v[178:181], v[118:121]
	v_mfma_f32_16x16x32_f16 v[106:109], v[202:205], v[186:189], v[106:109]
	v_mfma_f32_16x16x32_f16 v[110:113], v[210:213], v[186:189], v[110:113]
	v_mfma_f32_16x16x32_f16 v[98:101], v[202:205], v[194:197], v[98:101]
	v_mfma_f32_16x16x32_f16 v[102:105], v[210:213], v[194:197], v[102:105]
	v_mfma_f32_16x16x32_f16 v[122:125], v[206:209], v[174:177], v[122:125]
	v_mfma_f32_16x16x32_f16 v[126:129], v[214:217], v[174:177], v[126:129]
	v_mfma_f32_16x16x32_f16 v[114:117], v[206:209], v[182:185], v[114:117]
	v_mfma_f32_16x16x32_f16 v[118:121], v[214:217], v[182:185], v[118:121]
	v_mfma_f32_16x16x32_f16 v[106:109], v[206:209], v[190:193], v[106:109]
	v_mfma_f32_16x16x32_f16 v[110:113], v[214:217], v[190:193], v[110:113]
	v_mfma_f32_16x16x32_f16 v[98:101], v[206:209], v[198:201], v[98:101]
	v_mfma_f32_16x16x32_f16 v[102:105], v[214:217], v[198:201], v[102:105]
	s_setprio 0
	s_mov_b32 m0, s65
	v_lshl_add_u64 v[162:163], v[218:219], 0, s[14:15]
	s_barrier
	ds_read_b128 v[170:173], v165 offset:49152
	ds_read_b128 v[174:177], v165 offset:50176
	ds_read_b128 v[178:181], v165 offset:51200
	ds_read_b128 v[182:185], v165 offset:52224
	ds_read_b128 v[186:189], v165 offset:53248
	ds_read_b128 v[190:193], v165 offset:54272
	ds_read_b128 v[194:197], v165 offset:55296
	ds_read_b128 v[198:201], v165 offset:56320
	global_load_lds_dwordx4 v[162:163], off
	v_lshl_add_u64 v[162:163], v[218:219], 0, s[16:17]
	s_mov_b32 m0, s72
	s_nop 0
	global_load_lds_dwordx4 v[162:163], off
	s_barrier
	s_waitcnt lgkmcnt(0)
	s_setprio 1
	s_waitcnt lgkmcnt(0)
	v_mfma_f32_16x16x32_f16 v[34:37], v[130:133], v[170:173], v[34:37]
	v_mfma_f32_16x16x32_f16 v[38:41], v[138:141], v[170:173], v[38:41]
	v_mfma_f32_16x16x32_f16 v[18:21], v[130:133], v[178:181], v[18:21]
	v_mfma_f32_16x16x32_f16 v[22:25], v[138:141], v[178:181], v[22:25]
	v_mfma_f32_16x16x32_f16 v[10:13], v[130:133], v[186:189], v[10:13]
	v_mfma_f32_16x16x32_f16 v[14:17], v[138:141], v[186:189], v[14:17]
	v_mfma_f32_16x16x32_f16 v[2:5], v[130:133], v[194:197], v[2:5]
	v_mfma_f32_16x16x32_f16 v[6:9], v[138:141], v[194:197], v[6:9]
	v_mfma_f32_16x16x32_f16 v[34:37], v[134:137], v[174:177], v[34:37]
	v_mfma_f32_16x16x32_f16 v[38:41], v[142:145], v[174:177], v[38:41]
	v_mfma_f32_16x16x32_f16 v[18:21], v[134:137], v[182:185], v[18:21]
	v_mfma_f32_16x16x32_f16 v[22:25], v[142:145], v[182:185], v[22:25]
	v_mfma_f32_16x16x32_f16 v[10:13], v[134:137], v[190:193], v[10:13]
	v_mfma_f32_16x16x32_f16 v[14:17], v[142:145], v[190:193], v[14:17]
	v_mfma_f32_16x16x32_f16 v[2:5], v[134:137], v[198:201], v[2:5]
	v_mfma_f32_16x16x32_f16 v[6:9], v[142:145], v[198:201], v[6:9]
	s_setprio 0
	s_barrier
	s_mov_b32 m0, s73
	v_lshl_add_u64 v[130:131], v[220:221], 0, s[14:15]
	global_load_lds_dwordx4 v[130:131], off
	v_lshl_add_u64 v[130:131], v[222:223], 0, s[14:15]
	s_mov_b32 m0, s74
	s_nop 0
	global_load_lds_dwordx4 v[130:131], off
	s_waitcnt vmcnt(6)
	s_barrier
	s_cmp_lg_u32 s93, 12
	s_cbranch_scc1 .Lpl_skip8
	s_and_b64 vcc, exec, s[6:7]
	s_cbranch_vccz .Lpl_skip8
	s_add_u32 s94, s43, 0x40080
	s_addc_u32 s95, s29, 0
	s_mov_b32 m0, s79
	v_lshl_add_u64 v[130:131], s[94:95], 0, v[160:161]
	global_load_lds_dwordx4 v[130:131], off
	v_lshl_add_u64 v[130:131], v[130:131], 0, s[0:1]
	s_mov_b32 m0, s80
	s_nop 0
	global_load_lds_dwordx4 v[130:131], off
.Lpl_skip8:
	s_setprio 1
	v_mfma_f32_16x16x32_f16 v[90:93], v[202:205], v[170:173], v[90:93]
	v_mfma_f32_16x16x32_f16 v[94:97], v[210:213], v[170:173], v[94:97]
	v_mfma_f32_16x16x32_f16 v[82:85], v[202:205], v[178:181], v[82:85]
	v_mfma_f32_16x16x32_f16 v[86:89], v[210:213], v[178:181], v[86:89]
	v_mfma_f32_16x16x32_f16 v[74:77], v[202:205], v[186:189], v[74:77]
	v_mfma_f32_16x16x32_f16 v[78:81], v[210:213], v[186:189], v[78:81]
	v_mfma_f32_16x16x32_f16 v[70:73], v[202:205], v[194:197], v[70:73]
	v_mfma_f32_16x16x32_f16 v[66:69], v[210:213], v[194:197], v[66:69]
	v_mfma_f32_16x16x32_f16 v[90:93], v[206:209], v[174:177], v[90:93]
	v_mfma_f32_16x16x32_f16 v[94:97], v[214:217], v[174:177], v[94:97]
	v_mfma_f32_16x16x32_f16 v[82:85], v[206:209], v[182:185], v[82:85]
	v_mfma_f32_16x16x32_f16 v[86:89], v[214:217], v[182:185], v[86:89]
	v_mfma_f32_16x16x32_f16 v[74:77], v[206:209], v[190:193], v[74:77]
	v_mfma_f32_16x16x32_f16 v[78:81], v[214:217], v[190:193], v[78:81]
	v_mfma_f32_16x16x32_f16 v[70:73], v[206:209], v[198:201], v[70:73]
	v_mfma_f32_16x16x32_f16 v[66:69], v[214:217], v[198:201], v[66:69]
	s_setprio 0
	s_add_i32 s93, s93, 2
	s_add_u32 s44, s44, 0x100
	s_addc_u32 s45, s45, 0
	s_add_u32 s91, s91, 0x100
	s_addc_u32 s92, s92, 0
	s_cmp_gt_u32 s93, 13
	s_barrier
	s_cbranch_scc1 .LBB0_264

; DI unsigned pk2(float a, float b) { typedef _Float16 h2 __attribute__((ext_vector_type(2))); h2 v; v[0] = (f16)a; v[1] = (f16)b; return __builtin_bit_cast(unsigned, v); }
;   DI void operator()(const f32x4 (&acc)[2][2][4][2], const GUnit& u, int wr, int wc, int fr, int fq) const {
;     ...
;     f16* base = (seg == 8) ? KVM : Z; const long ld = (seg == 8) ? 1024 : ZW;
; #pragma unroll
;     for (int ai = 0; ai < 2; ++ai)
; #pragma unroll
;       for (int m = 0; m < 4; ++m) {
;         f16* zp = base + (size_t)(row0 + ai * 128 + m * 16) * ld + u.pn * 256 + 32 * wc + 8 * fq;
; #pragma unroll
;         for (int bj = 0; bj < 2; ++bj) {
;           f32x4 v0 = acc[ai][bj][m][0], v1 = acc[ai][bj][m][1];
;           if (seg == 5) { v0 *= QSCALE; v1 *= QSCALE; }
;           u32x4_ w; w.x = pk2(v0[0], v0[1]); w.y = pk2(v0[2], v0[3]); w.z = pk2(v1[0], v1[1]); w.w = pk2(v1[2], v1[3]);
;           __builtin_nontemporal_store(w, (u32x4_*)(zp + bj * 128));
;         }
;       }
.LBB0_264:
	v_lshl_add_u32 v170, s42, 8, v153
	s_cmp_lg_u32 s27, 7
	s_mov_b64 s[42:43], -1
	s_cbranch_scc0 .LBB0_277
	s_cmp_gt_u32 s27, 1
	s_cbranch_scc0 .LBB0_271
	s_add_i32 s4, s27, -3
	s_cmp_gt_u32 s4, 1
	v_lshlrev_b32_e32 v162, 1, v150
	s_cbranch_scc0 .LBB0_268
	v_mov_b64_e32 v[130:131], s[70:71]
	s_cmp_eq_u32 s27, 5
	v_mad_i64_i32 v[134:135], s[42:43], v170, s81, v[130:131]
	s_cselect_b64 vcc, -1, 0
	s_lshl_b32 s42, s88, 8
	s_ashr_i32 s43, s42, 31
	s_lshl_b64 s[42:43], s[42:43], 1
	v_lshl_add_u64 v[134:135], v[134:135], 0, s[42:43]
	s_lshl_b32 s4, s75, 1
	v_lshl_add_u64 v[134:135], v[134:135], 0, s[4:5]
	v_mov_b32_e32 v163, v149
	v_lshl_add_u64 v[136:137], v[134:135], 0, v[162:163]
	s_cbranch_vccz .Lge_noscale
	v_pk_mul_f32 v[2:3], v[2:3], s[24:25] op_sel_hi:[1,0]
	v_pk_mul_f32 v[4:5], v[4:5], s[24:25] op_sel_hi:[1,0]
	v_pk_mul_f32 v[6:7], v[6:7], s[24:25] op_sel_hi:[1,0]
	v_pk_mul_f32 v[8:9], v[8:9], s[24:25] op_sel_hi:[1,0]
	v_pk_mul_f32 v[10:11], v[10:11], s[24:25] op_sel_hi:[1,0]
	v_pk_mul_f32 v[12:13], v[12:13], s[24:25] op_sel_hi:[1,0]
	v_pk_mul_f32 v[14:15], v[14:15], s[24:25] op_sel_hi:[1,0]
	v_pk_mul_f32 v[16:17], v[16:17], s[24:25] op_sel_hi:[1,0]
	v_pk_mul_f32 v[18:19], v[18:19], s[24:25] op_sel_hi:[1,0]
	v_pk_mul_f32 v[20:21], v[20:21], s[24:25] op_sel_hi:[1,0]
	v_pk_mul_f32 v[22:23], v[22:23], s[24:25] op_sel_hi:[1,0]
	v_pk_mul_f32 v[24:25], v[24:25], s[24:25] op_sel_hi:[1,0]
	v_pk_mul_f32 v[26:27], v[26:27], s[24:25] op_sel_hi:[1,0]
	v_pk_mul_f32 v[28:29], v[28:29], s[24:25] op_sel_hi:[1,0]
	v_pk_mul_f32 v[30:31], v[30:31], s[24:25] op_sel_hi:[1,0]
	v_pk_mul_f32 v[32:33], v[32:33], s[24:25] op_sel_hi:[1,0]
	v_pk_mul_f32 v[34:35], v[34:35], s[24:25] op_sel_hi:[1,0]
	v_pk_mul_f32 v[36:37], v[36:37], s[24:25] op_sel_hi:[1,0]
	v_pk_mul_f32 v[38:39], v[38:39], s[24:25] op_sel_hi:[1,0]
	v_pk_mul_f32 v[40:41], v[40:41], s[24:25] op_sel_hi:[1,0]
	v_pk_mul_f32 v[42:43], v[42:43], s[24:25] op_sel_hi:[1,0]
	v_pk_mul_f32 v[44:45], v[44:45], s[24:25] op_sel_hi:[1,0]
	v_pk_mul_f32 v[46:47], v[46:47], s[24:25] op_sel_hi:[1,0]
	v_pk_mul_f32 v[48:49], v[48:49], s[24:25] op_sel_hi:[1,0]
	v_pk_mul_f32 v[50:51], v[50:51], s[24:25] op_sel_hi:[1,0]
	v_pk_mul_f32 v[52:53], v[52:53], s[24:25] op_sel_hi:[1,0]
	v_pk_mul_f32 v[54:55], v[54:55], s[24:25] op_sel_hi:[1,0]
	v_pk_mul_f32 v[56:57], v[56:57], s[24:25] op_sel_hi:[1,0]
	v_pk_mul_f32 v[58:59], v[58:59], s[24:25] op_sel_hi:[1,0]
	v_pk_mul_f32 v[60:61], v[60:61], s[24:25] op_sel_hi:[1,0]
	v_pk_mul_f32 v[62:63], v[62:63], s[24:25] op_sel_hi:[1,0]
	v_pk_mul_f32 v[64:65], v[64:65], s[24:25] op_sel_hi:[1,0]
	v_pk_mul_f32 v[66:67], v[66:67], s[24:25] op_sel_hi:[1,0]
	v_pk_mul_f32 v[68:69], v[68:69], s[24:25] op_sel_hi:[1,0]
	v_pk_mul_f32 v[70:71], v[70:71], s[24:25] op_sel_hi:[1,0]
	v_pk_mul_f32 v[72:73], v[72:73], s[24:25] op_sel_hi:[1,0]
	v_pk_mul_f32 v[74:75], v[74:75], s[24:25] op_sel_hi:[1,0]
	v_pk_mul_f32 v[76:77], v[76:77], s[24:25] op_sel_hi:[1,0]
	v_pk_mul_f32 v[78:79], v[78:79], s[24:25] op_sel_hi:[1,0]
	v_pk_mul_f32 v[80:81], v[80:81], s[24:25] op_sel_hi:[1,0]
	v_pk_mul_f32 v[82:83], v[82:83], s[24:25] op_sel_hi:[1,0]
	v_pk_mul_f32 v[84:85], v[84:85], s[24:25] op_sel_hi:[1,0]
	v_pk_mul_f32 v[86:87], v[86:87], s[24:25] op_sel_hi:[1,0]
	v_pk_mul_f32 v[88:89], v[88:89], s[24:25] op_sel_hi:[1,0]
	v_pk_mul_f32 v[90:91], v[90:91], s[24:25] op_sel_hi:[1,0]
	v_pk_mul_f32 v[92:93], v[92:93], s[24:25] op_sel_hi:[1,0]
	v_pk_mul_f32 v[94:95], v[94:95], s[24:25] op_sel_hi:[1,0]
	v_pk_mul_f32 v[96:97], v[96:97], s[24:25] op_sel_hi:[1,0]
	v_pk_mul_f32 v[98:99], v[98:99], s[24:25] op_sel_hi:[1,0]
	v_pk_mul_f32 v[100:101], v[100:101], s[24:25] op_sel_hi:[1,0]
	v_pk_mul_f32 v[102:103], v[102:103], s[24:25] op_sel_hi:[1,0]
	v_pk_mul_f32 v[104:105], v[104:105], s[24:25] op_sel_hi:[1,0]
	v_pk_mul_f32 v[106:107], v[106:107], s[24:25] op_sel_hi:[1,0]
	v_pk_mul_f32 v[108:109], v[108:109], s[24:25] op_sel_hi:[1,0]
	v_pk_mul_f32 v[110:111], v[110:111], s[24:25] op_sel_hi:[1,0]
	v_pk_mul_f32 v[112:113], v[112:113], s[24:25] op_sel_hi:[1,0]
	v_pk_mul_f32 v[114:115], v[114:115], s[24:25] op_sel_hi:[1,0]
	v_pk_mul_f32 v[116:117], v[116:117], s[24:25] op_sel_hi:[1,0]
	v_pk_mul_f32 v[118:119], v[118:119], s[24:25] op_sel_hi:[1,0]
	v_pk_mul_f32 v[120:121], v[120:121], s[24:25] op_sel_hi:[1,0]
	v_pk_mul_f32 v[122:123], v[122:123], s[24:25] op_sel_hi:[1,0]
	v_pk_mul_f32 v[124:125], v[124:125], s[24:25] op_sel_hi:[1,0]
	v_pk_mul_f32 v[126:127], v[126:127], s[24:25] op_sel_hi:[1,0]
	v_pk_mul_f32 v[128:129], v[128:129], s[24:25] op_sel_hi:[1,0]
.Lge_noscale:
	s_mov_b64 s[42:43], 0x30000
	s_mov_b32 s4, 0xf0000
	v_cvt_pk_f16_f32 v132, v58, v59
	v_cvt_pk_f16_f32 v133, v60, v61
	v_cvt_pk_f16_f32 v134, v62, v63
	v_cvt_pk_f16_f32 v135, v64, v65
	global_store_dwordx4 v[136:137], v[132:135], off nt
	v_cvt_pk_f16_f32 v138, v122, v123
	v_cvt_pk_f16_f32 v139, v124, v125
	v_cvt_pk_f16_f32 v140, v126, v127
	v_cvt_pk_f16_f32 v141, v128, v129
	global_store_dwordx4 v[136:137], v[138:141], off offset:256 nt
	s_nop 0
	v_lshl_add_u64 v[136:137], v[136:137], 0, s[42:43]
	v_cvt_pk_f16_f32 v142, v50, v51
	v_cvt_pk_f16_f32 v143, v52, v53
	v_cvt_pk_f16_f32 v144, v54, v55
	v_cvt_pk_f16_f32 v145, v56, v57
	global_store_dwordx4 v[136:137], v[142:145], off nt
	v_cvt_pk_f16_f32 v132, v114, v115
	v_cvt_pk_f16_f32 v133, v116, v117
	v_cvt_pk_f16_f32 v134, v118, v119
	v_cvt_pk_f16_f32 v135, v120, v121
	global_store_dwordx4 v[136:137], v[132:135], off offset:256 nt
	s_nop 0
	v_lshl_add_u64 v[136:137], v[136:137], 0, s[42:43]
	v_cvt_pk_f16_f32 v138, v42, v43
	v_cvt_pk_f16_f32 v139, v44, v45
	v_cvt_pk_f16_f32 v140, v46, v47
	v_cvt_pk_f16_f32 v141, v48, v49
	global_store_dwordx4 v[136:137], v[138:141], off nt
	v_cvt_pk_f16_f32 v142, v106, v107
	v_cvt_pk_f16_f32 v143, v108, v109
	v_cvt_pk_f16_f32 v144, v110, v111
	v_cvt_pk_f16_f32 v145, v112, v113
	global_store_dwordx4 v[136:137], v[142:145], off offset:256 nt
	s_nop 0
	v_lshl_add_u64 v[136:137], v[136:137], 0, s[42:43]
	v_cvt_pk_f16_f32 v132, v26, v27
	v_cvt_pk_f16_f32 v133, v28, v29
	v_cvt_pk_f16_f32 v134, v30, v31
	v_cvt_pk_f16_f32 v135, v32, v33
	global_store_dwordx4 v[136:137], v[132:135], off nt
	v_cvt_pk_f16_f32 v138, v98, v99
	v_cvt_pk_f16_f32 v139, v100, v101
	v_cvt_pk_f16_f32 v140, v102, v103
	v_cvt_pk_f16_f32 v141, v104, v105
	global_store_dwordx4 v[136:137], v[138:141], off offset:256 nt
	s_and_b64 vcc, exec, s[6:7]
	s_cbranch_vccz .Lge_rest
	v_lshl_add_u64 v[240:241], v[136:137], 0, s[4:5]
	s_mov_b32 s100, 1
	s_branch .Lge_done
; DI unsigned pk2(float a, float b) { typedef _Float16 h2 __attribute__((ext_vector_type(2))); h2 v; v[0] = (f16)a; v[1] = (f16)b; return __builtin_bit_cast(unsigned, v); }
;   DI void operator()(const f32x4 (&acc)[2][2][4][2], const GUnit& u, int wr, int wc, int fr, int fq) const {
;     ...
;     if (seg == 3 || seg == 4) {
;       const float sc = (seg == 4) ? 0.125f : 1.f;
; #pragma unroll
;       for (int ai = 0; ai < 2; ++ai) {
;         f32x4 tt[4][4];
; #pragma unroll
;         for (int m = 0; m < 4; ++m) {
;           const float* rp = ROT + (size_t)(row0 + ai * 128 + m * 16) * 96 + 32 + 16 * fq;
;           tt[m][0] = *(const f32x4*)rp; tt[m][1] = *(const f32x4*)(rp + 4); tt[m][2] = *(const f32x4*)(rp + 8); tt[m][3] = *(const f32x4*)(rp + 12);
;         }
; #pragma unroll
;         for (int m = 0; m < 4; ++m) {
;           f16* zp = Z + (size_t)(row0 + ai * 128 + m * 16) * ZW + u.pn * 256 + 64 * wc + 8 * fq;
;           const f32x4 t0 = tt[m][0], t1 = tt[m][1], t2 = tt[m][2], t3 = tt[m][3];
;           const float cs[8] = {t0[0], t0[2], t1[0], t1[2], t2[0], t2[2], t3[0], t3[2]}, sn[8] = {t0[1], t0[3], t1[1], t1[3], t2[1], t2[3], t3[1], t3[3]};
;           float lo[8], hi[8];
; #pragma unroll
;           for (int n = 0; n < 2; ++n)
; #pragma unroll
;             for (int j = 0; j < 4; ++j) { const int e = 4 * n + j; const float x1 = acc[ai][0][m][n][j], x2 = acc[ai][1][m][n][j]; lo[e] = (x1 * cs[e] - x2 * sn[e]) * sc; hi[e] = (x1 * sn[e] + x2 * cs[e]) * sc; }
;     ...
; #pragma unroll
;     for (int ai = 0; ai < 2; ++ai)
; #pragma unroll
;       for (int m = 0; m < 4; ++m) {
;         f16* zp = base + (size_t)(row0 + ai * 128 + m * 16) * ld + u.pn * 256 + 32 * wc + 8 * fq;
; #pragma unroll
;         for (int bj = 0; bj < 2; ++bj) {
;           f32x4 v0 = acc[ai][bj][m][0], v1 = acc[ai][bj][m][1];
;           if (seg == 5) { v0 *= QSCALE; v1 *= QSCALE; }
;           u32x4_ w; w.x = pk2(v0[0], v0[1]); w.y = pk2(v0[2], v0[3]); w.z = pk2(v1[0], v1[1]); w.w = pk2(v1[2], v1[3]);
;           __builtin_nontemporal_store(w, (u32x4_*)(zp + bj * 128));
;         }
;       }
.Lge_rest:
	s_nop 0
	v_lshl_add_u64 v[136:137], v[136:137], 0, s[4:5]
	v_cvt_pk_f16_f32 v142, v34, v35
	v_cvt_pk_f16_f32 v143, v36, v37
	v_cvt_pk_f16_f32 v144, v38, v39
	v_cvt_pk_f16_f32 v145, v40, v41
	global_store_dwordx4 v[136:137], v[142:145], off nt
	v_cvt_pk_f16_f32 v132, v90, v91
	v_cvt_pk_f16_f32 v133, v92, v93
	v_cvt_pk_f16_f32 v134, v94, v95
	v_cvt_pk_f16_f32 v135, v96, v97
	global_store_dwordx4 v[136:137], v[132:135], off offset:256 nt
	s_nop 0
	v_lshl_add_u64 v[136:137], v[136:137], 0, s[42:43]
	v_cvt_pk_f16_f32 v138, v18, v19
	v_cvt_pk_f16_f32 v139, v20, v21
	v_cvt_pk_f16_f32 v140, v22, v23
	v_cvt_pk_f16_f32 v141, v24, v25
	global_store_dwordx4 v[136:137], v[138:141], off nt
	v_cvt_pk_f16_f32 v142, v82, v83
	v_cvt_pk_f16_f32 v143, v84, v85
	v_cvt_pk_f16_f32 v144, v86, v87
	v_cvt_pk_f16_f32 v145, v88, v89
	global_store_dwordx4 v[136:137], v[142:145], off offset:256 nt
	s_nop 0
	v_lshl_add_u64 v[136:137], v[136:137], 0, s[42:43]
	v_cvt_pk_f16_f32 v132, v10, v11
	v_cvt_pk_f16_f32 v133, v12, v13
	v_cvt_pk_f16_f32 v134, v14, v15
	v_cvt_pk_f16_f32 v135, v16, v17
	global_store_dwordx4 v[136:137], v[132:135], off nt
	v_cvt_pk_f16_f32 v138, v74, v75
	v_cvt_pk_f16_f32 v139, v76, v77
	v_cvt_pk_f16_f32 v140, v78, v79
	v_cvt_pk_f16_f32 v141, v80, v81
	global_store_dwordx4 v[136:137], v[138:141], off offset:256 nt
	s_nop 0
	v_lshl_add_u64 v[136:137], v[136:137], 0, s[42:43]
	v_cvt_pk_f16_f32 v142, v2, v3
	v_cvt_pk_f16_f32 v143, v4, v5
	v_cvt_pk_f16_f32 v144, v6, v7
	v_cvt_pk_f16_f32 v145, v8, v9
	global_store_dwordx4 v[136:137], v[142:145], off nt
	v_cvt_pk_f16_f32 v132, v70, v71
	v_cvt_pk_f16_f32 v133, v72, v73
	v_cvt_pk_f16_f32 v134, v66, v67
	v_cvt_pk_f16_f32 v135, v68, v69
	global_store_dwordx4 v[136:137], v[132:135], off offset:256 nt
.Lge_done:
	s_mov_b64 s[42:43], 0
.LBB0_268:
	s_andn2_b64 vcc, exec, s[42:43]
	s_cbranch_vccnz .LBB0_270
	v_mad_i64_i32 v[130:131], s[42:43], v170, s82, v[158:159]
	global_load_dwordx4 v[172:175], v[130:131], off offset:128
	global_load_dwordx4 v[176:179], v[130:131], off offset:144
	global_load_dwordx4 v[180:183], v[130:131], off offset:160
	global_load_dwordx4 v[184:187], v[130:131], off offset:176
	v_or_b32_e32 v171, 16, v170
	v_mad_i64_i32 v[130:131], s[42:43], v171, s82, v[158:159]
	global_load_dwordx4 v[188:191], v[130:131], off offset:144
	global_load_dwordx4 v[192:195], v[130:131], off offset:128
	global_load_dwordx4 v[196:199], v[130:131], off offset:176
	global_load_dwordx4 v[200:203], v[130:131], off offset:160
	v_or_b32_e32 v238, 32, v170
	v_or_b32_e32 v239, 48, v170
	v_mad_i64_i32 v[132:133], s[42:43], v238, s82, v[158:159]
	v_mad_i64_i32 v[142:143], s[42:43], v239, s82, v[158:159]
	global_load_dwordx4 v[204:207], v[132:133], off offset:176
	global_load_dwordx4 v[208:211], v[132:133], off offset:160
	global_load_dwordx4 v[212:215], v[132:133], off offset:144
	global_load_dwordx4 v[216:219], v[132:133], off offset:128
	s_nop 0
	global_load_dwordx4 v[130:133], v[142:143], off offset:176
	global_load_dwordx4 v[134:137], v[142:143], off offset:160
	global_load_dwordx4 v[138:141], v[142:143], off offset:144
	s_nop 0
	global_load_dwordx4 v[142:145], v[142:143], off offset:128
	v_mov_b64_e32 v[166:167], s[70:71]
	s_cmp_eq_u32 s27, 4
	v_mad_i64_i32 v[220:221], s[42:43], v170, s81, v[166:167]
	s_cselect_b64 vcc, -1, 0
	s_lshl_b32 s42, s88, 8
	s_ashr_i32 s43, s42, 31
	s_lshl_b64 s[42:43], s[42:43], 1
	s_mov_b32 s27, s5
	v_cndmask_b32_e32 v164, 1.0, v169, vcc
	v_lshl_add_u64 v[220:221], v[220:221], 0, s[42:43]
	v_mov_b32_e32 v163, v149
	v_lshl_add_u64 v[220:221], v[220:221], 0, s[26:27]
	v_lshl_add_u64 v[220:221], v[220:221], 0, v[162:163]
	s_waitcnt vmcnt(0)
	v_mov_b32_e32 v223, v174
	v_mov_b32_e32 v174, v173
	v_mov_b32_e32 v173, v178
	v_mov_b32_e32 v178, v177
	v_mov_b32_e32 v177, v182
	v_mov_b32_e32 v182, v181
	v_mov_b32_e32 v181, v186
	v_mov_b32_e32 v186, v185
	v_mov_b32_e32 v222, v172
	v_mov_b32_e32 v172, v176
	v_mov_b32_e32 v176, v180
	v_mov_b32_e32 v180, v184
	v_pk_mul_f32 v[184:185], v[122:123], v[174:175]
	v_pk_mul_f32 v[224:225], v[124:125], v[178:179]
	v_pk_mul_f32 v[226:227], v[126:127], v[182:183]
	v_pk_mul_f32 v[228:229], v[128:129], v[186:187]
	v_pk_mul_f32 v[230:231], v[122:123], v[222:223]
	v_pk_mul_f32 v[232:233], v[124:125], v[172:173]
	v_pk_mul_f32 v[234:235], v[126:127], v[176:177]
	v_pk_mul_f32 v[236:237], v[128:129], v[180:181]
	v_pk_fma_f32 v[184:185], v[58:59], v[222:223], v[184:185] neg_lo:[0,0,1] neg_hi:[0,0,1]
	v_pk_fma_f32 v[172:173], v[60:61], v[172:173], v[224:225] neg_lo:[0,0,1] neg_hi:[0,0,1]
	v_pk_fma_f32 v[176:177], v[62:63], v[176:177], v[226:227] neg_lo:[0,0,1] neg_hi:[0,0,1]
	v_pk_fma_f32 v[180:181], v[64:65], v[180:181], v[228:229] neg_lo:[0,0,1] neg_hi:[0,0,1]
	v_pk_fma_f32 v[174:175], v[58:59], v[174:175], v[230:231]
	v_pk_fma_f32 v[178:179], v[60:61], v[178:179], v[232:233]
	v_pk_fma_f32 v[182:183], v[62:63], v[182:183], v[234:235]
	v_pk_fma_f32 v[186:187], v[64:65], v[186:187], v[236:237]
	v_pk_mul_f32 v[184:185], v[164:165], v[184:185] op_sel_hi:[0,1]
	v_pk_mul_f32 v[222:223], v[164:165], v[172:173] op_sel_hi:[0,1]
	v_pk_mul_f32 v[176:177], v[164:165], v[176:177] op_sel_hi:[0,1]
	v_pk_mul_f32 v[180:181], v[164:165], v[180:181] op_sel_hi:[0,1]
	v_pk_mul_f32 v[224:225], v[164:165], v[174:175] op_sel_hi:[0,1]
	v_pk_mul_f32 v[178:179], v[164:165], v[178:179] op_sel_hi:[0,1]
	v_pk_mul_f32 v[182:183], v[164:165], v[182:183] op_sel_hi:[0,1]
	v_pk_mul_f32 v[186:187], v[164:165], v[186:187] op_sel_hi:[0,1]
	v_cvt_pk_f16_f32 v172, v184, v185
	v_cvt_pk_f16_f32 v173, v222, v223
	v_cvt_pk_f16_f32 v174, v176, v177
	v_cvt_pk_f16_f32 v175, v180, v181
	v_cvt_pk_f16_f32 v176, v224, v225
; DI unsigned pk2(float a, float b) { typedef _Float16 h2 __attribute__((ext_vector_type(2))); h2 v; v[0] = (f16)a; v[1] = (f16)b; return __builtin_bit_cast(unsigned, v); }
;   DI void operator()(const f32x4 (&acc)[2][2][4][2], const GUnit& u, int wr, int wc, int fr, int fq) const {
;     ...
;     if (seg == 3 || seg == 4) {
;       const float sc = (seg == 4) ? 0.125f : 1.f;
; #pragma unroll
;       for (int ai = 0; ai < 2; ++ai) {
;         f32x4 tt[4][4];
; #pragma unroll
;         for (int m = 0; m < 4; ++m) {
;           const float* rp = ROT + (size_t)(row0 + ai * 128 + m * 16) * 96 + 32 + 16 * fq;
;           tt[m][0] = *(const f32x4*)rp; tt[m][1] = *(const f32x4*)(rp + 4); tt[m][2] = *(const f32x4*)(rp + 8); tt[m][3] = *(const f32x4*)(rp + 12);
;         }
; #pragma unroll
;         for (int m = 0; m < 4; ++m) {
;           f16* zp = Z + (size_t)(row0 + ai * 128 + m * 16) * ZW + u.pn * 256 + 64 * wc + 8 * fq;
;           const f32x4 t0 = tt[m][0], t1 = tt[m][1], t2 = tt[m][2], t3 = tt[m][3];
;           const float cs[8] = {t0[0], t0[2], t1[0], t1[2], t2[0], t2[2], t3[0], t3[2]}, sn[8] = {t0[1], t0[3], t1[1], t1[3], t2[1], t2[3], t3[1], t3[3]};
;           float lo[8], hi[8];
; #pragma unroll
;           for (int n = 0; n < 2; ++n)
; #pragma unroll
;             for (int j = 0; j < 4; ++j) { const int e = 4 * n + j; const float x1 = acc[ai][0][m][n][j], x2 = acc[ai][1][m][n][j]; lo[e] = (x1 * cs[e] - x2 * sn[e]) * sc; hi[e] = (x1 * sn[e] + x2 * cs[e]) * sc; }
;           u32x4_ wl, wh; wl.x = pk2(lo[0], lo[1]); wl.y = pk2(lo[2], lo[3]); wl.z = pk2(lo[4], lo[5]); wl.w = pk2(lo[6], lo[7]);
;           wh.x = pk2(hi[0], hi[1]); wh.y = pk2(hi[2], hi[3]); wh.z = pk2(hi[4], hi[5]); wh.w = pk2(hi[6], hi[7]);
;           __builtin_nontemporal_store(wl, (u32x4_*)zp); __builtin_nontemporal_store(wh, (u32x4_*)(zp + 32));
;         }
;       }
;       return;
	v_cvt_pk_f16_f32 v177, v178, v179
	v_cvt_pk_f16_f32 v178, v182, v183
	v_cvt_pk_f16_f32 v179, v186, v187
	global_store_dwordx4 v[220:221], v[172:175], off nt
	global_store_dwordx4 v[220:221], v[176:179], off offset:64 nt
	v_mov_b32_e32 v183, v202
	v_mad_i64_i32 v[172:173], s[44:45], v171, s81, v[166:167]
	v_lshl_add_u64 v[172:173], v[172:173], 0, s[42:43]
	v_lshl_add_u64 v[172:173], v[172:173], 0, s[26:27]
	v_mov_b32_e32 v177, v194
	v_mov_b32_e32 v194, v193
	v_mov_b32_e32 v179, v190
	v_mov_b32_e32 v190, v189
	v_lshl_add_u64 v[180:181], v[172:173], 0, v[162:163]
	v_mov_b32_e32 v176, v192
	v_pk_mul_f32 v[172:173], v[114:115], v[194:195]
	v_mov_b32_e32 v178, v188
	v_pk_mul_f32 v[174:175], v[116:117], v[190:191]
	v_pk_fma_f32 v[172:173], v[50:51], v[176:177], v[172:173] neg_lo:[0,0,1] neg_hi:[0,0,1]
	v_pk_fma_f32 v[174:175], v[52:53], v[178:179], v[174:175] neg_lo:[0,0,1] neg_hi:[0,0,1]
	v_pk_mul_f32 v[176:177], v[114:115], v[176:177]
	v_pk_mul_f32 v[178:179], v[116:117], v[178:179]
	v_pk_mul_f32 v[172:173], v[164:165], v[172:173] op_sel_hi:[0,1]
	v_pk_mul_f32 v[174:175], v[164:165], v[174:175] op_sel_hi:[0,1]
	v_mov_b32_e32 v202, v201
	v_mov_b32_e32 v185, v198
	v_mov_b32_e32 v198, v197
	v_pk_fma_f32 v[176:177], v[50:51], v[194:195], v[176:177]
	v_pk_fma_f32 v[178:179], v[52:53], v[190:191], v[178:179]
	v_cvt_pk_f16_f32 v172, v172, v173
	v_cvt_pk_f16_f32 v173, v174, v175
	v_mov_b32_e32 v182, v200
	v_pk_mul_f32 v[174:175], v[118:119], v[202:203]
	v_mov_b32_e32 v184, v196
	v_pk_mul_f32 v[186:187], v[120:121], v[198:199]
	v_pk_mul_f32 v[176:177], v[164:165], v[176:177] op_sel_hi:[0,1]
	v_pk_mul_f32 v[178:179], v[164:165], v[178:179] op_sel_hi:[0,1]
	v_pk_fma_f32 v[174:175], v[54:55], v[182:183], v[174:175] neg_lo:[0,0,1] neg_hi:[0,0,1]
	v_pk_fma_f32 v[186:187], v[56:57], v[184:185], v[186:187] neg_lo:[0,0,1] neg_hi:[0,0,1]
	v_cvt_pk_f16_f32 v176, v176, v177
	v_cvt_pk_f16_f32 v177, v178, v179
	v_pk_mul_f32 v[178:179], v[118:119], v[182:183]
	v_pk_mul_f32 v[182:183], v[120:121], v[184:185]
	v_pk_mul_f32 v[174:175], v[164:165], v[174:175] op_sel_hi:[0,1]
	v_pk_mul_f32 v[186:187], v[164:165], v[186:187] op_sel_hi:[0,1]
	v_pk_fma_f32 v[178:179], v[54:55], v[202:203], v[178:179]
	v_pk_fma_f32 v[182:183], v[56:57], v[198:199], v[182:183]
	v_cvt_pk_f16_f32 v174, v174, v175
	v_cvt_pk_f16_f32 v175, v186, v187
	v_pk_mul_f32 v[178:179], v[164:165], v[178:179] op_sel_hi:[0,1]
	v_pk_mul_f32 v[182:183], v[164:165], v[182:183] op_sel_hi:[0,1]
	v_cvt_pk_f16_f32 v178, v178, v179
	v_cvt_pk_f16_f32 v179, v182, v183
	global_store_dwordx4 v[180:181], v[172:175], off nt
	global_store_dwordx4 v[180:181], v[176:179], off offset:64 nt
	v_mov_b32_e32 v183, v210
	v_mad_i64_i32 v[172:173], s[44:45], v238, s81, v[166:167]
	v_lshl_add_u64 v[172:173], v[172:173], 0, s[42:43]
	v_lshl_add_u64 v[172:173], v[172:173], 0, s[26:27]
	v_mov_b32_e32 v177, v218
	v_mov_b32_e32 v218, v217
	v_mov_b32_e32 v179, v214
	v_mov_b32_e32 v214, v213
	v_lshl_add_u64 v[180:181], v[172:173], 0, v[162:163]
	v_mov_b32_e32 v176, v216
	v_pk_mul_f32 v[172:173], v[106:107], v[218:219]
	v_mov_b32_e32 v178, v212
	v_pk_mul_f32 v[174:175], v[108:109], v[214:215]
	v_pk_fma_f32 v[172:173], v[42:43], v[176:177], v[172:173] neg_lo:[0,0,1] neg_hi:[0,0,1]
	v_pk_fma_f32 v[174:175], v[44:45], v[178:179], v[174:175] neg_lo:[0,0,1] neg_hi:[0,0,1]
	v_pk_mul_f32 v[176:177], v[106:107], v[176:177]
	v_pk_mul_f32 v[178:179], v[108:109], v[178:179]
	v_pk_mul_f32 v[172:173], v[164:165], v[172:173] op_sel_hi:[0,1]
	v_pk_mul_f32 v[174:175], v[164:165], v[174:175] op_sel_hi:[0,1]
	v_mov_b32_e32 v210, v209
	v_pk_fma_f32 v[176:177], v[42:43], v[218:219], v[176:177]
	v_pk_fma_f32 v[178:179], v[44:45], v[214:215], v[178:179]
	v_cvt_pk_f16_f32 v172, v172, v173
	v_cvt_pk_f16_f32 v173, v174, v175
	v_mov_b32_e32 v182, v208
	v_pk_mul_f32 v[174:175], v[110:111], v[210:211]
	v_mov_b32_e32 v184, v204
	v_mov_b32_e32 v185, v206
	v_mov_b32_e32 v206, v205
	v_pk_mul_f32 v[176:177], v[164:165], v[176:177] op_sel_hi:[0,1]
	v_pk_mul_f32 v[178:179], v[164:165], v[178:179] op_sel_hi:[0,1]
	v_pk_fma_f32 v[174:175], v[46:47], v[182:183], v[174:175] neg_lo:[0,0,1] neg_hi:[0,0,1]
	v_pk_mul_f32 v[186:187], v[112:113], v[206:207]
	v_cvt_pk_f16_f32 v176, v176, v177
	v_cvt_pk_f16_f32 v177, v178, v179
	v_pk_mul_f32 v[178:179], v[110:111], v[182:183]
	v_pk_mul_f32 v[182:183], v[112:113], v[184:185]
	v_pk_fma_f32 v[186:187], v[48:49], v[184:185], v[186:187] neg_lo:[0,0,1] neg_hi:[0,0,1]
	v_pk_fma_f32 v[178:179], v[46:47], v[210:211], v[178:179]
	v_pk_fma_f32 v[182:183], v[48:49], v[206:207], v[182:183]
	v_pk_mul_f32 v[174:175], v[164:165], v[174:175] op_sel_hi:[0,1]
	v_pk_mul_f32 v[186:187], v[164:165], v[186:187] op_sel_hi:[0,1]
	v_pk_mul_f32 v[178:179], v[164:165], v[178:179] op_sel_hi:[0,1]
	v_pk_mul_f32 v[182:183], v[164:165], v[182:183] op_sel_hi:[0,1]
	v_cvt_pk_f16_f32 v174, v174, v175
	v_cvt_pk_f16_f32 v175, v186, v187
	v_cvt_pk_f16_f32 v178, v178, v179
	v_cvt_pk_f16_f32 v179, v182, v183
	global_store_dwordx4 v[180:181], v[172:175], off nt
	global_store_dwordx4 v[180:181], v[176:179], off offset:64 nt
	v_mov_b32_e32 v181, v132
	v_mad_i64_i32 v[172:173], s[44:45], v239, s81, v[166:167]
	v_mov_b32_e32 v179, v144
	v_mov_b32_e32 v144, v143
	v_mov_b32_e32 v178, v142
	v_pk_mul_f32 v[142:143], v[98:99], v[144:145]
	v_lshl_add_u64 v[172:173], v[172:173], 0, s[42:43]
	v_pk_fma_f32 v[142:143], v[26:27], v[178:179], v[142:143] neg_lo:[0,0,1] neg_hi:[0,0,1]
	v_lshl_add_u64 v[172:173], v[172:173], 0, s[26:27]
	v_pk_mul_f32 v[142:143], v[164:165], v[142:143] op_sel_hi:[0,1]
	v_lshl_add_u64 v[176:177], v[172:173], 0, v[162:163]
	v_cvt_pk_f16_f32 v172, v142, v143
; DI unsigned pk2(float a, float b) { typedef _Float16 h2 __attribute__((ext_vector_type(2))); h2 v; v[0] = (f16)a; v[1] = (f16)b; return __builtin_bit_cast(unsigned, v); }
;   DI void operator()(const f32x4 (&acc)[2][2][4][2], const GUnit& u, int wr, int wc, int fr, int fq) const {
;     ...
;     if (seg == 3 || seg == 4) {
;       const float sc = (seg == 4) ? 0.125f : 1.f;
; #pragma unroll
;       for (int ai = 0; ai < 2; ++ai) {
;         f32x4 tt[4][4];
; #pragma unroll
;         for (int m = 0; m < 4; ++m) {
;           const float* rp = ROT + (size_t)(row0 + ai * 128 + m * 16) * 96 + 32 + 16 * fq;
;           tt[m][0] = *(const f32x4*)rp; tt[m][1] = *(const f32x4*)(rp + 4); tt[m][2] = *(const f32x4*)(rp + 8); tt[m][3] = *(const f32x4*)(rp + 12);
;         }
; #pragma unroll
;         for (int m = 0; m < 4; ++m) {
;           f16* zp = Z + (size_t)(row0 + ai * 128 + m * 16) * ZW + u.pn * 256 + 64 * wc + 8 * fq;
;           const f32x4 t0 = tt[m][0], t1 = tt[m][1], t2 = tt[m][2], t3 = tt[m][3];
;           const float cs[8] = {t0[0], t0[2], t1[0], t1[2], t2[0], t2[2], t3[0], t3[2]}, sn[8] = {t0[1], t0[3], t1[1], t1[3], t2[1], t2[3], t3[1], t3[3]};
;           float lo[8], hi[8];
; #pragma unroll
;           for (int n = 0; n < 2; ++n)
; #pragma unroll
;             for (int j = 0; j < 4; ++j) { const int e = 4 * n + j; const float x1 = acc[ai][0][m][n][j], x2 = acc[ai][1][m][n][j]; lo[e] = (x1 * cs[e] - x2 * sn[e]) * sc; hi[e] = (x1 * sn[e] + x2 * cs[e]) * sc; }
;           u32x4_ wl, wh; wl.x = pk2(lo[0], lo[1]); wl.y = pk2(lo[2], lo[3]); wl.z = pk2(lo[4], lo[5]); wl.w = pk2(lo[6], lo[7]);
;           wh.x = pk2(hi[0], hi[1]); wh.y = pk2(hi[2], hi[3]); wh.z = pk2(hi[4], hi[5]); wh.w = pk2(hi[6], hi[7]);
;           __builtin_nontemporal_store(wl, (u32x4_*)zp); __builtin_nontemporal_store(wh, (u32x4_*)(zp + 32));
;         }
;       }
;       return;
	v_mov_b32_e32 v143, v140
	v_mov_b32_e32 v140, v139
	v_mov_b32_e32 v142, v138
	v_pk_mul_f32 v[138:139], v[100:101], v[140:141]
	v_mov_b32_e32 v132, v131
	v_pk_fma_f32 v[138:139], v[28:29], v[142:143], v[138:139] neg_lo:[0,0,1] neg_hi:[0,0,1]
	v_mov_b32_e32 v180, v130
	v_pk_mul_f32 v[130:131], v[104:105], v[132:133]
	v_pk_mul_f32 v[138:139], v[164:165], v[138:139] op_sel_hi:[0,1]
	v_pk_fma_f32 v[130:131], v[32:33], v[180:181], v[130:131] neg_lo:[0,0,1] neg_hi:[0,0,1]
	v_cvt_pk_f16_f32 v173, v138, v139
	v_mov_b32_e32 v139, v136
	v_mov_b32_e32 v136, v135
	v_pk_mul_f32 v[130:131], v[164:165], v[130:131] op_sel_hi:[0,1]
	v_mov_b32_e32 v138, v134
	v_pk_mul_f32 v[134:135], v[102:103], v[136:137]
	v_cvt_pk_f16_f32 v175, v130, v131
	v_pk_mul_f32 v[130:131], v[98:99], v[178:179]
	v_pk_fma_f32 v[134:135], v[30:31], v[138:139], v[134:135] neg_lo:[0,0,1] neg_hi:[0,0,1]
	v_pk_fma_f32 v[130:131], v[26:27], v[144:145], v[130:131]
	v_pk_mul_f32 v[134:135], v[164:165], v[134:135] op_sel_hi:[0,1]
	v_pk_mul_f32 v[130:131], v[164:165], v[130:131] op_sel_hi:[0,1]
	v_cvt_pk_f16_f32 v174, v134, v135
	v_cvt_pk_f16_f32 v134, v130, v131
	v_pk_mul_f32 v[130:131], v[100:101], v[142:143]
	v_add_u32_e32 v171, 0x80, v170
	v_pk_fma_f32 v[130:131], v[28:29], v[140:141], v[130:131]
	v_add_u32_e32 v230, 0x90, v170
	v_pk_mul_f32 v[130:131], v[164:165], v[130:131] op_sel_hi:[0,1]
	v_cvt_pk_f16_f32 v135, v130, v131
	v_pk_mul_f32 v[130:131], v[102:103], v[138:139]
	v_add_u32_e32 v231, 0xa0, v170
	v_pk_fma_f32 v[130:131], v[30:31], v[136:137], v[130:131]
	v_add_u32_e32 v232, 0xb0, v170
	v_pk_mul_f32 v[130:131], v[164:165], v[130:131] op_sel_hi:[0,1]
	v_cvt_pk_f16_f32 v136, v130, v131
	v_pk_mul_f32 v[130:131], v[104:105], v[180:181]
	v_mad_i64_i32 v[142:143], s[44:45], v232, s82, v[158:159]
	v_pk_fma_f32 v[130:131], v[32:33], v[132:133], v[130:131]
	v_mad_i64_i32 v[220:221], s[44:45], v171, s81, v[166:167]
	v_pk_mul_f32 v[130:131], v[164:165], v[130:131] op_sel_hi:[0,1]
	v_cvt_pk_f16_f32 v137, v130, v131
	global_store_dwordx4 v[176:177], v[172:175], off nt
	global_store_dwordx4 v[176:177], v[134:137], off offset:64 nt
	v_mad_i64_i32 v[130:131], s[44:45], v171, s82, v[158:159]
	global_load_dwordx4 v[172:175], v[130:131], off offset:128
	global_load_dwordx4 v[176:179], v[130:131], off offset:144
	global_load_dwordx4 v[180:183], v[130:131], off offset:160
	global_load_dwordx4 v[184:187], v[130:131], off offset:176
	v_mad_i64_i32 v[130:131], s[44:45], v230, s82, v[158:159]
	global_load_dwordx4 v[188:191], v[130:131], off offset:128
	global_load_dwordx4 v[192:195], v[130:131], off offset:144
	global_load_dwordx4 v[196:199], v[130:131], off offset:176
	global_load_dwordx4 v[200:203], v[130:131], off offset:160
	v_mad_i64_i32 v[130:131], s[44:45], v231, s82, v[158:159]
	global_load_dwordx4 v[204:207], v[130:131], off offset:176
	global_load_dwordx4 v[208:211], v[130:131], off offset:160
	global_load_dwordx4 v[212:215], v[130:131], off offset:144
	global_load_dwordx4 v[216:219], v[130:131], off offset:128
	s_nop 0
	global_load_dwordx4 v[130:133], v[142:143], off offset:176
	global_load_dwordx4 v[134:137], v[142:143], off offset:160
	global_load_dwordx4 v[138:141], v[142:143], off offset:144
	s_nop 0
	global_load_dwordx4 v[142:145], v[142:143], off offset:128
	v_lshl_add_u64 v[220:221], v[220:221], 0, s[42:43]
	v_lshl_add_u64 v[220:221], v[220:221], 0, s[26:27]
	v_lshl_add_u64 v[224:225], v[220:221], 0, v[162:163]
	s_waitcnt vmcnt(0)
	v_mov_b32_e32 v227, v174
	v_mov_b32_e32 v174, v173
	v_mov_b32_e32 v226, v172
	v_pk_mul_f32 v[172:173], v[90:91], v[174:175]
	v_mov_b32_e32 v229, v178
	v_pk_fma_f32 v[172:173], v[34:35], v[226:227], v[172:173] neg_lo:[0,0,1] neg_hi:[0,0,1]
	v_mov_b32_e32 v178, v177
	v_pk_mul_f32 v[172:173], v[164:165], v[172:173] op_sel_hi:[0,1]
	v_cvt_pk_f16_f32 v220, v172, v173
	v_mov_b32_e32 v228, v176
	v_pk_mul_f32 v[172:173], v[92:93], v[178:179]
	v_mov_b32_e32 v177, v182
	v_pk_fma_f32 v[172:173], v[36:37], v[228:229], v[172:173] neg_lo:[0,0,1] neg_hi:[0,0,1]
	v_mov_b32_e32 v182, v181
	v_pk_mul_f32 v[172:173], v[164:165], v[172:173] op_sel_hi:[0,1]
	v_cvt_pk_f16_f32 v221, v172, v173
	v_mov_b32_e32 v176, v180
	v_pk_mul_f32 v[172:173], v[94:95], v[182:183]
	v_mov_b32_e32 v181, v186
	v_pk_fma_f32 v[172:173], v[38:39], v[176:177], v[172:173] neg_lo:[0,0,1] neg_hi:[0,0,1]
	v_mov_b32_e32 v186, v185
	v_pk_mul_f32 v[172:173], v[164:165], v[172:173] op_sel_hi:[0,1]
	v_cvt_pk_f16_f32 v222, v172, v173
	v_mov_b32_e32 v180, v184
	v_pk_mul_f32 v[172:173], v[96:97], v[186:187]
	v_mov_b32_e32 v185, v198
	v_pk_fma_f32 v[172:173], v[40:41], v[180:181], v[172:173] neg_lo:[0,0,1] neg_hi:[0,0,1]
	v_mov_b32_e32 v198, v197
	v_pk_mul_f32 v[172:173], v[164:165], v[172:173] op_sel_hi:[0,1]
	v_cvt_pk_f16_f32 v223, v172, v173
	v_pk_mul_f32 v[172:173], v[90:91], v[226:227]
	v_mov_b32_e32 v184, v196
	v_pk_fma_f32 v[172:173], v[34:35], v[174:175], v[172:173]
	v_pk_mul_f32 v[174:175], v[92:93], v[228:229]
	v_pk_mul_f32 v[172:173], v[164:165], v[172:173] op_sel_hi:[0,1]
	v_pk_fma_f32 v[174:175], v[36:37], v[178:179], v[174:175]
	v_cvt_pk_f16_f32 v172, v172, v173
	v_pk_mul_f32 v[174:175], v[164:165], v[174:175] op_sel_hi:[0,1]
	v_cvt_pk_f16_f32 v173, v174, v175
	v_pk_mul_f32 v[174:175], v[94:95], v[176:177]
	v_pk_mul_f32 v[176:177], v[96:97], v[180:181]
	v_pk_fma_f32 v[174:175], v[38:39], v[182:183], v[174:175]
	v_pk_fma_f32 v[176:177], v[40:41], v[186:187], v[176:177]
	v_pk_mul_f32 v[174:175], v[164:165], v[174:175] op_sel_hi:[0,1]
	v_pk_mul_f32 v[176:177], v[164:165], v[176:177] op_sel_hi:[0,1]
	v_cvt_pk_f16_f32 v174, v174, v175
	v_cvt_pk_f16_f32 v175, v176, v177
	global_store_dwordx4 v[224:225], v[220:223], off nt
; DI unsigned pk2(float a, float b) { typedef _Float16 h2 __attribute__((ext_vector_type(2))); h2 v; v[0] = (f16)a; v[1] = (f16)b; return __builtin_bit_cast(unsigned, v); }
;   DI void operator()(const f32x4 (&acc)[2][2][4][2], const GUnit& u, int wr, int wc, int fr, int fq) const {
;     ...
;     if (seg == 3 || seg == 4) {
;       const float sc = (seg == 4) ? 0.125f : 1.f;
; #pragma unroll
;       for (int ai = 0; ai < 2; ++ai) {
;         f32x4 tt[4][4];
; #pragma unroll
;         for (int m = 0; m < 4; ++m) {
;           const float* rp = ROT + (size_t)(row0 + ai * 128 + m * 16) * 96 + 32 + 16 * fq;
;           tt[m][0] = *(const f32x4*)rp; tt[m][1] = *(const f32x4*)(rp + 4); tt[m][2] = *(const f32x4*)(rp + 8); tt[m][3] = *(const f32x4*)(rp + 12);
;         }
; #pragma unroll
;         for (int m = 0; m < 4; ++m) {
;           f16* zp = Z + (size_t)(row0 + ai * 128 + m * 16) * ZW + u.pn * 256 + 64 * wc + 8 * fq;
;           const f32x4 t0 = tt[m][0], t1 = tt[m][1], t2 = tt[m][2], t3 = tt[m][3];
;           const float cs[8] = {t0[0], t0[2], t1[0], t1[2], t2[0], t2[2], t3[0], t3[2]}, sn[8] = {t0[1], t0[3], t1[1], t1[3], t2[1], t2[3], t3[1], t3[3]};
;           float lo[8], hi[8];
; #pragma unroll
;           for (int n = 0; n < 2; ++n)
; #pragma unroll
;             for (int j = 0; j < 4; ++j) { const int e = 4 * n + j; const float x1 = acc[ai][0][m][n][j], x2 = acc[ai][1][m][n][j]; lo[e] = (x1 * cs[e] - x2 * sn[e]) * sc; hi[e] = (x1 * sn[e] + x2 * cs[e]) * sc; }
;           u32x4_ wl, wh; wl.x = pk2(lo[0], lo[1]); wl.y = pk2(lo[2], lo[3]); wl.z = pk2(lo[4], lo[5]); wl.w = pk2(lo[6], lo[7]);
;           wh.x = pk2(hi[0], hi[1]); wh.y = pk2(hi[2], hi[3]); wh.z = pk2(hi[4], hi[5]); wh.w = pk2(hi[6], hi[7]);
;           __builtin_nontemporal_store(wl, (u32x4_*)zp); __builtin_nontemporal_store(wh, (u32x4_*)(zp + 32));
;         }
;       }
;       return;
	global_store_dwordx4 v[224:225], v[172:175], off offset:64 nt
	v_mov_b32_e32 v177, v190
	v_mov_b32_e32 v190, v189
	v_mad_i64_i32 v[172:173], s[44:45], v230, s81, v[166:167]
	v_lshl_add_u64 v[172:173], v[172:173], 0, s[42:43]
	v_lshl_add_u64 v[172:173], v[172:173], 0, s[26:27]
	v_mov_b32_e32 v179, v194
	v_mov_b32_e32 v194, v193
	v_lshl_add_u64 v[180:181], v[172:173], 0, v[162:163]
	v_mov_b32_e32 v176, v188
	v_pk_mul_f32 v[172:173], v[82:83], v[190:191]
	v_mov_b32_e32 v178, v192
	v_pk_mul_f32 v[174:175], v[84:85], v[194:195]
	v_pk_fma_f32 v[172:173], v[18:19], v[176:177], v[172:173] neg_lo:[0,0,1] neg_hi:[0,0,1]
	v_pk_fma_f32 v[174:175], v[20:21], v[178:179], v[174:175] neg_lo:[0,0,1] neg_hi:[0,0,1]
	v_pk_mul_f32 v[176:177], v[82:83], v[176:177]
	v_pk_mul_f32 v[178:179], v[84:85], v[178:179]
	v_pk_mul_f32 v[172:173], v[164:165], v[172:173] op_sel_hi:[0,1]
	v_pk_mul_f32 v[174:175], v[164:165], v[174:175] op_sel_hi:[0,1]
	v_mov_b32_e32 v183, v202
	v_mov_b32_e32 v202, v201
	v_pk_fma_f32 v[176:177], v[18:19], v[190:191], v[176:177]
	v_pk_fma_f32 v[178:179], v[20:21], v[194:195], v[178:179]
	v_cvt_pk_f16_f32 v172, v172, v173
	v_cvt_pk_f16_f32 v173, v174, v175
	v_mov_b32_e32 v182, v200
	v_pk_mul_f32 v[174:175], v[86:87], v[202:203]
	v_pk_mul_f32 v[186:187], v[88:89], v[198:199]
	v_pk_mul_f32 v[176:177], v[164:165], v[176:177] op_sel_hi:[0,1]
	v_pk_mul_f32 v[178:179], v[164:165], v[178:179] op_sel_hi:[0,1]
	v_pk_fma_f32 v[174:175], v[22:23], v[182:183], v[174:175] neg_lo:[0,0,1] neg_hi:[0,0,1]
	v_pk_fma_f32 v[186:187], v[24:25], v[184:185], v[186:187] neg_lo:[0,0,1] neg_hi:[0,0,1]
	v_cvt_pk_f16_f32 v176, v176, v177
	v_cvt_pk_f16_f32 v177, v178, v179
	v_pk_mul_f32 v[178:179], v[86:87], v[182:183]
	v_pk_mul_f32 v[182:183], v[88:89], v[184:185]
	v_pk_mul_f32 v[174:175], v[164:165], v[174:175] op_sel_hi:[0,1]
	v_pk_mul_f32 v[186:187], v[164:165], v[186:187] op_sel_hi:[0,1]
	v_pk_fma_f32 v[178:179], v[22:23], v[202:203], v[178:179]
	v_pk_fma_f32 v[182:183], v[24:25], v[198:199], v[182:183]
	v_cvt_pk_f16_f32 v174, v174, v175
	v_cvt_pk_f16_f32 v175, v186, v187
	v_pk_mul_f32 v[178:179], v[164:165], v[178:179] op_sel_hi:[0,1]
	v_pk_mul_f32 v[182:183], v[164:165], v[182:183] op_sel_hi:[0,1]
	v_cvt_pk_f16_f32 v178, v178, v179
	v_cvt_pk_f16_f32 v179, v182, v183
	global_store_dwordx4 v[180:181], v[172:175], off nt
	global_store_dwordx4 v[180:181], v[176:179], off offset:64 nt
	v_mov_b32_e32 v183, v210
	v_mad_i64_i32 v[172:173], s[44:45], v231, s81, v[166:167]
	v_lshl_add_u64 v[172:173], v[172:173], 0, s[42:43]
	v_lshl_add_u64 v[172:173], v[172:173], 0, s[26:27]
	v_mov_b32_e32 v177, v218
	v_mov_b32_e32 v218, v217
	v_mov_b32_e32 v179, v214
	v_mov_b32_e32 v214, v213
	v_lshl_add_u64 v[180:181], v[172:173], 0, v[162:163]
	v_mov_b32_e32 v176, v216
	v_pk_mul_f32 v[172:173], v[74:75], v[218:219]
	v_mov_b32_e32 v178, v212
	v_pk_mul_f32 v[174:175], v[76:77], v[214:215]
	v_mad_i64_i32 v[166:167], s[44:45], v232, s81, v[166:167]
	v_pk_fma_f32 v[172:173], v[10:11], v[176:177], v[172:173] neg_lo:[0,0,1] neg_hi:[0,0,1]
	v_pk_fma_f32 v[174:175], v[12:13], v[178:179], v[174:175] neg_lo:[0,0,1] neg_hi:[0,0,1]
	v_pk_mul_f32 v[176:177], v[74:75], v[176:177]
	v_pk_mul_f32 v[178:179], v[76:77], v[178:179]
	v_lshl_add_u64 v[166:167], v[166:167], 0, s[42:43]
	v_pk_mul_f32 v[172:173], v[164:165], v[172:173] op_sel_hi:[0,1]
	v_pk_mul_f32 v[174:175], v[164:165], v[174:175] op_sel_hi:[0,1]
	v_mov_b32_e32 v210, v209
	v_mov_b32_e32 v185, v206
	v_mov_b32_e32 v206, v205
	v_pk_fma_f32 v[176:177], v[10:11], v[218:219], v[176:177]
	v_pk_fma_f32 v[178:179], v[12:13], v[214:215], v[178:179]
	v_lshl_add_u64 v[166:167], v[166:167], 0, s[26:27]
; DI unsigned pk2(float a, float b) { typedef _Float16 h2 __attribute__((ext_vector_type(2))); h2 v; v[0] = (f16)a; v[1] = (f16)b; return __builtin_bit_cast(unsigned, v); }
;   DI void operator()(const f32x4 (&acc)[2][2][4][2], const GUnit& u, int wr, int wc, int fr, int fq) const {
;     ...
;     if (seg == 3 || seg == 4) {
;       const float sc = (seg == 4) ? 0.125f : 1.f;
; #pragma unroll
;       for (int ai = 0; ai < 2; ++ai) {
;         f32x4 tt[4][4];
; #pragma unroll
;         for (int m = 0; m < 4; ++m) {
;           const float* rp = ROT + (size_t)(row0 + ai * 128 + m * 16) * 96 + 32 + 16 * fq;
;           tt[m][0] = *(const f32x4*)rp; tt[m][1] = *(const f32x4*)(rp + 4); tt[m][2] = *(const f32x4*)(rp + 8); tt[m][3] = *(const f32x4*)(rp + 12);
;         }
; #pragma unroll
;         for (int m = 0; m < 4; ++m) {
;           f16* zp = Z + (size_t)(row0 + ai * 128 + m * 16) * ZW + u.pn * 256 + 64 * wc + 8 * fq;
;           const f32x4 t0 = tt[m][0], t1 = tt[m][1], t2 = tt[m][2], t3 = tt[m][3];
;           const float cs[8] = {t0[0], t0[2], t1[0], t1[2], t2[0], t2[2], t3[0], t3[2]}, sn[8] = {t0[1], t0[3], t1[1], t1[3], t2[1], t2[3], t3[1], t3[3]};
;           float lo[8], hi[8];
; #pragma unroll
;           for (int n = 0; n < 2; ++n)
; #pragma unroll
;             for (int j = 0; j < 4; ++j) { const int e = 4 * n + j; const float x1 = acc[ai][0][m][n][j], x2 = acc[ai][1][m][n][j]; lo[e] = (x1 * cs[e] - x2 * sn[e]) * sc; hi[e] = (x1 * sn[e] + x2 * cs[e]) * sc; }
;           u32x4_ wl, wh; wl.x = pk2(lo[0], lo[1]); wl.y = pk2(lo[2], lo[3]); wl.z = pk2(lo[4], lo[5]); wl.w = pk2(lo[6], lo[7]);
;           wh.x = pk2(hi[0], hi[1]); wh.y = pk2(hi[2], hi[3]); wh.z = pk2(hi[4], hi[5]); wh.w = pk2(hi[6], hi[7]);
;           __builtin_nontemporal_store(wl, (u32x4_*)zp); __builtin_nontemporal_store(wh, (u32x4_*)(zp + 32));
;         }
;       }
;       return;
	v_cvt_pk_f16_f32 v172, v172, v173
	v_cvt_pk_f16_f32 v173, v174, v175
	v_mov_b32_e32 v182, v208
	v_pk_mul_f32 v[174:175], v[78:79], v[210:211]
	v_mov_b32_e32 v184, v204
	v_pk_mul_f32 v[186:187], v[80:81], v[206:207]
	v_pk_mul_f32 v[176:177], v[164:165], v[176:177] op_sel_hi:[0,1]
	v_pk_mul_f32 v[178:179], v[164:165], v[178:179] op_sel_hi:[0,1]
	v_lshl_add_u64 v[162:163], v[166:167], 0, v[162:163]
	v_mov_b32_e32 v167, v144
	v_mov_b32_e32 v144, v143
	v_pk_fma_f32 v[174:175], v[14:15], v[182:183], v[174:175] neg_lo:[0,0,1] neg_hi:[0,0,1]
	v_pk_fma_f32 v[186:187], v[16:17], v[184:185], v[186:187] neg_lo:[0,0,1] neg_hi:[0,0,1]
	v_cvt_pk_f16_f32 v176, v176, v177
	v_cvt_pk_f16_f32 v177, v178, v179
	v_pk_mul_f32 v[178:179], v[78:79], v[182:183]
	v_pk_mul_f32 v[182:183], v[80:81], v[184:185]
	v_mov_b32_e32 v166, v142
	v_pk_mul_f32 v[142:143], v[70:71], v[144:145]
	v_pk_mul_f32 v[174:175], v[164:165], v[174:175] op_sel_hi:[0,1]
	v_pk_mul_f32 v[186:187], v[164:165], v[186:187] op_sel_hi:[0,1]
	v_pk_fma_f32 v[178:179], v[14:15], v[210:211], v[178:179]
	v_pk_fma_f32 v[182:183], v[16:17], v[206:207], v[182:183]
	v_pk_fma_f32 v[142:143], v[2:3], v[166:167], v[142:143] neg_lo:[0,0,1] neg_hi:[0,0,1]
	v_cvt_pk_f16_f32 v174, v174, v175
	v_cvt_pk_f16_f32 v175, v186, v187
	v_pk_mul_f32 v[178:179], v[164:165], v[178:179] op_sel_hi:[0,1]
	v_pk_mul_f32 v[182:183], v[164:165], v[182:183] op_sel_hi:[0,1]
	v_pk_mul_f32 v[142:143], v[164:165], v[142:143] op_sel_hi:[0,1]
	v_cvt_pk_f16_f32 v178, v178, v179
	v_cvt_pk_f16_f32 v179, v182, v183
	global_store_dwordx4 v[180:181], v[172:175], off nt
	global_store_dwordx4 v[180:181], v[176:179], off offset:64 nt
	s_nop 0
	v_cvt_pk_f16_f32 v172, v142, v143
	v_mov_b32_e32 v143, v140
	v_mov_b32_e32 v140, v139
	v_mov_b32_e32 v142, v138
	v_pk_mul_f32 v[138:139], v[72:73], v[140:141]
	v_mov_b32_e32 v177, v132
	v_mov_b32_e32 v132, v131
	v_pk_fma_f32 v[138:139], v[4:5], v[142:143], v[138:139] neg_lo:[0,0,1] neg_hi:[0,0,1]
	v_mov_b32_e32 v176, v130
	v_pk_mul_f32 v[130:131], v[68:69], v[132:133]
	v_pk_mul_f32 v[138:139], v[164:165], v[138:139] op_sel_hi:[0,1]
	v_pk_fma_f32 v[130:131], v[8:9], v[176:177], v[130:131] neg_lo:[0,0,1] neg_hi:[0,0,1]
	v_cvt_pk_f16_f32 v173, v138, v139
	v_mov_b32_e32 v139, v136
	v_mov_b32_e32 v136, v135
	v_pk_mul_f32 v[130:131], v[164:165], v[130:131] op_sel_hi:[0,1]
	v_mov_b32_e32 v138, v134
	v_pk_mul_f32 v[134:135], v[66:67], v[136:137]
	v_cvt_pk_f16_f32 v175, v130, v131
	v_pk_mul_f32 v[130:131], v[70:71], v[166:167]
	v_pk_fma_f32 v[134:135], v[6:7], v[138:139], v[134:135] neg_lo:[0,0,1] neg_hi:[0,0,1]
	v_pk_fma_f32 v[130:131], v[2:3], v[144:145], v[130:131]
	v_pk_mul_f32 v[134:135], v[164:165], v[134:135] op_sel_hi:[0,1]
	v_pk_mul_f32 v[130:131], v[164:165], v[130:131] op_sel_hi:[0,1]
	v_cvt_pk_f16_f32 v174, v134, v135
	v_cvt_pk_f16_f32 v134, v130, v131
	v_pk_mul_f32 v[130:131], v[72:73], v[142:143]
	s_nop 0
	v_pk_fma_f32 v[130:131], v[4:5], v[140:141], v[130:131]
	s_nop 0
	v_pk_mul_f32 v[130:131], v[164:165], v[130:131] op_sel_hi:[0,1]
	v_cvt_pk_f16_f32 v135, v130, v131
	v_pk_mul_f32 v[130:131], v[66:67], v[138:139]
	s_nop 0
	v_pk_fma_f32 v[130:131], v[6:7], v[136:137], v[130:131]
	s_nop 0
	v_pk_mul_f32 v[130:131], v[164:165], v[130:131] op_sel_hi:[0,1]
	v_cvt_pk_f16_f32 v136, v130, v131
	v_pk_mul_f32 v[130:131], v[68:69], v[176:177]
	s_nop 0
	v_pk_fma_f32 v[130:131], v[8:9], v[132:133], v[130:131]
	s_nop 0
	v_pk_mul_f32 v[130:131], v[164:165], v[130:131] op_sel_hi:[0,1]
	v_cvt_pk_f16_f32 v137, v130, v131
	global_store_dwordx4 v[162:163], v[172:175], off nt
	global_store_dwordx4 v[162:163], v[134:137], off offset:64 nt

; DI unsigned pk2(float a, float b) { typedef _Float16 h2 __attribute__((ext_vector_type(2))); h2 v; v[0] = (f16)a; v[1] = (f16)b; return __builtin_bit_cast(unsigned, v); }
;   DI void operator()(const f32x4 (&acc)[2][2][4][2], const GUnit& u, int wr, int wc, int fr, int fq) const {
;     ...
;     if (seg == 0 || seg == 1) {
;       const float sc = (seg == 0) ? QSCALE : 1.f;
;       if (wc == 0) {
; #pragma unroll
;         for (int ai = 0; ai < 2; ++ai) {
;           f32x4 ca[4], cb[4];
; #pragma unroll
;           for (int m = 0; m < 4; ++m) { const float* rp = ROT + (size_t)(row0 + ai * 128 + m * 16) * 96 + 8 * fq; ca[m] = *(const f32x4*)rp; cb[m] = *(const f32x4*)(rp + 4); }
; #pragma unroll
;           for (int m = 0; m < 4; ++m) {
;             f16* zp = Z + (size_t)(row0 + ai * 128 + m * 16) * ZW + u.pn * 256 + 4 * fq;
;             const float cs[4] = {ca[m][0], ca[m][2], cb[m][0], cb[m][2]}, sn[4] = {ca[m][1], ca[m][3], cb[m][1], cb[m][3]};
; #pragma unroll
;             for (int bj = 0; bj < 2; ++bj) {
;               const f32x4 x1 = acc[ai][bj][m][0], x2 = acc[ai][bj][m][1];
;               f32x4 o1, o2;
; #pragma unroll
;               for (int j = 0; j < 4; ++j) { o1[j] = (x1[j] * cs[j] - x2[j] * sn[j]) * sc; o2[j] = (x1[j] * sn[j] + x2[j] * cs[j]) * sc; }
;               u32x2_ w1, w2; w1.x = pk2(o1[0], o1[1]); w1.y = pk2(o1[2], o1[3]); w2.x = pk2(o2[0], o2[1]); w2.y = pk2(o2[2], o2[3]);
;               __builtin_nontemporal_store(w1, (u32x2_*)(zp + bj * 128)); __builtin_nontemporal_store(w2, (u32x2_*)(zp + bj * 128 + 16));
;             }
;           }
;         }
.LBB0_274:
	s_andn2_b64 vcc, exec, s[42:43]
	s_cbranch_vccnz .LBB0_276
	v_mad_i64_i32 v[132:133], s[42:43], v170, s82, v[156:157]
	v_or_b32_e32 v164, 16, v170
	global_load_dwordx4 v[134:137], v[132:133], off
	global_load_dwordx4 v[138:141], v[132:133], off offset:16
	v_mad_i64_i32 v[132:133], s[42:43], v164, s82, v[156:157]
	global_load_dwordx4 v[142:145], v[132:133], off
	global_load_dwordx4 v[172:175], v[132:133], off offset:16
	v_or_b32_e32 v171, 32, v170
	v_or_b32_e32 v206, 48, v170
	v_mad_i64_i32 v[162:163], s[44:45], v171, s82, v[156:157]
	v_mad_i64_i32 v[166:167], s[44:45], v206, s82, v[156:157]
	global_load_dwordx4 v[176:179], v[162:163], off offset:16
	global_load_dwordx4 v[180:183], v[162:163], off
	global_load_dwordx4 v[184:187], v[166:167], off offset:16
	global_load_dwordx4 v[188:191], v[166:167], off
	v_add_u32_e32 v248, 0x80, v170
	v_mad_i64_i32 v[240:241], s[44:45], v248, s82, v[156:157]
	global_load_dwordx4 v[208:211], v[240:241], off
	global_load_dwordx4 v[212:215], v[240:241], off offset:16
	v_add_u32_e32 v248, 0x90, v170
	v_mad_i64_i32 v[242:243], s[44:45], v248, s82, v[156:157]
	global_load_dwordx4 v[216:219], v[242:243], off
	global_load_dwordx4 v[220:223], v[242:243], off offset:16
	v_add_u32_e32 v248, 0xa0, v170
	v_mad_i64_i32 v[244:245], s[44:45], v248, s82, v[156:157]
	global_load_dwordx4 v[224:227], v[244:245], off offset:16
	global_load_dwordx4 v[228:231], v[244:245], off
	v_add_u32_e32 v248, 0xb0, v170
	v_mad_i64_i32 v[246:247], s[44:45], v248, s82, v[156:157]
	global_load_dwordx4 v[232:235], v[246:247], off offset:16
	global_load_dwordx4 v[236:239], v[246:247], off
	s_lshl_b32 s42, s88, 8
	v_mov_b64_e32 v[132:133], s[70:71]
	s_ashr_i32 s43, s42, 31
	v_mad_i64_i32 v[192:193], s[44:45], v170, s81, v[132:133]
	s_lshl_b64 s[42:43], s[42:43], 1
	v_mad_i64_i32 v[194:195], s[44:45], v164, s81, v[132:133]
	v_lshl_add_u64 v[162:163], v[192:193], 0, s[42:43]
	v_lshl_add_u64 v[166:167], v[194:195], 0, s[42:43]
	v_mov_b32_e32 v131, v149
	v_lshl_add_u64 v[162:163], v[162:163], 0, v[130:131]
	v_lshl_add_u64 v[166:167], v[166:167], 0, v[130:131]
	s_waitcnt vmcnt(0)
	v_mov_b32_e32 v192, v134
	v_mov_b32_e32 v193, v136
	v_mov_b32_e32 v136, v135
	v_mov_b32_e32 v134, v138
	v_mov_b32_e32 v135, v140
	v_mov_b32_e32 v140, v139
	v_pk_mul_f32 v[138:139], v[62:63], v[136:137]
	v_pk_mul_f32 v[194:195], v[64:65], v[140:141]
	v_pk_mul_f32 v[196:197], v[62:63], v[192:193]
	v_pk_mul_f32 v[198:199], v[64:65], v[134:135]
	v_pk_mul_f32 v[200:201], v[126:127], v[136:137]
	v_pk_mul_f32 v[202:203], v[128:129], v[140:141]
	v_pk_mul_f32 v[126:127], v[126:127], v[192:193]
	v_pk_mul_f32 v[128:129], v[128:129], v[134:135]
	v_mov_b32_e32 v204, v142
	v_mov_b32_e32 v205, v144
	v_mov_b32_e32 v144, v143
	v_mov_b32_e32 v142, v172
	v_mov_b32_e32 v143, v174
	v_mov_b32_e32 v174, v173
	v_pk_fma_f32 v[138:139], v[58:59], v[192:193], v[138:139] neg_lo:[0,0,1] neg_hi:[0,0,1]
	v_pk_fma_f32 v[172:173], v[60:61], v[134:135], v[194:195] neg_lo:[0,0,1] neg_hi:[0,0,1]
	v_pk_fma_f32 v[194:195], v[58:59], v[136:137], v[196:197]
	v_pk_fma_f32 v[196:197], v[60:61], v[140:141], v[198:199]
	v_pk_fma_f32 v[192:193], v[122:123], v[192:193], v[200:201] neg_lo:[0,0,1] neg_hi:[0,0,1]
	v_pk_fma_f32 v[134:135], v[124:125], v[134:135], v[202:203] neg_lo:[0,0,1] neg_hi:[0,0,1]
	v_pk_fma_f32 v[122:123], v[122:123], v[136:137], v[126:127]
	v_pk_fma_f32 v[124:125], v[124:125], v[140:141], v[128:129]
	v_pk_mul_f32 v[126:127], v[54:55], v[144:145]
	v_pk_mul_f32 v[128:129], v[56:57], v[174:175]
	v_pk_mul_f32 v[136:137], v[54:55], v[204:205]
	v_pk_mul_f32 v[140:141], v[56:57], v[142:143]
	v_cvt_pk_f16_f32 v138, v138, v139
	v_cvt_pk_f16_f32 v139, v172, v173
	v_cvt_pk_f16_f32 v192, v192, v193
	v_cvt_pk_f16_f32 v193, v134, v135
	v_cvt_pk_f16_f32 v122, v122, v123
	v_cvt_pk_f16_f32 v123, v124, v125
	v_pk_fma_f32 v[124:125], v[50:51], v[204:205], v[126:127] neg_lo:[0,0,1] neg_hi:[0,0,1]
	v_pk_fma_f32 v[126:127], v[52:53], v[142:143], v[128:129] neg_lo:[0,0,1] neg_hi:[0,0,1]
	v_pk_fma_f32 v[128:129], v[50:51], v[144:145], v[136:137]
	v_pk_fma_f32 v[134:135], v[52:53], v[174:175], v[140:141]
	v_pk_mul_f32 v[198:199], v[118:119], v[144:145]
	v_cvt_pk_f16_f32 v172, v194, v195
	v_cvt_pk_f16_f32 v173, v196, v197
	global_store_dwordx2 v[162:163], v[138:139], off nt
	global_store_dwordx2 v[162:163], v[172:173], off offset:32 nt
	global_store_dwordx2 v[162:163], v[192:193], off offset:256 nt
	global_store_dwordx2 v[162:163], v[122:123], off offset:288 nt
	v_cvt_pk_f16_f32 v122, v124, v125
	v_cvt_pk_f16_f32 v123, v126, v127
	v_cvt_pk_f16_f32 v124, v128, v129
	v_cvt_pk_f16_f32 v125, v134, v135
	v_pk_mul_f32 v[118:119], v[118:119], v[204:205]
	global_store_dwordx2 v[166:167], v[122:123], off nt
	global_store_dwordx2 v[166:167], v[124:125], off offset:32 nt
	v_pk_fma_f32 v[122:123], v[114:115], v[204:205], v[198:199] neg_lo:[0,0,1] neg_hi:[0,0,1]
	v_pk_mul_f32 v[124:125], v[120:121], v[174:175]
	v_pk_fma_f32 v[114:115], v[114:115], v[144:145], v[118:119]
	v_pk_mul_f32 v[118:119], v[120:121], v[142:143]
	v_pk_fma_f32 v[124:125], v[116:117], v[142:143], v[124:125] neg_lo:[0,0,1] neg_hi:[0,0,1]
	v_pk_fma_f32 v[116:117], v[116:117], v[174:175], v[118:119]
	v_cvt_pk_f16_f32 v122, v122, v123
	v_cvt_pk_f16_f32 v123, v124, v125
	v_cvt_pk_f16_f32 v114, v114, v115
	v_cvt_pk_f16_f32 v115, v116, v117
	v_mov_b32_e32 v117, v182
	v_mov_b32_e32 v182, v181
	v_mov_b32_e32 v121, v178
	v_mov_b32_e32 v178, v177
	global_store_dwordx2 v[166:167], v[122:123], off offset:256 nt
	global_store_dwordx2 v[166:167], v[114:115], off offset:288 nt
	v_mov_b32_e32 v116, v180
	v_pk_mul_f32 v[118:119], v[46:47], v[182:183]
	v_mov_b32_e32 v120, v176
; DI unsigned pk2(float a, float b) { typedef _Float16 h2 __attribute__((ext_vector_type(2))); h2 v; v[0] = (f16)a; v[1] = (f16)b; return __builtin_bit_cast(unsigned, v); }
;   DI void operator()(const f32x4 (&acc)[2][2][4][2], const GUnit& u, int wr, int wc, int fr, int fq) const {
;     ...
;     if (seg == 0 || seg == 1) {
;       const float sc = (seg == 0) ? QSCALE : 1.f;
;       if (wc == 0) {
; #pragma unroll
;         for (int ai = 0; ai < 2; ++ai) {
;           f32x4 ca[4], cb[4];
; #pragma unroll
;           for (int m = 0; m < 4; ++m) { const float* rp = ROT + (size_t)(row0 + ai * 128 + m * 16) * 96 + 8 * fq; ca[m] = *(const f32x4*)rp; cb[m] = *(const f32x4*)(rp + 4); }
; #pragma unroll
;           for (int m = 0; m < 4; ++m) {
;             f16* zp = Z + (size_t)(row0 + ai * 128 + m * 16) * ZW + u.pn * 256 + 4 * fq;
;             const float cs[4] = {ca[m][0], ca[m][2], cb[m][0], cb[m][2]}, sn[4] = {ca[m][1], ca[m][3], cb[m][1], cb[m][3]};
; #pragma unroll
;             for (int bj = 0; bj < 2; ++bj) {
;               const f32x4 x1 = acc[ai][bj][m][0], x2 = acc[ai][bj][m][1];
;               f32x4 o1, o2;
; #pragma unroll
;               for (int j = 0; j < 4; ++j) { o1[j] = (x1[j] * cs[j] - x2[j] * sn[j]) * sc; o2[j] = (x1[j] * sn[j] + x2[j] * cs[j]) * sc; }
;               u32x2_ w1, w2; w1.x = pk2(o1[0], o1[1]); w1.y = pk2(o1[2], o1[3]); w2.x = pk2(o2[0], o2[1]); w2.y = pk2(o2[2], o2[3]);
;               __builtin_nontemporal_store(w1, (u32x2_*)(zp + bj * 128)); __builtin_nontemporal_store(w2, (u32x2_*)(zp + bj * 128 + 16));
;             }
;           }
;         }
	v_pk_mul_f32 v[122:123], v[48:49], v[178:179]
	v_mad_i64_i32 v[114:115], s[44:45], v171, s81, v[132:133]
	v_pk_fma_f32 v[118:119], v[42:43], v[116:117], v[118:119] neg_lo:[0,0,1] neg_hi:[0,0,1]
	v_pk_fma_f32 v[122:123], v[44:45], v[120:121], v[122:123] neg_lo:[0,0,1] neg_hi:[0,0,1]
	v_lshl_add_u64 v[114:115], v[114:115], 0, s[42:43]
	v_cvt_pk_f16_f32 v118, v118, v119
	v_cvt_pk_f16_f32 v119, v122, v123
	v_pk_mul_f32 v[122:123], v[46:47], v[116:117]
	v_pk_mul_f32 v[124:125], v[48:49], v[120:121]
	v_lshl_add_u64 v[114:115], v[114:115], 0, v[130:131]
	v_pk_fma_f32 v[122:123], v[42:43], v[182:183], v[122:123]
	v_pk_fma_f32 v[124:125], v[44:45], v[178:179], v[124:125]
	v_cvt_pk_f16_f32 v122, v122, v123
	v_cvt_pk_f16_f32 v123, v124, v125
	global_store_dwordx2 v[114:115], v[118:119], off nt
	global_store_dwordx2 v[114:115], v[122:123], off offset:32 nt
	v_pk_mul_f32 v[118:119], v[110:111], v[182:183]
	v_pk_mul_f32 v[110:111], v[110:111], v[116:117]
	v_pk_fma_f32 v[118:119], v[106:107], v[116:117], v[118:119] neg_lo:[0,0,1] neg_hi:[0,0,1]
	v_pk_mul_f32 v[122:123], v[112:113], v[178:179]
	v_pk_fma_f32 v[106:107], v[106:107], v[182:183], v[110:111]
	v_pk_mul_f32 v[110:111], v[112:113], v[120:121]
	v_pk_fma_f32 v[122:123], v[108:109], v[120:121], v[122:123] neg_lo:[0,0,1] neg_hi:[0,0,1]
	v_pk_fma_f32 v[108:109], v[108:109], v[178:179], v[110:111]
	v_cvt_pk_f16_f32 v118, v118, v119
	v_cvt_pk_f16_f32 v119, v122, v123
	v_cvt_pk_f16_f32 v106, v106, v107
	v_cvt_pk_f16_f32 v107, v108, v109
	v_mov_b32_e32 v109, v190
	v_mov_b32_e32 v190, v189
	v_mov_b32_e32 v113, v186
	v_mov_b32_e32 v186, v185
	global_store_dwordx2 v[114:115], v[118:119], off offset:256 nt
	global_store_dwordx2 v[114:115], v[106:107], off offset:288 nt
	v_mov_b32_e32 v108, v188
	v_pk_mul_f32 v[110:111], v[30:31], v[190:191]
	v_mov_b32_e32 v112, v184
	v_pk_mul_f32 v[114:115], v[32:33], v[186:187]
	v_pk_fma_f32 v[110:111], v[26:27], v[108:109], v[110:111] neg_lo:[0,0,1] neg_hi:[0,0,1]
	v_pk_fma_f32 v[114:115], v[28:29], v[112:113], v[114:115] neg_lo:[0,0,1] neg_hi:[0,0,1]
	v_mad_i64_i32 v[106:107], s[44:45], v206, s81, v[132:133]
	v_cvt_pk_f16_f32 v110, v110, v111
	v_cvt_pk_f16_f32 v111, v114, v115
	v_pk_mul_f32 v[114:115], v[30:31], v[108:109]
	v_pk_mul_f32 v[116:117], v[32:33], v[112:113]
	v_lshl_add_u64 v[106:107], v[106:107], 0, s[42:43]
	v_pk_fma_f32 v[114:115], v[26:27], v[190:191], v[114:115]
	v_pk_fma_f32 v[116:117], v[28:29], v[186:187], v[116:117]
	v_lshl_add_u64 v[106:107], v[106:107], 0, v[130:131]
	v_cvt_pk_f16_f32 v114, v114, v115
	v_cvt_pk_f16_f32 v115, v116, v117
	global_store_dwordx2 v[106:107], v[110:111], off nt
	global_store_dwordx2 v[106:107], v[114:115], off offset:32 nt
	v_pk_mul_f32 v[110:111], v[102:103], v[190:191]
	v_pk_mul_f32 v[114:115], v[104:105], v[186:187]
	v_pk_mul_f32 v[102:103], v[102:103], v[108:109]
	v_pk_fma_f32 v[110:111], v[98:99], v[108:109], v[110:111] neg_lo:[0,0,1] neg_hi:[0,0,1]
	v_pk_fma_f32 v[114:115], v[100:101], v[112:113], v[114:115] neg_lo:[0,0,1] neg_hi:[0,0,1]
	v_pk_fma_f32 v[98:99], v[98:99], v[190:191], v[102:103]
	v_pk_mul_f32 v[102:103], v[104:105], v[112:113]
	v_cvt_pk_f16_f32 v110, v110, v111
	v_cvt_pk_f16_f32 v111, v114, v115
	v_pk_fma_f32 v[100:101], v[100:101], v[186:187], v[102:103]
	v_add_u32_e32 v134, 0x80, v170
	v_cvt_pk_f16_f32 v98, v98, v99
	v_cvt_pk_f16_f32 v99, v100, v101
	global_store_dwordx2 v[106:107], v[110:111], off offset:256 nt
	global_store_dwordx2 v[106:107], v[98:99], off offset:288 nt
	v_add_u32_e32 v142, 0x90, v170
	v_add_u32_e32 v143, 0xa0, v170
	v_add_u32_e32 v144, 0xb0, v170
	v_mad_i64_i32 v[134:135], s[44:45], v134, s81, v[132:133]
	v_lshl_add_u64 v[134:135], v[134:135], 0, s[42:43]
	v_lshl_add_u64 v[134:135], v[134:135], 0, v[130:131]
	v_mov_b32_e32 v98, v208
	v_mov_b32_e32 v99, v209
	v_mov_b32_e32 v100, v210
	v_mov_b32_e32 v101, v211
	v_mov_b32_e32 v102, v212
	v_mov_b32_e32 v103, v213
	v_mov_b32_e32 v104, v214
	v_mov_b32_e32 v105, v215
	v_mov_b32_e32 v106, v216
	v_mov_b32_e32 v107, v217
	v_mov_b32_e32 v108, v218
	v_mov_b32_e32 v109, v219
	v_mov_b32_e32 v110, v220
	v_mov_b32_e32 v111, v221
	v_mov_b32_e32 v112, v222
	v_mov_b32_e32 v113, v223
	v_mov_b32_e32 v114, v224
	v_mov_b32_e32 v115, v225
	v_mov_b32_e32 v116, v226
	v_mov_b32_e32 v117, v227
	v_mov_b32_e32 v118, v228
	v_mov_b32_e32 v119, v229
	v_mov_b32_e32 v120, v230
	v_mov_b32_e32 v121, v231
	v_mov_b32_e32 v122, v232
	v_mov_b32_e32 v123, v233
	v_mov_b32_e32 v124, v234
	v_mov_b32_e32 v125, v235
	v_mov_b32_e32 v126, v236
	v_mov_b32_e32 v127, v237
	v_mov_b32_e32 v128, v238
	v_mov_b32_e32 v129, v239
	v_mov_b32_e32 v137, v100
	v_mov_b32_e32 v100, v99
	v_mov_b32_e32 v139, v104
	v_mov_b32_e32 v104, v103
	v_mov_b32_e32 v136, v98
	v_pk_mul_f32 v[98:99], v[38:39], v[100:101]
	v_mov_b32_e32 v138, v102
	v_pk_mul_f32 v[102:103], v[40:41], v[104:105]
	v_pk_fma_f32 v[98:99], v[34:35], v[136:137], v[98:99] neg_lo:[0,0,1] neg_hi:[0,0,1]
	v_pk_fma_f32 v[102:103], v[36:37], v[138:139], v[102:103] neg_lo:[0,0,1] neg_hi:[0,0,1]
	v_cvt_pk_f16_f32 v98, v98, v99
	v_cvt_pk_f16_f32 v99, v102, v103
	v_pk_mul_f32 v[102:103], v[38:39], v[136:137]
	v_pk_mul_f32 v[140:141], v[40:41], v[138:139]
	v_pk_fma_f32 v[102:103], v[34:35], v[100:101], v[102:103]
	v_pk_fma_f32 v[140:141], v[36:37], v[104:105], v[140:141]
	v_cvt_pk_f16_f32 v102, v102, v103
	v_cvt_pk_f16_f32 v103, v140, v141
	global_store_dwordx2 v[134:135], v[98:99], off nt
	global_store_dwordx2 v[134:135], v[102:103], off offset:32 nt
	v_pk_mul_f32 v[98:99], v[94:95], v[100:101]
	v_pk_mul_f32 v[94:95], v[94:95], v[136:137]
	v_pk_fma_f32 v[98:99], v[90:91], v[136:137], v[98:99] neg_lo:[0,0,1] neg_hi:[0,0,1]
; DI unsigned pk2(float a, float b) { typedef _Float16 h2 __attribute__((ext_vector_type(2))); h2 v; v[0] = (f16)a; v[1] = (f16)b; return __builtin_bit_cast(unsigned, v); }
;   DI void operator()(const f32x4 (&acc)[2][2][4][2], const GUnit& u, int wr, int wc, int fr, int fq) const {
;     ...
;     if (seg == 0 || seg == 1) {
;       const float sc = (seg == 0) ? QSCALE : 1.f;
;       if (wc == 0) {
; #pragma unroll
;         for (int ai = 0; ai < 2; ++ai) {
;           f32x4 ca[4], cb[4];
; #pragma unroll
;           for (int m = 0; m < 4; ++m) { const float* rp = ROT + (size_t)(row0 + ai * 128 + m * 16) * 96 + 8 * fq; ca[m] = *(const f32x4*)rp; cb[m] = *(const f32x4*)(rp + 4); }
; #pragma unroll
;           for (int m = 0; m < 4; ++m) {
;             f16* zp = Z + (size_t)(row0 + ai * 128 + m * 16) * ZW + u.pn * 256 + 4 * fq;
;             const float cs[4] = {ca[m][0], ca[m][2], cb[m][0], cb[m][2]}, sn[4] = {ca[m][1], ca[m][3], cb[m][1], cb[m][3]};
; #pragma unroll
;             for (int bj = 0; bj < 2; ++bj) {
;               const f32x4 x1 = acc[ai][bj][m][0], x2 = acc[ai][bj][m][1];
;               f32x4 o1, o2;
; #pragma unroll
;               for (int j = 0; j < 4; ++j) { o1[j] = (x1[j] * cs[j] - x2[j] * sn[j]) * sc; o2[j] = (x1[j] * sn[j] + x2[j] * cs[j]) * sc; }
;               u32x2_ w1, w2; w1.x = pk2(o1[0], o1[1]); w1.y = pk2(o1[2], o1[3]); w2.x = pk2(o2[0], o2[1]); w2.y = pk2(o2[2], o2[3]);
;               __builtin_nontemporal_store(w1, (u32x2_*)(zp + bj * 128)); __builtin_nontemporal_store(w2, (u32x2_*)(zp + bj * 128 + 16));
;             }
;           }
;         }
	v_pk_mul_f32 v[102:103], v[96:97], v[104:105]
	v_pk_fma_f32 v[90:91], v[90:91], v[100:101], v[94:95]
	v_pk_mul_f32 v[94:95], v[96:97], v[138:139]
	v_pk_fma_f32 v[102:103], v[92:93], v[138:139], v[102:103] neg_lo:[0,0,1] neg_hi:[0,0,1]
	v_pk_fma_f32 v[92:93], v[92:93], v[104:105], v[94:95]
	v_cvt_pk_f16_f32 v98, v98, v99
	v_cvt_pk_f16_f32 v99, v102, v103
	v_cvt_pk_f16_f32 v90, v90, v91
	v_cvt_pk_f16_f32 v91, v92, v93
	v_mov_b32_e32 v93, v108
	v_mov_b32_e32 v108, v107
	v_mov_b32_e32 v97, v112
	v_mov_b32_e32 v112, v111
	global_store_dwordx2 v[134:135], v[98:99], off offset:256 nt
	global_store_dwordx2 v[134:135], v[90:91], off offset:288 nt
	v_mov_b32_e32 v92, v106
	v_pk_mul_f32 v[94:95], v[22:23], v[108:109]
	v_mov_b32_e32 v96, v110
	v_pk_mul_f32 v[98:99], v[24:25], v[112:113]
	v_mad_i64_i32 v[90:91], s[44:45], v142, s81, v[132:133]
	v_pk_fma_f32 v[94:95], v[18:19], v[92:93], v[94:95] neg_lo:[0,0,1] neg_hi:[0,0,1]
	v_pk_fma_f32 v[98:99], v[20:21], v[96:97], v[98:99] neg_lo:[0,0,1] neg_hi:[0,0,1]
	v_lshl_add_u64 v[90:91], v[90:91], 0, s[42:43]
	v_cvt_pk_f16_f32 v94, v94, v95
	v_cvt_pk_f16_f32 v95, v98, v99
	v_pk_mul_f32 v[98:99], v[22:23], v[92:93]
	v_pk_mul_f32 v[100:101], v[24:25], v[96:97]
	v_lshl_add_u64 v[90:91], v[90:91], 0, v[130:131]
	v_pk_fma_f32 v[98:99], v[18:19], v[108:109], v[98:99]
	v_pk_fma_f32 v[100:101], v[20:21], v[112:113], v[100:101]
	v_cvt_pk_f16_f32 v98, v98, v99
	v_cvt_pk_f16_f32 v99, v100, v101
	global_store_dwordx2 v[90:91], v[94:95], off nt
	global_store_dwordx2 v[90:91], v[98:99], off offset:32 nt
	v_pk_mul_f32 v[94:95], v[86:87], v[108:109]
	v_pk_mul_f32 v[86:87], v[86:87], v[92:93]
	v_pk_fma_f32 v[94:95], v[82:83], v[92:93], v[94:95] neg_lo:[0,0,1] neg_hi:[0,0,1]
	v_pk_mul_f32 v[98:99], v[88:89], v[112:113]
	v_pk_fma_f32 v[82:83], v[82:83], v[108:109], v[86:87]
	v_pk_mul_f32 v[86:87], v[88:89], v[96:97]
	v_pk_fma_f32 v[98:99], v[84:85], v[96:97], v[98:99] neg_lo:[0,0,1] neg_hi:[0,0,1]
	v_pk_fma_f32 v[84:85], v[84:85], v[112:113], v[86:87]
	v_cvt_pk_f16_f32 v94, v94, v95
	v_cvt_pk_f16_f32 v95, v98, v99
	v_cvt_pk_f16_f32 v82, v82, v83
	v_cvt_pk_f16_f32 v83, v84, v85
	v_mov_b32_e32 v85, v120
	v_mov_b32_e32 v120, v119
	v_mov_b32_e32 v89, v116
	v_mov_b32_e32 v116, v115
	global_store_dwordx2 v[90:91], v[94:95], off offset:256 nt
	global_store_dwordx2 v[90:91], v[82:83], off offset:288 nt
	v_mov_b32_e32 v84, v118
	v_pk_mul_f32 v[86:87], v[14:15], v[120:121]
	v_mov_b32_e32 v88, v114
	v_pk_mul_f32 v[90:91], v[16:17], v[116:117]
	v_mad_i64_i32 v[82:83], s[44:45], v143, s81, v[132:133]
	v_pk_fma_f32 v[86:87], v[10:11], v[84:85], v[86:87] neg_lo:[0,0,1] neg_hi:[0,0,1]
	v_pk_fma_f32 v[90:91], v[12:13], v[88:89], v[90:91] neg_lo:[0,0,1] neg_hi:[0,0,1]
	v_lshl_add_u64 v[82:83], v[82:83], 0, s[42:43]
	v_cvt_pk_f16_f32 v86, v86, v87
	v_cvt_pk_f16_f32 v87, v90, v91
	v_pk_mul_f32 v[90:91], v[14:15], v[84:85]
	v_pk_mul_f32 v[92:93], v[16:17], v[88:89]
	v_lshl_add_u64 v[82:83], v[82:83], 0, v[130:131]
	v_pk_fma_f32 v[90:91], v[10:11], v[120:121], v[90:91]
	v_pk_fma_f32 v[92:93], v[12:13], v[116:117], v[92:93]
	v_cvt_pk_f16_f32 v90, v90, v91
	v_cvt_pk_f16_f32 v91, v92, v93
	global_store_dwordx2 v[82:83], v[86:87], off nt
	global_store_dwordx2 v[82:83], v[90:91], off offset:32 nt
	v_pk_mul_f32 v[86:87], v[78:79], v[120:121]
	v_pk_mul_f32 v[78:79], v[78:79], v[84:85]
	v_pk_fma_f32 v[86:87], v[74:75], v[84:85], v[86:87] neg_lo:[0,0,1] neg_hi:[0,0,1]
	v_pk_mul_f32 v[90:91], v[80:81], v[116:117]
	v_pk_fma_f32 v[74:75], v[74:75], v[120:121], v[78:79]
	v_pk_mul_f32 v[78:79], v[80:81], v[88:89]
	v_pk_fma_f32 v[90:91], v[76:77], v[88:89], v[90:91] neg_lo:[0,0,1] neg_hi:[0,0,1]
	v_pk_fma_f32 v[76:77], v[76:77], v[116:117], v[78:79]
	v_cvt_pk_f16_f32 v86, v86, v87
	v_cvt_pk_f16_f32 v87, v90, v91
	v_cvt_pk_f16_f32 v74, v74, v75
	v_cvt_pk_f16_f32 v75, v76, v77
	v_mov_b32_e32 v77, v128
	v_mov_b32_e32 v128, v127
	v_mov_b32_e32 v81, v124
	v_mov_b32_e32 v124, v123
	global_store_dwordx2 v[82:83], v[86:87], off offset:256 nt
	global_store_dwordx2 v[82:83], v[74:75], off offset:288 nt
	v_mov_b32_e32 v76, v126
	v_pk_mul_f32 v[78:79], v[6:7], v[128:129]
	v_mov_b32_e32 v80, v122
	v_pk_mul_f32 v[82:83], v[8:9], v[124:125]
	v_pk_fma_f32 v[78:79], v[2:3], v[76:77], v[78:79] neg_lo:[0,0,1] neg_hi:[0,0,1]
	v_pk_fma_f32 v[82:83], v[4:5], v[80:81], v[82:83] neg_lo:[0,0,1] neg_hi:[0,0,1]
	v_mad_i64_i32 v[74:75], s[44:45], v144, s81, v[132:133]
	v_cvt_pk_f16_f32 v78, v78, v79
	v_cvt_pk_f16_f32 v79, v82, v83
	v_pk_mul_f32 v[82:83], v[6:7], v[76:77]
	v_pk_mul_f32 v[84:85], v[8:9], v[80:81]
	v_lshl_add_u64 v[74:75], v[74:75], 0, s[42:43]
	v_pk_fma_f32 v[82:83], v[2:3], v[128:129], v[82:83]
	v_pk_fma_f32 v[84:85], v[4:5], v[124:125], v[84:85]
	v_lshl_add_u64 v[74:75], v[74:75], 0, v[130:131]
	v_cvt_pk_f16_f32 v82, v82, v83
	v_cvt_pk_f16_f32 v83, v84, v85
	global_store_dwordx2 v[74:75], v[78:79], off nt
	global_store_dwordx2 v[74:75], v[82:83], off offset:32 nt
	v_pk_mul_f32 v[78:79], v[66:67], v[128:129]
	v_pk_mul_f32 v[82:83], v[68:69], v[124:125]
	v_pk_fma_f32 v[78:79], v[70:71], v[76:77], v[78:79] neg_lo:[0,0,1] neg_hi:[0,0,1]
	v_pk_fma_f32 v[82:83], v[72:73], v[80:81], v[82:83] neg_lo:[0,0,1] neg_hi:[0,0,1]
	v_pk_mul_f32 v[66:67], v[66:67], v[76:77]
	v_pk_mul_f32 v[68:69], v[68:69], v[80:81]
	v_cvt_pk_f16_f32 v78, v78, v79
	v_cvt_pk_f16_f32 v79, v82, v83
	v_pk_fma_f32 v[66:67], v[70:71], v[128:129], v[66:67]
	v_pk_fma_f32 v[68:69], v[72:73], v[124:125], v[68:69]
	v_cvt_pk_f16_f32 v66, v66, v67
	v_cvt_pk_f16_f32 v67, v68, v69
	global_store_dwordx2 v[74:75], v[78:79], off offset:256 nt
	global_store_dwordx2 v[74:75], v[66:67], off offset:288 nt

; template <bool PEEL, class Sched, class Epi>
; DI void gemm_stream(LAS unsigned char* lds, int K, long lda, long ldb, const Sched& S, const Epi& E) {
;     ...
;     if (!has_next) break;
; #pragma unroll
;     for (int a = 0; a < 2; ++a)
; #pragma unroll
;       for (int b = 0; b < 2; ++b)
; #pragma unroll
;         for (int m = 0; m < 4; ++m)
; #pragma unroll
;           for (int n = 0; n < 2; ++n) { acc[a][b][m][n] = (f32x4){0.f, 0.f, 0.f, 0.f}; asm volatile("" : "+v"(acc[a][b][m][n])); }
;     cur = nxt; cA = nA; cB = nB; ++ui;
;   }
.LBB0_281:
	s_andn2_b64 vcc, exec, s[6:7]
	s_mov_b64 s[6:7], -1
	s_cbranch_vccnz .LBB0_213
	s_mov_b32 s4, s5
	s_mov_b32 s6, s5
	s_mov_b32 s7, s5
	v_mov_b64_e32 v[60:61], s[6:7]
	v_mov_b64_e32 v[64:65], s[6:7]
	v_mov_b64_e32 v[52:53], s[6:7]
	v_mov_b64_e32 v[56:57], s[6:7]
	v_mov_b64_e32 v[44:45], s[6:7]
	v_mov_b64_e32 v[48:49], s[6:7]
	v_mov_b64_e32 v[28:29], s[6:7]
	v_mov_b64_e32 v[32:33], s[6:7]
	v_mov_b64_e32 v[124:125], s[6:7]
	v_mov_b64_e32 v[128:129], s[6:7]
	v_mov_b64_e32 v[116:117], s[6:7]
	v_mov_b64_e32 v[120:121], s[6:7]
	v_mov_b64_e32 v[108:109], s[6:7]
	v_mov_b64_e32 v[112:113], s[6:7]
	v_mov_b64_e32 v[100:101], s[6:7]
	v_mov_b64_e32 v[104:105], s[6:7]
	v_mov_b64_e32 v[58:59], s[4:5]
	v_mov_b64_e32 v[62:63], s[4:5]
	v_mov_b64_e32 v[50:51], s[4:5]
	v_mov_b64_e32 v[54:55], s[4:5]
	v_mov_b64_e32 v[42:43], s[4:5]
	v_mov_b64_e32 v[46:47], s[4:5]
	v_mov_b64_e32 v[26:27], s[4:5]
	v_mov_b64_e32 v[30:31], s[4:5]
	v_mov_b64_e32 v[122:123], s[4:5]
	v_mov_b64_e32 v[126:127], s[4:5]
	v_mov_b64_e32 v[114:115], s[4:5]
	v_mov_b64_e32 v[118:119], s[4:5]
	v_mov_b64_e32 v[106:107], s[4:5]
	v_mov_b64_e32 v[110:111], s[4:5]
	v_mov_b64_e32 v[98:99], s[4:5]
	v_mov_b64_e32 v[102:103], s[4:5]
	s_cmp_eq_u32 s100, 1
	s_cbranch_scc1 .Lzero_skip
	v_mov_b64_e32 v[68:69], s[4:5]
	v_mov_b64_e32 v[36:37], s[4:5]
	v_mov_b64_e32 v[40:41], s[4:5]
	v_mov_b64_e32 v[20:21], s[4:5]
	v_mov_b64_e32 v[24:25], s[4:5]
	v_mov_b64_e32 v[12:13], s[4:5]
	v_mov_b64_e32 v[16:17], s[4:5]
	v_mov_b64_e32 v[2:3], s[4:5]
	v_mov_b64_e32 v[8:9], s[4:5]
	v_mov_b64_e32 v[92:93], s[4:5]
	v_mov_b64_e32 v[96:97], s[4:5]
	v_mov_b64_e32 v[84:85], s[4:5]
	v_mov_b64_e32 v[88:89], s[4:5]
	v_mov_b64_e32 v[76:77], s[4:5]
	v_mov_b64_e32 v[80:81], s[4:5]
	v_mov_b64_e32 v[72:73], s[4:5]
	v_mov_b64_e32 v[66:67], s[4:5]
	v_mov_b64_e32 v[34:35], s[4:5]
	v_mov_b64_e32 v[38:39], s[4:5]
	v_mov_b64_e32 v[18:19], s[4:5]
	v_mov_b64_e32 v[22:23], s[4:5]
	v_mov_b64_e32 v[10:11], s[4:5]
	v_mov_b64_e32 v[14:15], s[4:5]
	v_mov_b64_e32 v[4:5], s[4:5]
	v_mov_b64_e32 v[6:7], s[4:5]
	v_mov_b64_e32 v[90:91], s[4:5]
	v_mov_b64_e32 v[94:95], s[4:5]
	v_mov_b64_e32 v[82:83], s[4:5]
	v_mov_b64_e32 v[86:87], s[4:5]
	v_mov_b64_e32 v[74:75], s[4:5]
	v_mov_b64_e32 v[78:79], s[4:5]
	v_mov_b64_e32 v[70:71], s[4:5]
.Lzero_skip:
	s_mov_b64 s[6:7], 0
	s_branch .LBB0_213

; #define MFMA(a, b, c) __builtin_amdgcn_mfma_f32_32x32x16_f16((a), (b), (c), 0, 0, 0)
; #define QK_LD(dst, s0) do { dst[0] = *(const f16x8*)(Kst + kbe + 512 * ((s0) >> 1)); dst[1] = *(const f16x8*)(Kst + kbe + 512 * ((s0) >> 1) + 8192); \
;     dst[2] = *(const f16x8*)(Kst + kbo + 512 * ((s0) >> 1)); dst[3] = *(const f16x8*)(Kst + kbo + 512 * ((s0) >> 1) + 8192); } while (0)
; #define QK_LD(dst, s0) do { dst[0] = *(const f16x8*)(Kst + kbe + 512 * ((s0) >> 1)); dst[1] = *(const f16x8*)(Kst + kbe + 512 * ((s0) >> 1) + 8192); \
;     dst[2] = *(const f16x8*)(Kst + kbo + 512 * ((s0) >> 1)); dst[3] = *(const f16x8*)(Kst + kbo + 512 * ((s0) >> 1) + 8192); } while (0)
; DI void qk_exp(f32x16& n0, f32x16& n1, const char* Kst, const f16x8 (&qf)[8], unsigned kbe, unsigned kbo, f32x16& c0, f32x16& c1, float me, float& ps) {
;     ...
;   float s_ = 0.f;
;   QK_LD(ka, 0);
;   n0 = MFMA(ka[0], qf[0], zero); n1 = MFMA(ka[1], qf[0], zero); n0 = MFMA(ka[2], qf[1], n0); n1 = MFMA(ka[3], qf[1], n1);
.LBB0_600:
	s_add_i32 s6, s22, 3
	s_cmp_le_i32 s23, s6
	s_cselect_b64 s[4:5], -1, 0
	s_cmp_lt_i32 s23, s12
	s_waitcnt lgkmcnt(0)
	s_barrier
	s_cselect_b64 s[8:9], -1, 0
	s_lshl_b32 s100, s25, 15
	s_and_b32 s100, s100, 0x18000
	v_or_b32_e32 v205, s100, v190
	ds_read_b128 v[98:101], v205
	ds_read_b128 v[102:105], v205 offset:8192
	v_or_b32_e32 v216, s100, v189
	ds_read_b128 v[196:199], v216
	ds_read_b128 v[200:203], v216 offset:8192
	s_and_b64 s[4:5], s[4:5], s[8:9]
	s_andn2_b64 vcc, exec, s[4:5]
	s_cbranch_vccnz .LBB0_611
	s_sub_i32 s4, s21, s23
	s_lshl_b32 s7, s4, 6
	s_sub_i32 s4, s15, s23
	s_lshl_b32 s9, s4, 6
	s_lshl_b32 s26, s23, 14
	s_lshl_b32 s27, s23, 15
	s_and_b32 s8, s27, 0x18000
	s_cmp_gt_i32 s23, 1
	s_mov_b64 s[4:5], -1
	s_cbranch_scc0 .LBB0_608
	s_branch .LBB0_603

; #define LAS __attribute__((address_space(3)))
; DI void glds16(const char* g, LAS unsigned char* l) { __builtin_amdgcn_global_load_lds((const unsigned*)g, (LAS unsigned*)l, 16, 0, 0); }
; DI void dma_kv128(LAS unsigned char* stage, unsigned ldsw, const char* K, const char* V, unsigned voff, long ldb) {
;   glds16(K + (size_t)voff, stage + ldsw); glds16(K + 32 * ldb + (size_t)voff, stage + ldsw + 8192);
;   glds16(V + (size_t)voff, stage + 16384 + ldsw); glds16(V + 32 * ldb + (size_t)voff, stage + 16384 + ldsw + 8192);
; }
.LBB0_603:
	s_cmp_ge_i32 s23, s14
	s_cbranch_scc0 .LBB0_605
	s_mul_i32 s5, s7, 0x3000
	s_mul_hi_i32 s4, s7, 0x3000
	s_add_u32 s28, s61, s5
	s_addc_u32 s29, s3, s4
	s_add_u32 s4, s28, s17
	s_addc_u32 s5, s29, 0
	s_add_u32 s28, s28, s18
	s_addc_u32 s29, s29, 0
	v_lshl_add_u64 v[218:219], s[4:5], 0, v[206:207]
	s_add_i32 s4, s8, s60
	s_mov_b32 m0, s4
	s_nop 0
	global_load_lds_dwordx4 v[218:219], off
	v_lshl_add_u64 v[218:219], v[218:219], 0, s[86:87]
	s_add_i32 m0, s4, 0x2000
	s_nop 0
	global_load_lds_dwordx4 v[218:219], off
	v_lshl_add_u64 v[218:219], s[28:29], 0, v[206:207]
	s_add_i32 m0, s4, 0x4000
	s_mov_b64 s[4:5], 0
	global_load_lds_dwordx4 v[218:219], off
	v_lshl_add_u64 v[218:219], v[218:219], 0, s[86:87]
.LBB0_605:
	s_andn2_b64 vcc, exec, s[4:5]
	s_cbranch_vccnz .LBB0_607
	s_mul_i32 s5, s9, 0x3000
	s_mul_hi_i32 s4, s9, 0x3000
	s_add_u32 s28, s61, s5
	s_addc_u32 s29, s3, s4
	s_add_u32 s4, s28, s19
	s_addc_u32 s5, s29, 0
	s_add_u32 s28, s28, s20
	s_addc_u32 s29, s29, 0
	v_lshl_add_u64 v[218:219], s[4:5], 0, v[206:207]
	s_add_i32 s4, s8, s60
	s_mov_b32 m0, s4
	s_nop 0
	global_load_lds_dwordx4 v[218:219], off
	v_lshl_add_u64 v[218:219], v[218:219], 0, s[86:87]
	s_add_i32 m0, s4, 0x2000
	s_nop 0
	global_load_lds_dwordx4 v[218:219], off
	v_lshl_add_u64 v[218:219], s[28:29], 0, v[206:207]
	s_add_i32 m0, s4, 0x4000
	s_nop 0
	global_load_lds_dwordx4 v[218:219], off
	v_lshl_add_u64 v[218:219], v[218:219], 0, s[86:87]

; #define LAS __attribute__((address_space(3)))
; DI void glds16(const char* g, LAS unsigned char* l) { __builtin_amdgcn_global_load_lds((const unsigned*)g, (LAS unsigned*)l, 16, 0, 0); }
; DI void dma_kv128(LAS unsigned char* stage, unsigned ldsw, const char* K, const char* V, unsigned voff, long ldb) {
;   glds16(K + (size_t)voff, stage + ldsw); glds16(K + 32 * ldb + (size_t)voff, stage + ldsw + 8192);
;   glds16(V + (size_t)voff, stage + 16384 + ldsw); glds16(V + 32 * ldb + (size_t)voff, stage + 16384 + ldsw + 8192);
; }
.LBB0_608:
	s_andn2_b64 vcc, exec, s[4:5]
	s_cbranch_vccnz .LBB0_610
	s_ashr_i32 s29, s26, 31
	s_add_u32 s4, s64, s26
	s_addc_u32 s5, s65, s29
	s_add_u32 s28, s80, s26
	s_addc_u32 s29, s81, s29
	v_lshl_add_u64 v[218:219], s[4:5], 0, v[162:163]
	s_add_i32 s4, s8, s60
	s_mov_b32 m0, s4
	s_nop 0
	global_load_lds_dwordx4 v[218:219], off
	v_lshl_add_u64 v[218:219], v[218:219], 0, s[34:35]
	s_add_i32 m0, s4, 0x2000
	s_nop 0
	global_load_lds_dwordx4 v[218:219], off
	v_lshl_add_u64 v[218:219], s[28:29], 0, v[162:163]
	s_add_i32 m0, s4, 0x4000
	s_nop 0
	global_load_lds_dwordx4 v[218:219], off
	v_lshl_add_u64 v[218:219], v[218:219], 0, s[34:35]
.LBB0_610:
	s_add_i32 s4, s8, s60
	s_add_i32 m0, s4, 0x6000
	s_add_i32 s8, s23, 1
	global_load_lds_dwordx4 v[218:219], off
	s_cmp_lt_i32 s23, s6
	s_cselect_b64 s[4:5], -1, 0
	s_cmp_lt_i32 s8, s12
	s_cselect_b64 s[28:29], -1, 0
	s_and_b64 s[4:5], s[4:5], s[28:29]
	s_sub_i32 s7, s7, 64
	s_sub_i32 s9, s9, 64
	s_addk_i32 s26, 0x4000
	s_add_i32 s27, s27, 0x8000
	s_and_b64 vcc, exec, s[4:5]
	s_cbranch_vccnz .LBB0_602
	s_branch .LBB0_612

; #define MFMA(a, b, c) __builtin_amdgcn_mfma_f32_32x32x16_f16((a), (b), (c), 0, 0, 0)
; #define SBAR() __builtin_amdgcn_sched_barrier(0)
; #define QK_LD(dst, s0) do { dst[0] = *(const f16x8*)(Kst + kbe + 512 * ((s0) >> 1)); dst[1] = *(const f16x8*)(Kst + kbe + 512 * ((s0) >> 1) + 8192); \
;     dst[2] = *(const f16x8*)(Kst + kbo + 512 * ((s0) >> 1)); dst[3] = *(const f16x8*)(Kst + kbo + 512 * ((s0) >> 1) + 8192); } while (0)
; #define QK_LD(dst, s0) do { dst[0] = *(const f16x8*)(Kst + kbe + 512 * ((s0) >> 1)); dst[1] = *(const f16x8*)(Kst + kbe + 512 * ((s0) >> 1) + 8192); \
;     dst[2] = *(const f16x8*)(Kst + kbo + 512 * ((s0) >> 1)); dst[3] = *(const f16x8*)(Kst + kbo + 512 * ((s0) >> 1) + 8192); } while (0)
; #define EXP8(c, b0) do { _Pragma("unroll") for (int j_ = 0; j_ < 8; ++j_) { c[(b0) + j_] = fexp2(c[(b0) + j_] - me); s_ += c[(b0) + j_]; } } while (0)
; DI void qk_exp(f32x16& n0, f32x16& n1, const char* Kst, const f16x8 (&qf)[8], unsigned kbe, unsigned kbo, f32x16& c0, f32x16& c1, float me, float& ps) {
;   const f32x16 zero = {0.f, 0.f, 0.f, 0.f, 0.f, 0.f, 0.f, 0.f, 0.f, 0.f, 0.f, 0.f, 0.f, 0.f, 0.f, 0.f};
;   f16x8 ka[4], kb[4];
;     ...
;   float s_ = 0.f;
;   QK_LD(ka, 0);
;   n0 = MFMA(ka[0], qf[0], zero); n1 = MFMA(ka[1], qf[0], zero); n0 = MFMA(ka[2], qf[1], n0); n1 = MFMA(ka[3], qf[1], n1);
;   QK_LD(kb, 2);
;   EXP8(c0, 0);
;   n0 = MFMA(kb[0], qf[2], n0); n1 = MFMA(kb[1], qf[2], n1); n0 = MFMA(kb[2], qf[3], n0); n1 = MFMA(kb[3], qf[3], n1);
;   QK_LD(ka, 4);
;   EXP8(c0, 8);
;   n0 = MFMA(ka[0], qf[4], n0); n1 = MFMA(ka[1], qf[4], n1); n0 = MFMA(ka[2], qf[5], n0); n1 = MFMA(ka[3], qf[5], n1);
;   QK_LD(kb, 6);
;   EXP8(c1, 0);
;   n0 = MFMA(kb[0], qf[6], n0); n1 = MFMA(kb[1], qf[6], n1); n0 = MFMA(kb[2], qf[7], n0); n1 = MFMA(kb[3], qf[7], n1);
;   EXP8(c1, 8);
;   ps = s_;
;     ...
; }
; DI void pv_max(f32x16 (&o)[4], unsigned vb0, unsigned vb1, const f32x16& p0, const f32x16& p1, const f32x16& n0, const f32x16& n1, float& pm) {
;   f16x8 pb[4]; pb[0] = pack8(p0, 0); pb[1] = pack8(p0, 1); pb[2] = pack8(p1, 0); pb[3] = pack8(p1, 1);
;   VFrag fa;
;   float mx = n0[0];
;   pv_rd<0>(fa, vb0, vb1);
;   asm volatile("s_waitcnt lgkmcnt(0)" ::: "memory"); SBAR();
;   pv_mm(o[0], fa, pb);
;   pv_rd<1>(fa, vb0, vb1);
.LBB0_612:
	v_cndmask_b32_e64 v204, v233, v194, s[0:1]
	s_lshl_b32 s0, s25, 15
	s_and_b32 s7, s0, 0x18000
	s_waitcnt lgkmcnt(0)
	v_mfma_f32_32x32x16_f16 v[114:129], v[98:101], v[150:153], 0
	v_sub_f32_e32 v82, v82, v204
	v_exp_f32_e32 v217, v82
	v_sub_f32_e32 v83, v83, v204
	v_exp_f32_e32 v218, v83
	v_sub_f32_e32 v83, v84, v204
	v_exp_f32_e32 v219, v83
	v_sub_f32_e32 v83, v85, v204
	v_mfma_f32_32x32x16_f16 v[98:113], v[102:105], v[150:153], 0
	v_exp_f32_e32 v220, v83
	v_sub_f32_e32 v83, v86, v204
	v_add_f32_e32 v82, 0, v217
	v_exp_f32_e32 v221, v83
	v_sub_f32_e32 v83, v87, v204
	v_add_f32_e32 v82, v218, v82
	v_exp_f32_e32 v224, v83
	v_mfma_f32_32x32x16_f16 v[114:129], v[196:199], v[158:161], v[114:129]
	v_sub_f32_e32 v83, v88, v204
	v_add_f32_e32 v82, v219, v82
	v_exp_f32_e32 v225, v83
	v_sub_f32_e32 v83, v89, v204
	v_add_f32_e32 v82, v220, v82
	v_exp_f32_e32 v226, v83
	v_add_f32_e32 v82, v221, v82
	v_mfma_f32_32x32x16_f16 v[98:113], v[200:203], v[158:161], v[98:113]
	ds_read_b128 v[196:199], v205 offset:512
	ds_read_b128 v[200:203], v205 offset:8704
	ds_read_b128 v[208:211], v216 offset:512
	ds_read_b128 v[212:215], v216 offset:8704
	v_add_f32_e32 v82, v224, v82
	v_add_f32_e32 v82, v225, v82
	v_add_f32_e32 v227, v226, v82
	v_sub_f32_e32 v90, v90, v204
	v_sub_f32_e32 v91, v91, v204
	v_sub_f32_e32 v66, v66, v204
	s_waitcnt lgkmcnt(0)
	v_mfma_f32_32x32x16_f16 v[114:129], v[196:199], v[142:145], v[114:129]
	v_sub_f32_e32 v67, v67, v204
	s_lshl_b32 s0, s22, 15
	s_and_b32 s9, s0, 0x10000
	v_mfma_f32_32x32x16_f16 v[98:113], v[200:203], v[142:145], v[98:113]
	ds_read_b128 v[82:85], v205 offset:1024
	ds_read_b128 v[86:89], v205 offset:9216
	ds_read_b128 v[196:199], v216 offset:1024
	ds_read_b128 v[200:203], v216 offset:9216
	v_mfma_f32_32x32x16_f16 v[114:129], v[208:211], v[154:157], v[114:129]
	v_exp_f32_e32 v208, v90
	v_exp_f32_e32 v209, v91
	v_sub_f32_e32 v91, v92, v204
	v_exp_f32_e32 v210, v91
	v_sub_f32_e32 v91, v93, v204
	v_exp_f32_e32 v211, v91
	v_sub_f32_e32 v91, v94, v204
	v_mfma_f32_32x32x16_f16 v[98:113], v[212:215], v[154:157], v[98:113]
	v_add_f32_e32 v90, v208, v227
	v_exp_f32_e32 v212, v91
	v_sub_f32_e32 v91, v95, v204
	v_add_f32_e32 v90, v209, v90
	v_exp_f32_e32 v213, v91
	v_sub_f32_e32 v91, v96, v204
	v_add_f32_e32 v90, v210, v90
	s_waitcnt lgkmcnt(0)
	v_mfma_f32_32x32x16_f16 v[114:129], v[82:85], v[138:141], v[114:129]
	v_exp_f32_e32 v214, v91
	v_sub_f32_e32 v91, v97, v204
	v_add_f32_e32 v90, v211, v90
	v_exp_f32_e32 v215, v91
	v_add_f32_e32 v90, v212, v90
	v_add_f32_e32 v90, v213, v90
	v_add_f32_e32 v90, v214, v90
	v_mfma_f32_32x32x16_f16 v[98:113], v[86:89], v[138:141], v[98:113]
	v_add_f32_e32 v227, v215, v90
	ds_read_b128 v[82:85], v205 offset:1536
	ds_read_b128 v[86:89], v205 offset:9728
	ds_read_b128 v[90:93], v216 offset:1536
	ds_read_b128 v[94:97], v216 offset:9728
	v_add_u32_e32 v205, s9, v192
	v_mfma_f32_32x32x16_f16 v[114:129], v[196:199], v[146:149], v[114:129]
	v_exp_f32_e32 v196, v66
	v_exp_f32_e32 v197, v67
	v_sub_f32_e32 v67, v68, v204
	v_exp_f32_e32 v198, v67
	v_sub_f32_e32 v67, v69, v204
	v_exp_f32_e32 v199, v67
	v_sub_f32_e32 v67, v70, v204
	v_mfma_f32_32x32x16_f16 v[98:113], v[200:203], v[146:149], v[98:113]
	v_add_f32_e32 v66, v196, v227
	v_exp_f32_e32 v200, v67
	v_sub_f32_e32 v67, v71, v204
	v_add_f32_e32 v66, v197, v66
	v_exp_f32_e32 v201, v67
	v_sub_f32_e32 v67, v72, v204
	v_add_f32_e32 v66, v198, v66
	s_waitcnt lgkmcnt(0)
	v_mfma_f32_32x32x16_f16 v[114:129], v[82:85], v[130:133], v[114:129]
	v_exp_f32_e32 v202, v67
	v_sub_f32_e32 v67, v73, v204
	v_add_f32_e32 v66, v199, v66
	v_exp_f32_e32 v203, v67
	v_sub_f32_e32 v67, v74, v204
	v_add_f32_e32 v66, v200, v66
	v_add_f32_e32 v66, v201, v66
	v_mfma_f32_32x32x16_f16 v[98:113], v[86:89], v[130:133], v[98:113]
	v_exp_f32_e32 v86, v67
	v_sub_f32_e32 v67, v75, v204
	v_exp_f32_e32 v87, v67
	v_sub_f32_e32 v67, v76, v204
	v_add_f32_e32 v66, v202, v66
	v_exp_f32_e32 v88, v67
	v_sub_f32_e32 v67, v77, v204
	v_add_f32_e32 v66, v203, v66
	v_exp_f32_e32 v89, v67
	v_sub_f32_e32 v67, v78, v204
	v_mfma_f32_32x32x16_f16 v[114:129], v[90:93], v[134:137], v[114:129]
	v_add_f32_e32 v66, v86, v66
	v_exp_f32_e32 v90, v67
	v_sub_f32_e32 v67, v79, v204
	v_add_f32_e32 v66, v87, v66
	v_exp_f32_e32 v91, v67
	v_sub_f32_e32 v67, v80, v204
	v_add_f32_e32 v66, v88, v66
	v_exp_f32_e32 v92, v67
	v_sub_f32_e32 v67, v81, v204
	v_add_f32_e32 v66, v89, v66
	v_exp_f32_e32 v93, v67
	v_add_f32_e32 v66, v90, v66
	v_add_f32_e32 v66, v91, v66
	v_add_f32_e32 v66, v92, v66
	v_add_f32_e32 v66, v93, v66
	v_add_f32_e32 v195, v195, v66
	v_add_u32_e32 v204, s9, v1
	ds_read_b64_tr_b16 v[66:67], v204 offset:0
	ds_read_b64_tr_b16 v[68:69], v205 offset:0x800
	ds_read_b64_tr_b16 v[70:71], v204 offset:0x1000
	v_mfma_f32_32x32x16_f16 v[98:113], v[94:97], v[134:137], v[98:113]
	ds_read_b64_tr_b16 v[72:73], v205 offset:0x1800
	ds_read_b64_tr_b16 v[74:75], v204 offset:0x2000
	ds_read_b64_tr_b16 v[76:77], v205 offset:0x2800
	ds_read_b64_tr_b16 v[78:79], v204 offset:0x3000
	ds_read_b64_tr_b16 v[80:81], v205 offset:0x3800
	s_waitcnt lgkmcnt(0)
; #define SBAR() __builtin_amdgcn_sched_barrier(0)
; DI float fexp2(float x) { return __builtin_amdgcn_exp2f(x); }
; DI void pv_max(f32x16 (&o)[4], unsigned vb0, unsigned vb1, const f32x16& p0, const f32x16& p1, const f32x16& n0, const f32x16& n1, float& pm) {
;   f16x8 pb[4]; pb[0] = pack8(p0, 0); pb[1] = pack8(p0, 1); pb[2] = pack8(p1, 0); pb[3] = pack8(p1, 1);
;   VFrag fa;
;   float mx = n0[0];
;   pv_rd<0>(fa, vb0, vb1);
;   asm volatile("s_waitcnt lgkmcnt(0)" ::: "memory"); SBAR();
;   pv_mm(o[0], fa, pb);
;   pv_rd<1>(fa, vb0, vb1);
; #pragma unroll
;   for (int r = 1; r < 8; ++r) mx = fmaxf(mx, n0[r]);
;   asm volatile("s_waitcnt lgkmcnt(0)" ::: "memory"); SBAR();
;   pv_mm(o[1], fa, pb);
;   pv_rd<2>(fa, vb0, vb1);
; #pragma unroll
;   for (int r = 8; r < 16; ++r) mx = fmaxf(mx, n0[r]);
;   asm volatile("s_waitcnt lgkmcnt(0)" ::: "memory"); SBAR();
;   pv_mm(o[2], fa, pb);
;   pv_rd<3>(fa, vb0, vb1);
; #pragma unroll
;   for (int r = 0; r < 8; ++r) mx = fmaxf(mx, n1[r]);
;   asm volatile("s_waitcnt lgkmcnt(0)" ::: "memory"); SBAR();
;   pv_mm(o[3], fa, pb);
; #pragma unroll
;   for (int r = 8; r < 16; ++r) mx = fmaxf(mx, n1[r]);
;   pm = mx;
; }
; DI void osm_decide(float pmn, float& m, float& l, f32x16 (&o)[4]) {
;   if (!__all(pmn - m <= THR)) {
;     float mn = fmaxf(m, pmn); float alpha = fexp2(m - mn); m = mn; l *= alpha;
; #pragma unroll
;     for (int d = 0; d < 4; ++d)
; #pragma unroll
;       for (int r = 0; r < 16; ++r) o[d][r] *= alpha;
;   }
; }
	v_cvt_pk_f16_f32 v85, v225, v226
	v_cvt_pk_f16_f32 v84, v221, v224
	v_cvt_pk_f16_f32 v83, v219, v220
	v_cvt_pk_f16_f32 v82, v217, v218
	s_nop 1
	v_mfma_f32_32x32x16_f16 v[50:65], v[66:69], v[82:85], v[50:65]
	v_cvt_pk_f16_f32 v69, v214, v215
	v_cvt_pk_f16_f32 v68, v212, v213
	v_cvt_pk_f16_f32 v67, v210, v211
	v_cvt_pk_f16_f32 v66, v208, v209
	s_nop 1
	v_mfma_f32_32x32x16_f16 v[50:65], v[70:73], v[66:69], v[50:65]
	v_cvt_pk_f16_f32 v73, v202, v203
	v_cvt_pk_f16_f32 v72, v200, v201
	v_cvt_pk_f16_f32 v71, v198, v199
	v_cvt_pk_f16_f32 v70, v196, v197
	v_max_f32_e32 v196, v115, v115
	v_max_f32_e32 v197, v114, v114
	v_max_f32_e32 v196, v197, v196
	v_mfma_f32_32x32x16_f16 v[50:65], v[74:77], v[70:73], v[50:65]
	v_cvt_pk_f16_f32 v77, v92, v93
	v_cvt_pk_f16_f32 v76, v90, v91
	v_cvt_pk_f16_f32 v75, v88, v89
	v_cvt_pk_f16_f32 v74, v86, v87
	v_max3_f32 v196, v196, v116, v117
	v_max3_f32 v196, v196, v118, v119
	v_max3_f32 v196, v196, v120, v121
	v_mfma_f32_32x32x16_f16 v[50:65], v[78:81], v[74:77], v[50:65]
	ds_read_b64_tr_b16 v[78:79], v204 offset:0x200
	ds_read_b64_tr_b16 v[80:81], v205 offset:0xa00
	ds_read_b64_tr_b16 v[86:87], v204 offset:0x1200
	ds_read_b64_tr_b16 v[88:89], v205 offset:0x1a00
	ds_read_b64_tr_b16 v[90:91], v204 offset:0x2200
	ds_read_b64_tr_b16 v[92:93], v205 offset:0x2a00
	ds_read_b64_tr_b16 v[94:95], v204 offset:0x3200
	ds_read_b64_tr_b16 v[96:97], v205 offset:0x3a00
	s_waitcnt lgkmcnt(0)
	s_nop 0
	v_mfma_f32_32x32x16_f16 v[34:49], v[78:81], v[82:85], v[34:49]
	ds_read_b64_tr_b16 v[78:79], v204 offset:0x400
	ds_read_b64_tr_b16 v[80:81], v205 offset:0xc00
	v_max3_f32 v196, v196, v122, v123
	v_max3_f32 v196, v196, v124, v125
	v_max3_f32 v196, v196, v126, v127
	v_max3_f32 v196, v196, v128, v129
	v_mfma_f32_32x32x16_f16 v[34:49], v[86:89], v[66:69], v[34:49]
	ds_read_b64_tr_b16 v[86:87], v204 offset:0x1400
	ds_read_b64_tr_b16 v[88:89], v205 offset:0x1c00
	v_mfma_f32_32x32x16_f16 v[34:49], v[90:93], v[70:73], v[34:49]
	ds_read_b64_tr_b16 v[90:91], v204 offset:0x2400
	ds_read_b64_tr_b16 v[92:93], v205 offset:0x2c00
	v_mfma_f32_32x32x16_f16 v[34:49], v[94:97], v[74:77], v[34:49]
	ds_read_b64_tr_b16 v[94:95], v204 offset:0x3400
	ds_read_b64_tr_b16 v[96:97], v205 offset:0x3c00
	s_waitcnt lgkmcnt(0)
	v_mfma_f32_32x32x16_f16 v[18:33], v[78:81], v[82:85], v[18:33]
	ds_read_b64_tr_b16 v[78:79], v204 offset:0x600
	ds_read_b64_tr_b16 v[80:81], v205 offset:0xe00
	v_max3_f32 v196, v196, v98, v99
	v_max3_f32 v196, v196, v100, v101
	v_max3_f32 v196, v196, v102, v103
	v_max3_f32 v196, v196, v104, v105
	v_mfma_f32_32x32x16_f16 v[18:33], v[86:89], v[66:69], v[18:33]
	ds_read_b64_tr_b16 v[86:87], v204 offset:0x1600
	ds_read_b64_tr_b16 v[88:89], v205 offset:0x1e00
	v_mfma_f32_32x32x16_f16 v[18:33], v[90:93], v[70:73], v[18:33]
	ds_read_b64_tr_b16 v[90:91], v204 offset:0x2600
	ds_read_b64_tr_b16 v[92:93], v205 offset:0x2e00
	v_mfma_f32_32x32x16_f16 v[18:33], v[94:97], v[74:77], v[18:33]
	ds_read_b64_tr_b16 v[94:95], v204 offset:0x3600
	ds_read_b64_tr_b16 v[96:97], v205 offset:0x3e00
	s_waitcnt lgkmcnt(0)
	v_mfma_f32_32x32x16_f16 v[2:17], v[78:81], v[82:85], v[2:17]
	v_max3_f32 v78, v196, v106, v107
	v_max3_f32 v78, v78, v108, v109
	s_add_i32 s0, s24, s16
	v_mfma_f32_32x32x16_f16 v[2:17], v[86:89], v[66:69], v[2:17]
	v_max3_f32 v66, v78, v110, v111
	v_max3_f32 v66, v66, v112, v113
	v_mov_b32_e32 v68, v66
	s_nop 1
	v_permlane32_swap_b32_e32 v66, v68
	v_bfe_u32 v67, v193, s0, 1
	v_max_f32_e32 v68, v68, v68
	v_mfma_f32_32x32x16_f16 v[2:17], v[90:93], v[70:73], v[2:17]
	v_max_f32_e32 v66, v66, v66
	v_max_f32_e32 v66, v66, v68
	v_cmp_eq_u32_e64 s[0:1], 0, v67
	s_nop 1
	v_cndmask_b32_e64 v66, v66, v232, s[0:1]
	v_sub_f32_e32 v67, v66, v194
	v_mfma_f32_32x32x16_f16 v[2:17], v[94:97], v[74:77], v[2:17]
	v_cmp_ge_f32_e32 vcc, s73, v67
	s_cmp_eq_u64 vcc, exec
	s_cbranch_scc1 .LBB0_614
	v_max_f32_e32 v66, v66, v66
	v_max_f32_e32 v67, v194, v194
	v_max_f32_e32 v67, v67, v66
	v_sub_f32_e32 v66, v194, v67
	v_exp_f32_e32 v66, v66
	v_mov_b32_e32 v194, v67
	v_mul_f32_e32 v195, v195, v66
	v_pk_mul_f32 v[64:65], v[64:65], v[66:67] op_sel_hi:[1,0]
	v_pk_mul_f32 v[62:63], v[62:63], v[66:67] op_sel_hi:[1,0]
	v_pk_mul_f32 v[60:61], v[60:61], v[66:67] op_sel_hi:[1,0]
	v_pk_mul_f32 v[58:59], v[58:59], v[66:67] op_sel_hi:[1,0]
	v_pk_mul_f32 v[56:57], v[56:57], v[66:67] op_sel_hi:[1,0]
	v_pk_mul_f32 v[54:55], v[54:55], v[66:67] op_sel_hi:[1,0]
	v_pk_mul_f32 v[52:53], v[52:53], v[66:67] op_sel_hi:[1,0]
	v_pk_mul_f32 v[50:51], v[50:51], v[66:67] op_sel_hi:[1,0]
	v_pk_mul_f32 v[48:49], v[48:49], v[66:67] op_sel_hi:[1,0]
	v_pk_mul_f32 v[46:47], v[46:47], v[66:67] op_sel_hi:[1,0]
	v_pk_mul_f32 v[44:45], v[44:45], v[66:67] op_sel_hi:[1,0]
	v_pk_mul_f32 v[42:43], v[42:43], v[66:67] op_sel_hi:[1,0]
	v_pk_mul_f32 v[40:41], v[40:41], v[66:67] op_sel_hi:[1,0]
	v_pk_mul_f32 v[38:39], v[38:39], v[66:67] op_sel_hi:[1,0]
	v_pk_mul_f32 v[36:37], v[36:37], v[66:67] op_sel_hi:[1,0]
	v_pk_mul_f32 v[34:35], v[34:35], v[66:67] op_sel_hi:[1,0]
	v_pk_mul_f32 v[32:33], v[32:33], v[66:67] op_sel_hi:[1,0]
	v_pk_mul_f32 v[30:31], v[30:31], v[66:67] op_sel_hi:[1,0]
	v_pk_mul_f32 v[28:29], v[28:29], v[66:67] op_sel_hi:[1,0]
	v_pk_mul_f32 v[26:27], v[26:27], v[66:67] op_sel_hi:[1,0]
	v_pk_mul_f32 v[24:25], v[24:25], v[66:67] op_sel_hi:[1,0]
	v_pk_mul_f32 v[22:23], v[22:23], v[66:67] op_sel_hi:[1,0]
	v_pk_mul_f32 v[20:21], v[20:21], v[66:67] op_sel_hi:[1,0]
	v_pk_mul_f32 v[18:19], v[18:19], v[66:67] op_sel_hi:[1,0]
	v_pk_mul_f32 v[16:17], v[16:17], v[66:67] op_sel_hi:[1,0]
	v_pk_mul_f32 v[14:15], v[14:15], v[66:67] op_sel_hi:[1,0]
	v_pk_mul_f32 v[12:13], v[12:13], v[66:67] op_sel_hi:[1,0]
	v_pk_mul_f32 v[10:11], v[10:11], v[66:67] op_sel_hi:[1,0]
	v_pk_mul_f32 v[8:9], v[8:9], v[66:67] op_sel_hi:[1,0]
	v_pk_mul_f32 v[6:7], v[6:7], v[66:67] op_sel_hi:[1,0]
	v_pk_mul_f32 v[4:5], v[4:5], v[66:67] op_sel_hi:[1,0]
	v_pk_mul_f32 v[2:3], v[2:3], v[66:67] op_sel_hi:[1,0]

; #define MFMA(a, b, c) __builtin_amdgcn_mfma_f32_32x32x16_f16((a), (b), (c), 0, 0, 0)
; #define QK_LD(dst, s0) do { dst[0] = *(const f16x8*)(Kst + kbe + 512 * ((s0) >> 1)); dst[1] = *(const f16x8*)(Kst + kbe + 512 * ((s0) >> 1) + 8192); \
;     dst[2] = *(const f16x8*)(Kst + kbo + 512 * ((s0) >> 1)); dst[3] = *(const f16x8*)(Kst + kbo + 512 * ((s0) >> 1) + 8192); } while (0)
; #define QK_LD(dst, s0) do { dst[0] = *(const f16x8*)(Kst + kbe + 512 * ((s0) >> 1)); dst[1] = *(const f16x8*)(Kst + kbe + 512 * ((s0) >> 1) + 8192); \
;     dst[2] = *(const f16x8*)(Kst + kbo + 512 * ((s0) >> 1)); dst[3] = *(const f16x8*)(Kst + kbo + 512 * ((s0) >> 1) + 8192); } while (0)
; DI void qk_exp(f32x16& n0, f32x16& n1, const char* Kst, const f16x8 (&qf)[8], unsigned kbe, unsigned kbo, f32x16& c0, f32x16& c1, float me, float& ps) {
;     ...
;   float s_ = 0.f;
;   QK_LD(ka, 0);
;   n0 = MFMA(ka[0], qf[0], zero); n1 = MFMA(ka[1], qf[0], zero); n0 = MFMA(ka[2], qf[1], n0); n1 = MFMA(ka[3], qf[1], n1);
.LBB0_625:
	s_add_i32 s24, s22, 4
	s_cmp_le_i32 s8, s24
	s_cselect_b64 s[4:5], -1, 0
	s_cmp_lt_i32 s8, s12
	s_waitcnt lgkmcnt(0)
	s_barrier
	s_cselect_b64 s[26:27], -1, 0
	s_xor_b32 s100, s9, 0x10000
	v_add_u32_e32 v205, s100, v190
	ds_read_b128 v[66:69], v205
	ds_read_b128 v[70:73], v205 offset:8192
	v_add_u32_e32 v216, s100, v189
	ds_read_b128 v[196:199], v216
	ds_read_b128 v[200:203], v216 offset:8192
	s_and_b64 s[4:5], s[4:5], s[26:27]
	s_andn2_b64 vcc, exec, s[4:5]
	s_cbranch_vccnz .LBB0_636
	s_sub_i32 s4, s21, s8
	s_lshl_b32 s25, s4, 6
	s_sub_i32 s4, s15, s8
	s_lshl_b32 s26, s4, 6
	s_lshl_b32 s27, s8, 14
	s_lshl_b32 s28, s8, 15
	s_and_b32 s23, s28, 0x18000
	s_cmp_gt_i32 s8, 1
	s_mov_b64 s[4:5], -1
	s_cbranch_scc0 .LBB0_633
	s_branch .LBB0_628

; #define LAS __attribute__((address_space(3)))
; DI void glds16(const char* g, LAS unsigned char* l) { __builtin_amdgcn_global_load_lds((const unsigned*)g, (LAS unsigned*)l, 16, 0, 0); }
; DI void dma_kv128(LAS unsigned char* stage, unsigned ldsw, const char* K, const char* V, unsigned voff, long ldb) {
;   glds16(K + (size_t)voff, stage + ldsw); glds16(K + 32 * ldb + (size_t)voff, stage + ldsw + 8192);
;   glds16(V + (size_t)voff, stage + 16384 + ldsw); glds16(V + 32 * ldb + (size_t)voff, stage + 16384 + ldsw + 8192);
; }
.LBB0_628:
	s_cmp_ge_i32 s8, s14
	s_cbranch_scc0 .LBB0_630
	s_mul_i32 s5, s25, 0x3000
	s_mul_hi_i32 s4, s25, 0x3000
	s_add_u32 s29, s61, s5
	s_addc_u32 s40, s3, s4
	s_add_u32 s4, s29, s17
	s_addc_u32 s5, s40, 0
	s_add_u32 s42, s29, s18
	s_addc_u32 s43, s40, 0
	v_lshl_add_u64 v[218:219], s[4:5], 0, v[206:207]
	s_add_i32 s4, s23, s60
	s_mov_b32 m0, s4
	s_nop 0
	global_load_lds_dwordx4 v[218:219], off
	v_lshl_add_u64 v[218:219], v[218:219], 0, s[86:87]
	s_add_i32 m0, s4, 0x2000
	s_nop 0
	global_load_lds_dwordx4 v[218:219], off
	v_lshl_add_u64 v[218:219], s[42:43], 0, v[206:207]
	s_add_i32 m0, s4, 0x4000
	s_mov_b64 s[4:5], 0
	global_load_lds_dwordx4 v[218:219], off
	v_lshl_add_u64 v[218:219], v[218:219], 0, s[86:87]
.LBB0_630:
	s_andn2_b64 vcc, exec, s[4:5]
	s_cbranch_vccnz .LBB0_632
	s_mul_i32 s5, s26, 0x3000
	s_mul_hi_i32 s4, s26, 0x3000
	s_add_u32 s29, s61, s5
	s_addc_u32 s40, s3, s4
	s_add_u32 s4, s29, s19
	s_addc_u32 s5, s40, 0
	s_add_u32 s42, s29, s20
	s_addc_u32 s43, s40, 0
	v_lshl_add_u64 v[218:219], s[4:5], 0, v[206:207]
	s_add_i32 s4, s23, s60
	s_mov_b32 m0, s4
	s_nop 0
	global_load_lds_dwordx4 v[218:219], off
	v_lshl_add_u64 v[218:219], v[218:219], 0, s[86:87]
	s_add_i32 m0, s4, 0x2000
	s_nop 0
	global_load_lds_dwordx4 v[218:219], off
	v_lshl_add_u64 v[218:219], s[42:43], 0, v[206:207]
	s_add_i32 m0, s4, 0x4000
	s_nop 0
	global_load_lds_dwordx4 v[218:219], off
	v_lshl_add_u64 v[218:219], v[218:219], 0, s[86:87]

; #define LAS __attribute__((address_space(3)))
; DI void glds16(const char* g, LAS unsigned char* l) { __builtin_amdgcn_global_load_lds((const unsigned*)g, (LAS unsigned*)l, 16, 0, 0); }
; DI void dma_kv128(LAS unsigned char* stage, unsigned ldsw, const char* K, const char* V, unsigned voff, long ldb) {
;   glds16(K + (size_t)voff, stage + ldsw); glds16(K + 32 * ldb + (size_t)voff, stage + ldsw + 8192);
;   glds16(V + (size_t)voff, stage + 16384 + ldsw); glds16(V + 32 * ldb + (size_t)voff, stage + 16384 + ldsw + 8192);
; }
.LBB0_633:
	s_andn2_b64 vcc, exec, s[4:5]
	s_cbranch_vccnz .LBB0_635
	s_ashr_i32 s29, s27, 31
	s_add_u32 s4, s64, s27
	s_addc_u32 s5, s65, s29
	s_add_u32 s42, s80, s27
	s_addc_u32 s43, s81, s29
	v_lshl_add_u64 v[218:219], s[4:5], 0, v[162:163]
	s_add_i32 s4, s23, s60
	s_mov_b32 m0, s4
	s_nop 0
	global_load_lds_dwordx4 v[218:219], off
	v_lshl_add_u64 v[218:219], v[218:219], 0, s[34:35]
	s_add_i32 m0, s4, 0x2000
	s_nop 0
	global_load_lds_dwordx4 v[218:219], off
	v_lshl_add_u64 v[218:219], s[42:43], 0, v[162:163]
	s_add_i32 m0, s4, 0x4000
	s_nop 0
	global_load_lds_dwordx4 v[218:219], off
	v_lshl_add_u64 v[218:219], v[218:219], 0, s[34:35]
.LBB0_635:
	s_add_i32 s4, s23, s60
	s_add_i32 m0, s4, 0x6000
	s_add_i32 s23, s8, 1
	global_load_lds_dwordx4 v[218:219], off
	s_cmp_lt_i32 s8, s24
	s_cselect_b64 s[4:5], -1, 0
	s_cmp_lt_i32 s23, s12
	s_cselect_b64 s[42:43], -1, 0
	s_and_b64 s[4:5], s[4:5], s[42:43]
	s_sub_i32 s25, s25, 64
	s_sub_i32 s26, s26, 64
	s_addk_i32 s27, 0x4000
	s_add_i32 s28, s28, 0x8000
	s_and_b64 vcc, exec, s[4:5]
	s_cbranch_vccnz .LBB0_627
	s_branch .LBB0_637

; #define MFMA(a, b, c) __builtin_amdgcn_mfma_f32_32x32x16_f16((a), (b), (c), 0, 0, 0)
; #define SBAR() __builtin_amdgcn_sched_barrier(0)
; #define QK_LD(dst, s0) do { dst[0] = *(const f16x8*)(Kst + kbe + 512 * ((s0) >> 1)); dst[1] = *(const f16x8*)(Kst + kbe + 512 * ((s0) >> 1) + 8192); \
;     dst[2] = *(const f16x8*)(Kst + kbo + 512 * ((s0) >> 1)); dst[3] = *(const f16x8*)(Kst + kbo + 512 * ((s0) >> 1) + 8192); } while (0)
; #define QK_LD(dst, s0) do { dst[0] = *(const f16x8*)(Kst + kbe + 512 * ((s0) >> 1)); dst[1] = *(const f16x8*)(Kst + kbe + 512 * ((s0) >> 1) + 8192); \
;     dst[2] = *(const f16x8*)(Kst + kbo + 512 * ((s0) >> 1)); dst[3] = *(const f16x8*)(Kst + kbo + 512 * ((s0) >> 1) + 8192); } while (0)
; #define EXP8(c, b0) do { _Pragma("unroll") for (int j_ = 0; j_ < 8; ++j_) { c[(b0) + j_] = fexp2(c[(b0) + j_] - me); s_ += c[(b0) + j_]; } } while (0)
; DI void qk_exp(f32x16& n0, f32x16& n1, const char* Kst, const f16x8 (&qf)[8], unsigned kbe, unsigned kbo, f32x16& c0, f32x16& c1, float me, float& ps) {
;   const f32x16 zero = {0.f, 0.f, 0.f, 0.f, 0.f, 0.f, 0.f, 0.f, 0.f, 0.f, 0.f, 0.f, 0.f, 0.f, 0.f, 0.f};
;   f16x8 ka[4], kb[4];
;     ...
;   float s_ = 0.f;
;   QK_LD(ka, 0);
;   n0 = MFMA(ka[0], qf[0], zero); n1 = MFMA(ka[1], qf[0], zero); n0 = MFMA(ka[2], qf[1], n0); n1 = MFMA(ka[3], qf[1], n1);
;   QK_LD(kb, 2);
;   EXP8(c0, 0);
;   n0 = MFMA(kb[0], qf[2], n0); n1 = MFMA(kb[1], qf[2], n1); n0 = MFMA(kb[2], qf[3], n0); n1 = MFMA(kb[3], qf[3], n1);
;   QK_LD(ka, 4);
;   EXP8(c0, 8);
;   n0 = MFMA(ka[0], qf[4], n0); n1 = MFMA(ka[1], qf[4], n1); n0 = MFMA(ka[2], qf[5], n0); n1 = MFMA(ka[3], qf[5], n1);
;   QK_LD(kb, 6);
;   EXP8(c1, 0);
;   n0 = MFMA(kb[0], qf[6], n0); n1 = MFMA(kb[1], qf[6], n1); n0 = MFMA(kb[2], qf[7], n0); n1 = MFMA(kb[3], qf[7], n1);
;   EXP8(c1, 8);
;   ps = s_;
;     ...
; }
; DI void pv_max(f32x16 (&o)[4], unsigned vb0, unsigned vb1, const f32x16& p0, const f32x16& p1, const f32x16& n0, const f32x16& n1, float& pm) {
;   f16x8 pb[4]; pb[0] = pack8(p0, 0); pb[1] = pack8(p0, 1); pb[2] = pack8(p1, 0); pb[3] = pack8(p1, 1);
;   VFrag fa;
;   float mx = n0[0];
;   pv_rd<0>(fa, vb0, vb1);
;   asm volatile("s_waitcnt lgkmcnt(0)" ::: "memory"); SBAR();
;   pv_mm(o[0], fa, pb);
;   pv_rd<1>(fa, vb0, vb1);
.LBB0_637:
	v_cndmask_b32_e64 v204, v194, v233, s[0:1]
	s_waitcnt lgkmcnt(0)
	v_mfma_f32_32x32x16_f16 v[82:97], v[66:69], v[150:153], 0
	v_sub_f32_e32 v114, v114, v204
	v_exp_f32_e32 v217, v114
	v_sub_f32_e32 v115, v115, v204
	v_exp_f32_e32 v218, v115
	v_sub_f32_e32 v115, v116, v204
	v_exp_f32_e32 v219, v115
	v_sub_f32_e32 v115, v117, v204
	v_mfma_f32_32x32x16_f16 v[66:81], v[70:73], v[150:153], 0
	v_exp_f32_e32 v220, v115
	v_sub_f32_e32 v115, v118, v204
	v_add_f32_e32 v114, 0, v217
	v_exp_f32_e32 v221, v115
	v_sub_f32_e32 v115, v119, v204
	v_add_f32_e32 v114, v218, v114
	v_exp_f32_e32 v224, v115
	v_mfma_f32_32x32x16_f16 v[82:97], v[196:199], v[158:161], v[82:97]
	v_sub_f32_e32 v115, v120, v204
	v_add_f32_e32 v114, v219, v114
	v_exp_f32_e32 v225, v115
	v_sub_f32_e32 v115, v121, v204
	v_add_f32_e32 v114, v220, v114
	v_exp_f32_e32 v226, v115
	v_add_f32_e32 v114, v221, v114
	v_mfma_f32_32x32x16_f16 v[66:81], v[200:203], v[158:161], v[66:81]
	ds_read_b128 v[196:199], v205 offset:512
	ds_read_b128 v[200:203], v205 offset:8704
	ds_read_b128 v[208:211], v216 offset:512
	ds_read_b128 v[212:215], v216 offset:8704
	v_add_f32_e32 v114, v224, v114
	v_add_f32_e32 v114, v225, v114
	v_add_f32_e32 v227, v226, v114
	v_sub_f32_e32 v122, v122, v204
	v_sub_f32_e32 v123, v123, v204
	v_sub_f32_e32 v98, v98, v204
	s_waitcnt lgkmcnt(0)
	v_mfma_f32_32x32x16_f16 v[82:97], v[196:199], v[142:145], v[82:97]
	v_sub_f32_e32 v99, v99, v204
	v_mfma_f32_32x32x16_f16 v[66:81], v[200:203], v[142:145], v[66:81]
	ds_read_b128 v[114:117], v205 offset:1024
	ds_read_b128 v[118:121], v205 offset:9216
	ds_read_b128 v[196:199], v216 offset:1024
	ds_read_b128 v[200:203], v216 offset:9216
	v_mfma_f32_32x32x16_f16 v[82:97], v[208:211], v[154:157], v[82:97]
	v_exp_f32_e32 v208, v122
	v_exp_f32_e32 v209, v123
	v_sub_f32_e32 v123, v124, v204
	v_exp_f32_e32 v210, v123
	v_sub_f32_e32 v123, v125, v204
	v_exp_f32_e32 v211, v123
	v_sub_f32_e32 v123, v126, v204
	v_mfma_f32_32x32x16_f16 v[66:81], v[212:215], v[154:157], v[66:81]
	v_add_f32_e32 v122, v208, v227
	v_exp_f32_e32 v212, v123
	v_sub_f32_e32 v123, v127, v204
	v_add_f32_e32 v122, v209, v122
	v_exp_f32_e32 v213, v123
	v_sub_f32_e32 v123, v128, v204
	v_add_f32_e32 v122, v210, v122
	s_waitcnt lgkmcnt(0)
	v_mfma_f32_32x32x16_f16 v[82:97], v[114:117], v[138:141], v[82:97]
	v_exp_f32_e32 v214, v123
	v_sub_f32_e32 v123, v129, v204
	v_add_f32_e32 v122, v211, v122
	v_exp_f32_e32 v215, v123
	v_add_f32_e32 v122, v212, v122
	v_add_f32_e32 v122, v213, v122
	v_add_f32_e32 v122, v214, v122
	v_mfma_f32_32x32x16_f16 v[66:81], v[118:121], v[138:141], v[66:81]
	v_add_f32_e32 v227, v215, v122
	ds_read_b128 v[114:117], v205 offset:1536
	ds_read_b128 v[118:121], v205 offset:9728
	ds_read_b128 v[122:125], v216 offset:1536
	ds_read_b128 v[126:129], v216 offset:9728
	v_add_u32_e32 v205, s7, v192
	v_mfma_f32_32x32x16_f16 v[82:97], v[196:199], v[146:149], v[82:97]
	v_exp_f32_e32 v196, v98
	v_exp_f32_e32 v197, v99
	v_sub_f32_e32 v99, v100, v204
	v_exp_f32_e32 v198, v99
	v_sub_f32_e32 v99, v101, v204
	v_exp_f32_e32 v199, v99
	v_sub_f32_e32 v99, v102, v204
	v_mfma_f32_32x32x16_f16 v[66:81], v[200:203], v[146:149], v[66:81]
	v_add_f32_e32 v98, v196, v227
	v_exp_f32_e32 v200, v99
	v_sub_f32_e32 v99, v103, v204
	v_add_f32_e32 v98, v197, v98
	v_exp_f32_e32 v201, v99
	v_sub_f32_e32 v99, v104, v204
	v_add_f32_e32 v98, v198, v98
	s_waitcnt lgkmcnt(0)
	v_mfma_f32_32x32x16_f16 v[82:97], v[114:117], v[130:133], v[82:97]
	v_exp_f32_e32 v202, v99
	v_sub_f32_e32 v99, v105, v204
	v_add_f32_e32 v98, v199, v98
	v_exp_f32_e32 v203, v99
	v_sub_f32_e32 v99, v106, v204
	v_add_f32_e32 v98, v200, v98
	v_add_f32_e32 v98, v201, v98
	v_mfma_f32_32x32x16_f16 v[66:81], v[118:121], v[130:133], v[66:81]
	v_exp_f32_e32 v118, v99
	v_sub_f32_e32 v99, v107, v204
	v_exp_f32_e32 v119, v99
	v_sub_f32_e32 v99, v108, v204
	v_add_f32_e32 v98, v202, v98
	v_exp_f32_e32 v120, v99
	v_sub_f32_e32 v99, v109, v204
	v_add_f32_e32 v98, v203, v98
	v_exp_f32_e32 v121, v99
	v_sub_f32_e32 v99, v110, v204
	v_mfma_f32_32x32x16_f16 v[82:97], v[122:125], v[134:137], v[82:97]
	v_add_f32_e32 v98, v118, v98
	v_exp_f32_e32 v122, v99
	v_sub_f32_e32 v99, v111, v204
	v_add_f32_e32 v98, v119, v98
	v_exp_f32_e32 v123, v99
	v_sub_f32_e32 v99, v112, v204
	v_add_f32_e32 v98, v120, v98
	v_exp_f32_e32 v124, v99
	v_sub_f32_e32 v99, v113, v204
	v_add_f32_e32 v98, v121, v98
	v_exp_f32_e32 v125, v99
	v_add_f32_e32 v98, v122, v98
	v_add_f32_e32 v98, v123, v98
	v_add_f32_e32 v98, v124, v98
	v_add_f32_e32 v98, v125, v98
	v_add_f32_e32 v195, v195, v98
	v_add_u32_e32 v204, s7, v1
	ds_read_b64_tr_b16 v[98:99], v204 offset:0
	ds_read_b64_tr_b16 v[100:101], v205 offset:0x800
	ds_read_b64_tr_b16 v[102:103], v204 offset:0x1000
	v_mfma_f32_32x32x16_f16 v[66:81], v[126:129], v[134:137], v[66:81]
	ds_read_b64_tr_b16 v[104:105], v205 offset:0x1800
	ds_read_b64_tr_b16 v[106:107], v204 offset:0x2000
	ds_read_b64_tr_b16 v[108:109], v205 offset:0x2800
	ds_read_b64_tr_b16 v[110:111], v204 offset:0x3000
	ds_read_b64_tr_b16 v[112:113], v205 offset:0x3800
	s_waitcnt lgkmcnt(0)
; #define SBAR() __builtin_amdgcn_sched_barrier(0)
; DI void pv_max(f32x16 (&o)[4], unsigned vb0, unsigned vb1, const f32x16& p0, const f32x16& p1, const f32x16& n0, const f32x16& n1, float& pm) {
;   f16x8 pb[4]; pb[0] = pack8(p0, 0); pb[1] = pack8(p0, 1); pb[2] = pack8(p1, 0); pb[3] = pack8(p1, 1);
;   VFrag fa;
;   float mx = n0[0];
;   pv_rd<0>(fa, vb0, vb1);
;   asm volatile("s_waitcnt lgkmcnt(0)" ::: "memory"); SBAR();
;   pv_mm(o[0], fa, pb);
;   pv_rd<1>(fa, vb0, vb1);
; #pragma unroll
;   for (int r = 1; r < 8; ++r) mx = fmaxf(mx, n0[r]);
;   asm volatile("s_waitcnt lgkmcnt(0)" ::: "memory"); SBAR();
;   pv_mm(o[1], fa, pb);
;   pv_rd<2>(fa, vb0, vb1);
; #pragma unroll
;   for (int r = 8; r < 16; ++r) mx = fmaxf(mx, n0[r]);
;   asm volatile("s_waitcnt lgkmcnt(0)" ::: "memory"); SBAR();
;   pv_mm(o[2], fa, pb);
;   pv_rd<3>(fa, vb0, vb1);
; #pragma unroll
;   for (int r = 0; r < 8; ++r) mx = fmaxf(mx, n1[r]);
;   asm volatile("s_waitcnt lgkmcnt(0)" ::: "memory"); SBAR();
;   pv_mm(o[3], fa, pb);
; #pragma unroll
;   for (int r = 8; r < 16; ++r) mx = fmaxf(mx, n1[r]);
;   pm = mx;
; }
	v_cvt_pk_f16_f32 v117, v225, v226
	v_cvt_pk_f16_f32 v116, v221, v224
	v_cvt_pk_f16_f32 v115, v219, v220
	v_cvt_pk_f16_f32 v114, v217, v218
	s_nop 1
	v_mfma_f32_32x32x16_f16 v[50:65], v[98:101], v[114:117], v[50:65]
	v_cvt_pk_f16_f32 v101, v214, v215
	v_cvt_pk_f16_f32 v100, v212, v213
	v_cvt_pk_f16_f32 v99, v210, v211
	v_cvt_pk_f16_f32 v98, v208, v209
	s_nop 1
	v_mfma_f32_32x32x16_f16 v[50:65], v[102:105], v[98:101], v[50:65]
	v_cvt_pk_f16_f32 v105, v202, v203
	v_cvt_pk_f16_f32 v104, v200, v201
	v_cvt_pk_f16_f32 v103, v198, v199
	v_cvt_pk_f16_f32 v102, v196, v197
	v_max_f32_e32 v196, v83, v83
	v_max_f32_e32 v197, v82, v82
	v_max_f32_e32 v196, v197, v196
	v_mfma_f32_32x32x16_f16 v[50:65], v[106:109], v[102:105], v[50:65]
	v_cvt_pk_f16_f32 v109, v124, v125
	v_cvt_pk_f16_f32 v108, v122, v123
	v_cvt_pk_f16_f32 v107, v120, v121
	v_cvt_pk_f16_f32 v106, v118, v119
	v_max3_f32 v196, v196, v84, v85
	v_max3_f32 v196, v196, v86, v87
	v_max3_f32 v196, v196, v88, v89
	v_mfma_f32_32x32x16_f16 v[50:65], v[110:113], v[106:109], v[50:65]
	ds_read_b64_tr_b16 v[110:111], v204 offset:0x200
	ds_read_b64_tr_b16 v[112:113], v205 offset:0xa00
	ds_read_b64_tr_b16 v[118:119], v204 offset:0x1200
	ds_read_b64_tr_b16 v[120:121], v205 offset:0x1a00
	ds_read_b64_tr_b16 v[122:123], v204 offset:0x2200
	ds_read_b64_tr_b16 v[124:125], v205 offset:0x2a00
	ds_read_b64_tr_b16 v[126:127], v204 offset:0x3200
	ds_read_b64_tr_b16 v[128:129], v205 offset:0x3a00
	s_waitcnt lgkmcnt(0)
	s_nop 0
	v_mfma_f32_32x32x16_f16 v[34:49], v[110:113], v[114:117], v[34:49]
	ds_read_b64_tr_b16 v[110:111], v204 offset:0x400
	ds_read_b64_tr_b16 v[112:113], v205 offset:0xc00
	v_max3_f32 v196, v196, v90, v91
	v_max3_f32 v196, v196, v92, v93
	v_max3_f32 v196, v196, v94, v95
	v_max3_f32 v196, v196, v96, v97
	v_mfma_f32_32x32x16_f16 v[34:49], v[118:121], v[98:101], v[34:49]
	ds_read_b64_tr_b16 v[118:119], v204 offset:0x1400
	ds_read_b64_tr_b16 v[120:121], v205 offset:0x1c00
	v_mfma_f32_32x32x16_f16 v[34:49], v[122:125], v[102:105], v[34:49]
	ds_read_b64_tr_b16 v[122:123], v204 offset:0x2400
	ds_read_b64_tr_b16 v[124:125], v205 offset:0x2c00
	v_mfma_f32_32x32x16_f16 v[34:49], v[126:129], v[106:109], v[34:49]
	ds_read_b64_tr_b16 v[126:127], v204 offset:0x3400
	ds_read_b64_tr_b16 v[128:129], v205 offset:0x3c00
	s_waitcnt lgkmcnt(0)
	v_mfma_f32_32x32x16_f16 v[18:33], v[110:113], v[114:117], v[18:33]
	ds_read_b64_tr_b16 v[110:111], v204 offset:0x600
	ds_read_b64_tr_b16 v[112:113], v205 offset:0xe00
	v_max3_f32 v196, v196, v66, v67
	v_max3_f32 v196, v196, v68, v69
	v_max3_f32 v196, v196, v70, v71
	v_max3_f32 v196, v196, v72, v73
	v_mfma_f32_32x32x16_f16 v[18:33], v[118:121], v[98:101], v[18:33]
	ds_read_b64_tr_b16 v[118:119], v204 offset:0x1600
	ds_read_b64_tr_b16 v[120:121], v205 offset:0x1e00
	v_mfma_f32_32x32x16_f16 v[18:33], v[122:125], v[102:105], v[18:33]
	ds_read_b64_tr_b16 v[122:123], v204 offset:0x2600
	ds_read_b64_tr_b16 v[124:125], v205 offset:0x2e00
	v_mfma_f32_32x32x16_f16 v[18:33], v[126:129], v[106:109], v[18:33]
	ds_read_b64_tr_b16 v[126:127], v204 offset:0x3600
	ds_read_b64_tr_b16 v[128:129], v205 offset:0x3e00
	s_waitcnt lgkmcnt(0)
	v_mfma_f32_32x32x16_f16 v[2:17], v[110:113], v[114:117], v[2:17]
	v_max3_f32 v110, v196, v74, v75
	v_max3_f32 v110, v110, v76, v77
	v_max3_f32 v110, v110, v78, v79
	s_sub_i32 s0, s62, s22
	v_mfma_f32_32x32x16_f16 v[2:17], v[118:121], v[98:101], v[2:17]
	v_max3_f32 v98, v110, v80, v81
	v_mov_b32_e32 v100, v98
	v_lshrrev_b32_e32 v99, s0, v193
	s_nop 0
	v_permlane32_swap_b32_e32 v98, v100
	v_and_b32_e32 v99, 1, v99
	v_max_f32_e32 v100, v100, v100
	v_mfma_f32_32x32x16_f16 v[2:17], v[122:125], v[102:105], v[2:17]
	v_max_f32_e32 v98, v98, v98
	v_max_f32_e32 v98, v98, v100
	v_cmp_eq_u32_e64 s[0:1], 1, v99
	s_nop 1
	v_cndmask_b32_e64 v98, v232, v98, s[0:1]
	v_sub_f32_e32 v99, v98, v194
	v_mfma_f32_32x32x16_f16 v[2:17], v[126:129], v[106:109], v[2:17]
	v_cmp_ge_f32_e32 vcc, s73, v99
	s_cmp_eq_u64 vcc, exec
	s_cbranch_scc1 .LBB0_639
	v_max_f32_e32 v98, v98, v98
	v_max_f32_e32 v99, v194, v194
	v_max_f32_e32 v99, v99, v98
	v_sub_f32_e32 v98, v194, v99
	v_exp_f32_e32 v98, v98
	v_mov_b32_e32 v194, v99
	v_mul_f32_e32 v195, v195, v98
	v_pk_mul_f32 v[64:65], v[64:65], v[98:99] op_sel_hi:[1,0]
	v_pk_mul_f32 v[62:63], v[62:63], v[98:99] op_sel_hi:[1,0]
	v_pk_mul_f32 v[60:61], v[60:61], v[98:99] op_sel_hi:[1,0]
	v_pk_mul_f32 v[58:59], v[58:59], v[98:99] op_sel_hi:[1,0]
	v_pk_mul_f32 v[56:57], v[56:57], v[98:99] op_sel_hi:[1,0]
	v_pk_mul_f32 v[54:55], v[54:55], v[98:99] op_sel_hi:[1,0]
	v_pk_mul_f32 v[52:53], v[52:53], v[98:99] op_sel_hi:[1,0]
	v_pk_mul_f32 v[50:51], v[50:51], v[98:99] op_sel_hi:[1,0]
	v_pk_mul_f32 v[48:49], v[48:49], v[98:99] op_sel_hi:[1,0]
	v_pk_mul_f32 v[46:47], v[46:47], v[98:99] op_sel_hi:[1,0]
	v_pk_mul_f32 v[44:45], v[44:45], v[98:99] op_sel_hi:[1,0]
	v_pk_mul_f32 v[42:43], v[42:43], v[98:99] op_sel_hi:[1,0]
	v_pk_mul_f32 v[40:41], v[40:41], v[98:99] op_sel_hi:[1,0]
	v_pk_mul_f32 v[38:39], v[38:39], v[98:99] op_sel_hi:[1,0]
	v_pk_mul_f32 v[36:37], v[36:37], v[98:99] op_sel_hi:[1,0]
	v_pk_mul_f32 v[34:35], v[34:35], v[98:99] op_sel_hi:[1,0]
	v_pk_mul_f32 v[32:33], v[32:33], v[98:99] op_sel_hi:[1,0]
	v_pk_mul_f32 v[30:31], v[30:31], v[98:99] op_sel_hi:[1,0]
	v_pk_mul_f32 v[28:29], v[28:29], v[98:99] op_sel_hi:[1,0]
	v_pk_mul_f32 v[26:27], v[26:27], v[98:99] op_sel_hi:[1,0]
	v_pk_mul_f32 v[24:25], v[24:25], v[98:99] op_sel_hi:[1,0]
	v_pk_mul_f32 v[22:23], v[22:23], v[98:99] op_sel_hi:[1,0]
	v_pk_mul_f32 v[20:21], v[20:21], v[98:99] op_sel_hi:[1,0]
	v_pk_mul_f32 v[18:19], v[18:19], v[98:99] op_sel_hi:[1,0]
	v_pk_mul_f32 v[16:17], v[16:17], v[98:99] op_sel_hi:[1,0]
	v_pk_mul_f32 v[14:15], v[14:15], v[98:99] op_sel_hi:[1,0]
	v_pk_mul_f32 v[12:13], v[12:13], v[98:99] op_sel_hi:[1,0]
	v_pk_mul_f32 v[10:11], v[10:11], v[98:99] op_sel_hi:[1,0]
	v_pk_mul_f32 v[8:9], v[8:9], v[98:99] op_sel_hi:[1,0]
	v_pk_mul_f32 v[6:7], v[6:7], v[98:99] op_sel_hi:[1,0]
	v_pk_mul_f32 v[4:5], v[4:5], v[98:99] op_sel_hi:[1,0]
	v_pk_mul_f32 v[2:3], v[2:3], v[98:99] op_sel_hi:[1,0]

; #define MFMA(a, b, c) __builtin_amdgcn_mfma_f32_32x32x16_f16((a), (b), (c), 0, 0, 0)
; #define QK_LD(dst, s0) do { dst[0] = *(const f16x8*)(Kst + kbe + 512 * ((s0) >> 1)); dst[1] = *(const f16x8*)(Kst + kbe + 512 * ((s0) >> 1) + 8192); \
;     dst[2] = *(const f16x8*)(Kst + kbo + 512 * ((s0) >> 1)); dst[3] = *(const f16x8*)(Kst + kbo + 512 * ((s0) >> 1) + 8192); } while (0)
; #define QK_LD(dst, s0) do { dst[0] = *(const f16x8*)(Kst + kbe + 512 * ((s0) >> 1)); dst[1] = *(const f16x8*)(Kst + kbe + 512 * ((s0) >> 1) + 8192); \
;     dst[2] = *(const f16x8*)(Kst + kbo + 512 * ((s0) >> 1)); dst[3] = *(const f16x8*)(Kst + kbo + 512 * ((s0) >> 1) + 8192); } while (0)
; DI void qk_exp(f32x16& n0, f32x16& n1, const char* Kst, const f16x8 (&qf)[8], unsigned kbe, unsigned kbo, f32x16& c0, f32x16& c1, float me, float& ps) {
;     ...
;   float s_ = 0.f;
;   QK_LD(ka, 0);
;   n0 = MFMA(ka[0], qf[0], zero); n1 = MFMA(ka[1], qf[0], zero); n0 = MFMA(ka[2], qf[1], n0); n1 = MFMA(ka[3], qf[1], n1);
.LBB0_706:
	s_add_i32 s17, s5, 3
	s_cmp_le_i32 s18, s17
	s_cselect_b64 s[0:1], -1, 0
	s_cmp_lt_i32 s18, s12
	s_waitcnt lgkmcnt(0)
	s_barrier
	s_cselect_b64 s[20:21], -1, 0
	s_lshl_b32 s100, s19, 15
	s_and_b32 s100, s100, 0x18000
	v_or_b32_e32 v212, s100, v190
	ds_read_b128 v[98:101], v212
	ds_read_b128 v[102:105], v212 offset:8192
	v_or_b32_e32 v213, s100, v189
	ds_read_b128 v[194:197], v213
	ds_read_b128 v[198:201], v213 offset:8192
	s_and_b64 s[0:1], s[0:1], s[20:21]
	s_andn2_b64 vcc, exec, s[0:1]
	s_cbranch_vccnz .LBB0_717
	s_sub_i32 s0, s16, s18
	s_lshl_b32 s21, s0, 6
	s_sub_i32 s0, s15, s18
	s_lshl_b32 s22, s0, 6
	s_lshl_b32 s23, s18, 14
	s_lshl_b32 s24, s18, 15
	s_and_b32 s20, s24, 0x18000
	s_cmp_gt_i32 s18, 1
	s_mov_b64 s[0:1], -1
	s_cbranch_scc0 .LBB0_714
	s_branch .LBB0_709

; #define LAS __attribute__((address_space(3)))
; DI void glds16(const char* g, LAS unsigned char* l) { __builtin_amdgcn_global_load_lds((const unsigned*)g, (LAS unsigned*)l, 16, 0, 0); }
; DI void dma_kv128(LAS unsigned char* stage, unsigned ldsw, const char* K, const char* V, unsigned voff, long ldb) {
;   glds16(K + (size_t)voff, stage + ldsw); glds16(K + 32 * ldb + (size_t)voff, stage + ldsw + 8192);
;   glds16(V + (size_t)voff, stage + 16384 + ldsw); glds16(V + 32 * ldb + (size_t)voff, stage + 16384 + ldsw + 8192);
; }
.LBB0_709:
	s_cmp_ge_i32 s18, s14
	s_cbranch_scc0 .LBB0_711
	s_mul_i32 s1, s21, 0x3000
	s_mul_hi_i32 s0, s21, 0x3000
	s_add_u32 s25, s61, s1
	s_addc_u32 s27, s3, s0
	s_add_u32 s0, s25, s6
	s_addc_u32 s1, s27, 0
	s_add_u32 s26, s25, s7
	s_addc_u32 s27, s27, 0
	v_lshl_add_u64 v[218:219], s[0:1], 0, v[206:207]
	s_add_i32 s0, s20, s60
	s_mov_b32 m0, s0
	s_nop 0
	global_load_lds_dwordx4 v[218:219], off
	v_lshl_add_u64 v[218:219], v[218:219], 0, s[86:87]
	s_add_i32 m0, s0, 0x2000
	s_nop 0
	global_load_lds_dwordx4 v[218:219], off
	v_lshl_add_u64 v[218:219], s[26:27], 0, v[206:207]
	s_add_i32 m0, s0, 0x4000
	s_mov_b64 s[0:1], 0
	global_load_lds_dwordx4 v[218:219], off
	v_lshl_add_u64 v[218:219], v[218:219], 0, s[86:87]
.LBB0_711:
	s_andn2_b64 vcc, exec, s[0:1]
	s_cbranch_vccnz .LBB0_713
	s_mul_i32 s1, s22, 0x3000
	s_mul_hi_i32 s0, s22, 0x3000
	s_add_u32 s25, s61, s1
	s_addc_u32 s27, s3, s0
	s_add_u32 s0, s25, s8
	s_addc_u32 s1, s27, 0
	s_add_u32 s26, s25, s9
	s_addc_u32 s27, s27, 0
	v_lshl_add_u64 v[218:219], s[0:1], 0, v[206:207]
	s_add_i32 s0, s20, s60
	s_mov_b32 m0, s0
	s_nop 0
	global_load_lds_dwordx4 v[218:219], off
	v_lshl_add_u64 v[218:219], v[218:219], 0, s[86:87]
	s_add_i32 m0, s0, 0x2000
	s_nop 0
	global_load_lds_dwordx4 v[218:219], off
	v_lshl_add_u64 v[218:219], s[26:27], 0, v[206:207]
	s_add_i32 m0, s0, 0x4000
	s_nop 0
	global_load_lds_dwordx4 v[218:219], off
	v_lshl_add_u64 v[218:219], v[218:219], 0, s[86:87]

; #define LAS __attribute__((address_space(3)))
; DI void glds16(const char* g, LAS unsigned char* l) { __builtin_amdgcn_global_load_lds((const unsigned*)g, (LAS unsigned*)l, 16, 0, 0); }
; DI void dma_kv128(LAS unsigned char* stage, unsigned ldsw, const char* K, const char* V, unsigned voff, long ldb) {
;   glds16(K + (size_t)voff, stage + ldsw); glds16(K + 32 * ldb + (size_t)voff, stage + ldsw + 8192);
;   glds16(V + (size_t)voff, stage + 16384 + ldsw); glds16(V + 32 * ldb + (size_t)voff, stage + 16384 + ldsw + 8192);
; }
.LBB0_714:
	s_andn2_b64 vcc, exec, s[0:1]
	s_cbranch_vccnz .LBB0_716
	s_ashr_i32 s25, s23, 31
	s_add_u32 s0, s64, s23
	s_addc_u32 s1, s65, s25
	s_add_u32 s26, s80, s23
	s_addc_u32 s27, s81, s25
	v_lshl_add_u64 v[218:219], s[0:1], 0, v[162:163]
	s_add_i32 s0, s20, s60
	s_mov_b32 m0, s0
	s_nop 0
	global_load_lds_dwordx4 v[218:219], off
	v_lshl_add_u64 v[218:219], v[218:219], 0, s[34:35]
	s_add_i32 m0, s0, 0x2000
	s_nop 0
	global_load_lds_dwordx4 v[218:219], off
	v_lshl_add_u64 v[218:219], s[26:27], 0, v[162:163]
	s_add_i32 m0, s0, 0x4000
	s_nop 0
	global_load_lds_dwordx4 v[218:219], off
	v_lshl_add_u64 v[218:219], v[218:219], 0, s[34:35]
.LBB0_716:
	s_add_i32 s0, s20, s60
	s_add_i32 m0, s0, 0x6000
	s_add_i32 s20, s18, 1
	global_load_lds_dwordx4 v[218:219], off
	s_cmp_lt_i32 s18, s17
	s_cselect_b64 s[0:1], -1, 0
	s_cmp_lt_i32 s20, s12
	s_cselect_b64 s[26:27], -1, 0
	s_and_b64 s[0:1], s[0:1], s[26:27]
	s_sub_i32 s21, s21, 64
	s_sub_i32 s22, s22, 64
	s_addk_i32 s23, 0x4000
	s_add_i32 s24, s24, 0x8000
	s_and_b64 vcc, exec, s[0:1]
	s_cbranch_vccnz .LBB0_708
	s_branch .LBB0_718

; #define MFMA(a, b, c) __builtin_amdgcn_mfma_f32_32x32x16_f16((a), (b), (c), 0, 0, 0)
; #define SBAR() __builtin_amdgcn_sched_barrier(0)
; #define QK_LD(dst, s0) do { dst[0] = *(const f16x8*)(Kst + kbe + 512 * ((s0) >> 1)); dst[1] = *(const f16x8*)(Kst + kbe + 512 * ((s0) >> 1) + 8192); \
;     dst[2] = *(const f16x8*)(Kst + kbo + 512 * ((s0) >> 1)); dst[3] = *(const f16x8*)(Kst + kbo + 512 * ((s0) >> 1) + 8192); } while (0)
; #define QK_LD(dst, s0) do { dst[0] = *(const f16x8*)(Kst + kbe + 512 * ((s0) >> 1)); dst[1] = *(const f16x8*)(Kst + kbe + 512 * ((s0) >> 1) + 8192); \
;     dst[2] = *(const f16x8*)(Kst + kbo + 512 * ((s0) >> 1)); dst[3] = *(const f16x8*)(Kst + kbo + 512 * ((s0) >> 1) + 8192); } while (0)
; #define EXP8(c, b0) do { _Pragma("unroll") for (int j_ = 0; j_ < 8; ++j_) { c[(b0) + j_] = fexp2(c[(b0) + j_] - me); s_ += c[(b0) + j_]; } } while (0)
; DI void qk_exp(f32x16& n0, f32x16& n1, const char* Kst, const f16x8 (&qf)[8], unsigned kbe, unsigned kbo, f32x16& c0, f32x16& c1, float me, float& ps) {
;   const f32x16 zero = {0.f, 0.f, 0.f, 0.f, 0.f, 0.f, 0.f, 0.f, 0.f, 0.f, 0.f, 0.f, 0.f, 0.f, 0.f, 0.f};
;   f16x8 ka[4], kb[4];
;     ...
;   float s_ = 0.f;
;   QK_LD(ka, 0);
;   n0 = MFMA(ka[0], qf[0], zero); n1 = MFMA(ka[1], qf[0], zero); n0 = MFMA(ka[2], qf[1], n0); n1 = MFMA(ka[3], qf[1], n1);
;   QK_LD(kb, 2);
;   EXP8(c0, 0);
;   n0 = MFMA(kb[0], qf[2], n0); n1 = MFMA(kb[1], qf[2], n1); n0 = MFMA(kb[2], qf[3], n0); n1 = MFMA(kb[3], qf[3], n1);
;   QK_LD(ka, 4);
;   EXP8(c0, 8);
;   n0 = MFMA(ka[0], qf[4], n0); n1 = MFMA(ka[1], qf[4], n1); n0 = MFMA(ka[2], qf[5], n0); n1 = MFMA(ka[3], qf[5], n1);
;   QK_LD(kb, 6);
;   EXP8(c1, 0);
;   n0 = MFMA(kb[0], qf[6], n0); n1 = MFMA(kb[1], qf[6], n1); n0 = MFMA(kb[2], qf[7], n0); n1 = MFMA(kb[3], qf[7], n1);
;   EXP8(c1, 8);
;   ps = s_;
;     ...
; }
; DI void pv_max(f32x16 (&o)[4], unsigned vb0, unsigned vb1, const f32x16& p0, const f32x16& p1, const f32x16& n0, const f32x16& n1, float& pm) {
;   f16x8 pb[4]; pb[0] = pack8(p0, 0); pb[1] = pack8(p0, 1); pb[2] = pack8(p1, 0); pb[3] = pack8(p1, 1);
;   VFrag fa;
;   float mx = n0[0];
;   pv_rd<0>(fa, vb0, vb1);
;   asm volatile("s_waitcnt lgkmcnt(0)" ::: "memory"); SBAR();
;   pv_mm(o[0], fa, pb);
;   pv_rd<1>(fa, vb0, vb1);
.LBB0_718:
	s_lshl_b32 s0, s19, 15
	s_and_b32 s19, s0, 0x18000
	v_sub_f32_e32 v66, v66, v191
	s_waitcnt lgkmcnt(0)
	v_mfma_f32_32x32x16_f16 v[114:129], v[98:101], v[150:153], 0
	v_exp_f32_e32 v214, v66
	v_sub_f32_e32 v67, v67, v191
	v_exp_f32_e32 v215, v67
	v_sub_f32_e32 v67, v68, v191
	v_exp_f32_e32 v216, v67
	v_sub_f32_e32 v67, v69, v191
	v_exp_f32_e32 v217, v67
	v_mfma_f32_32x32x16_f16 v[98:113], v[102:105], v[150:153], 0
	v_sub_f32_e32 v67, v70, v191
	v_add_f32_e32 v66, 0, v214
	v_exp_f32_e32 v218, v67
	v_sub_f32_e32 v67, v71, v191
	v_add_f32_e32 v66, v215, v66
	v_exp_f32_e32 v219, v67
	v_sub_f32_e32 v67, v72, v191
	v_mfma_f32_32x32x16_f16 v[114:129], v[194:197], v[158:161], v[114:129]
	v_add_f32_e32 v66, v216, v66
	v_exp_f32_e32 v220, v67
	v_sub_f32_e32 v67, v73, v191
	v_add_f32_e32 v66, v217, v66
	v_exp_f32_e32 v221, v67
	v_add_f32_e32 v66, v218, v66
	v_add_f32_e32 v66, v219, v66
	v_mfma_f32_32x32x16_f16 v[98:113], v[198:201], v[158:161], v[98:113]
	ds_read_b128 v[194:197], v212 offset:512
	ds_read_b128 v[198:201], v212 offset:8704
	ds_read_b128 v[202:205], v213 offset:512
	ds_read_b128 v[208:211], v213 offset:8704
	v_add_f32_e32 v66, v220, v66
	v_add_f32_e32 v224, v221, v66
	v_sub_f32_e32 v74, v74, v191
	v_sub_f32_e32 v75, v75, v191
	v_sub_f32_e32 v82, v82, v191
	v_sub_f32_e32 v83, v83, v191
	s_waitcnt lgkmcnt(0)
	v_mfma_f32_32x32x16_f16 v[114:129], v[194:197], v[142:145], v[114:129]
	s_lshl_b32 s0, s5, 15
	s_and_b32 s21, s0, 0x18000
	v_mfma_f32_32x32x16_f16 v[98:113], v[198:201], v[142:145], v[98:113]
	ds_read_b128 v[66:69], v212 offset:1024
	ds_read_b128 v[70:73], v212 offset:9216
	ds_read_b128 v[194:197], v213 offset:1024
	ds_read_b128 v[198:201], v213 offset:9216
	v_mfma_f32_32x32x16_f16 v[114:129], v[202:205], v[154:157], v[114:129]
	v_exp_f32_e32 v202, v74
	v_exp_f32_e32 v203, v75
	v_sub_f32_e32 v75, v76, v191
	v_exp_f32_e32 v204, v75
	v_sub_f32_e32 v75, v77, v191
	v_exp_f32_e32 v205, v75
	v_sub_f32_e32 v75, v78, v191
	v_mfma_f32_32x32x16_f16 v[98:113], v[208:211], v[154:157], v[98:113]
	v_add_f32_e32 v74, v202, v224
	v_exp_f32_e32 v208, v75
	v_sub_f32_e32 v75, v79, v191
	v_add_f32_e32 v74, v203, v74
	v_exp_f32_e32 v209, v75
	v_sub_f32_e32 v75, v80, v191
	v_add_f32_e32 v74, v204, v74
	s_waitcnt lgkmcnt(0)
	v_mfma_f32_32x32x16_f16 v[114:129], v[66:69], v[138:141], v[114:129]
	v_exp_f32_e32 v210, v75
	v_sub_f32_e32 v75, v81, v191
	v_add_f32_e32 v74, v205, v74
	v_exp_f32_e32 v211, v75
	v_add_f32_e32 v74, v208, v74
	v_add_f32_e32 v74, v209, v74
	v_add_f32_e32 v74, v210, v74
	v_mfma_f32_32x32x16_f16 v[98:113], v[70:73], v[138:141], v[98:113]
	v_add_f32_e32 v224, v211, v74
	ds_read_b128 v[66:69], v212 offset:1536
	ds_read_b128 v[70:73], v212 offset:9728
	ds_read_b128 v[74:77], v213 offset:1536
	ds_read_b128 v[78:81], v213 offset:9728
	v_mfma_f32_32x32x16_f16 v[114:129], v[194:197], v[146:149], v[114:129]
	v_exp_f32_e32 v194, v82
	v_exp_f32_e32 v195, v83
	v_sub_f32_e32 v83, v84, v191
	v_exp_f32_e32 v196, v83
	v_sub_f32_e32 v83, v85, v191
	v_exp_f32_e32 v197, v83
	v_sub_f32_e32 v83, v86, v191
	v_add_f32_e32 v82, v194, v224
	v_exp_f32_e32 v86, v83
	v_sub_f32_e32 v83, v87, v191
	v_add_f32_e32 v82, v195, v82
	v_exp_f32_e32 v87, v83
	v_sub_f32_e32 v83, v88, v191
	v_add_f32_e32 v82, v196, v82
	v_exp_f32_e32 v88, v83
	v_sub_f32_e32 v83, v89, v191
	v_mfma_f32_32x32x16_f16 v[98:113], v[198:201], v[146:149], v[98:113]
	v_add_f32_e32 v82, v197, v82
	v_exp_f32_e32 v89, v83
	v_add_f32_e32 v82, v86, v82
	v_add_f32_e32 v82, v87, v82
	v_add_f32_e32 v82, v88, v82
	v_add_f32_e32 v82, v89, v82
	v_add_u32_e32 v198, s21, v1
	s_waitcnt lgkmcnt(0)
	v_mfma_f32_32x32x16_f16 v[114:129], v[66:69], v[130:133], v[114:129]
	v_sub_f32_e32 v66, v90, v191
	v_exp_f32_e32 v90, v66
	v_sub_f32_e32 v67, v91, v191
	v_exp_f32_e32 v91, v67
	v_sub_f32_e32 v67, v92, v191
	v_exp_f32_e32 v92, v67
	v_sub_f32_e32 v67, v93, v191
	v_exp_f32_e32 v93, v67
	v_sub_f32_e32 v67, v94, v191
	v_add_f32_e32 v66, v90, v82
	v_exp_f32_e32 v94, v67
	v_sub_f32_e32 v67, v95, v191
	v_add_f32_e32 v66, v91, v66
	v_exp_f32_e32 v95, v67
	v_sub_f32_e32 v67, v96, v191
	v_add_f32_e32 v66, v92, v66
	v_exp_f32_e32 v96, v67
	v_sub_f32_e32 v67, v97, v191
	v_mfma_f32_32x32x16_f16 v[98:113], v[70:73], v[130:133], v[98:113]
	v_add_f32_e32 v66, v93, v66
	v_exp_f32_e32 v97, v67
	v_add_f32_e32 v66, v94, v66
	v_add_f32_e32 v66, v95, v66
	v_add_f32_e32 v66, v96, v66
	v_add_f32_e32 v66, v97, v66
	v_add_f32_e32 v193, v193, v66
	ds_read_b64_tr_b16 v[66:67], v198 offset:0
	v_add_u32_e32 v199, s21, v192
	ds_read_b64_tr_b16 v[68:69], v199 offset:0x800
	ds_read_b64_tr_b16 v[70:71], v198 offset:0x1000
	v_mfma_f32_32x32x16_f16 v[114:129], v[74:77], v[134:137], v[114:129]
	ds_read_b64_tr_b16 v[72:73], v199 offset:0x1800
	ds_read_b64_tr_b16 v[74:75], v198 offset:0x2000
	ds_read_b64_tr_b16 v[76:77], v199 offset:0x2800
	v_mfma_f32_32x32x16_f16 v[98:113], v[78:81], v[134:137], v[98:113]
	ds_read_b64_tr_b16 v[78:79], v198 offset:0x3000
	ds_read_b64_tr_b16 v[80:81], v199 offset:0x3800
	s_waitcnt lgkmcnt(0)
; #define SBAR() __builtin_amdgcn_sched_barrier(0)
; DI void pv_max(f32x16 (&o)[4], unsigned vb0, unsigned vb1, const f32x16& p0, const f32x16& p1, const f32x16& n0, const f32x16& n1, float& pm) {
;   f16x8 pb[4]; pb[0] = pack8(p0, 0); pb[1] = pack8(p0, 1); pb[2] = pack8(p1, 0); pb[3] = pack8(p1, 1);
;   VFrag fa;
;   float mx = n0[0];
;   pv_rd<0>(fa, vb0, vb1);
;   asm volatile("s_waitcnt lgkmcnt(0)" ::: "memory"); SBAR();
;   pv_mm(o[0], fa, pb);
;   pv_rd<1>(fa, vb0, vb1);
; #pragma unroll
;   for (int r = 1; r < 8; ++r) mx = fmaxf(mx, n0[r]);
;   asm volatile("s_waitcnt lgkmcnt(0)" ::: "memory"); SBAR();
;   pv_mm(o[1], fa, pb);
;   pv_rd<2>(fa, vb0, vb1);
; #pragma unroll
;   for (int r = 8; r < 16; ++r) mx = fmaxf(mx, n0[r]);
;   asm volatile("s_waitcnt lgkmcnt(0)" ::: "memory"); SBAR();
;   pv_mm(o[2], fa, pb);
;   pv_rd<3>(fa, vb0, vb1);
; #pragma unroll
;   for (int r = 0; r < 8; ++r) mx = fmaxf(mx, n1[r]);
;   asm volatile("s_waitcnt lgkmcnt(0)" ::: "memory"); SBAR();
;   pv_mm(o[3], fa, pb);
; #pragma unroll
;   for (int r = 8; r < 16; ++r) mx = fmaxf(mx, n1[r]);
;   pm = mx;
; }
	v_cvt_pk_f16_f32 v85, v220, v221
	v_cvt_pk_f16_f32 v84, v218, v219
	v_cvt_pk_f16_f32 v83, v216, v217
	v_cvt_pk_f16_f32 v82, v214, v215
	s_nop 1
	v_mfma_f32_32x32x16_f16 v[50:65], v[66:69], v[82:85], v[50:65]
	v_cvt_pk_f16_f32 v69, v210, v211
	v_cvt_pk_f16_f32 v68, v208, v209
	v_cvt_pk_f16_f32 v67, v204, v205
	v_cvt_pk_f16_f32 v66, v202, v203
	s_nop 1
	v_mfma_f32_32x32x16_f16 v[50:65], v[70:73], v[66:69], v[50:65]
	v_cvt_pk_f16_f32 v73, v88, v89
	v_cvt_pk_f16_f32 v72, v86, v87
	v_cvt_pk_f16_f32 v71, v196, v197
	v_cvt_pk_f16_f32 v70, v194, v195
	v_max_f32_e32 v194, v115, v115
	v_max_f32_e32 v195, v114, v114
	v_max_f32_e32 v194, v195, v194
	v_mfma_f32_32x32x16_f16 v[50:65], v[74:77], v[70:73], v[50:65]
	v_cvt_pk_f16_f32 v77, v96, v97
	v_cvt_pk_f16_f32 v76, v94, v95
	v_cvt_pk_f16_f32 v75, v92, v93
	v_cvt_pk_f16_f32 v74, v90, v91
	v_max3_f32 v194, v194, v116, v117
	v_max3_f32 v194, v194, v118, v119
	v_max3_f32 v194, v194, v120, v121
	v_mfma_f32_32x32x16_f16 v[50:65], v[78:81], v[74:77], v[50:65]
	ds_read_b64_tr_b16 v[78:79], v198 offset:0x200
	ds_read_b64_tr_b16 v[80:81], v199 offset:0xa00
	ds_read_b64_tr_b16 v[86:87], v198 offset:0x1200
	ds_read_b64_tr_b16 v[88:89], v199 offset:0x1a00
	ds_read_b64_tr_b16 v[90:91], v198 offset:0x2200
	ds_read_b64_tr_b16 v[92:93], v199 offset:0x2a00
	ds_read_b64_tr_b16 v[94:95], v198 offset:0x3200
	ds_read_b64_tr_b16 v[96:97], v199 offset:0x3a00
	s_waitcnt lgkmcnt(0)
	s_nop 0
	v_mfma_f32_32x32x16_f16 v[34:49], v[78:81], v[82:85], v[34:49]
	ds_read_b64_tr_b16 v[78:79], v198 offset:0x400
	ds_read_b64_tr_b16 v[80:81], v199 offset:0xc00
	v_max3_f32 v194, v194, v122, v123
	v_max3_f32 v194, v194, v124, v125
	v_max3_f32 v194, v194, v126, v127
	v_max3_f32 v194, v194, v128, v129
	v_mfma_f32_32x32x16_f16 v[34:49], v[86:89], v[66:69], v[34:49]
	ds_read_b64_tr_b16 v[86:87], v198 offset:0x1400
	ds_read_b64_tr_b16 v[88:89], v199 offset:0x1c00
	v_mfma_f32_32x32x16_f16 v[34:49], v[90:93], v[70:73], v[34:49]
	ds_read_b64_tr_b16 v[90:91], v198 offset:0x2400
	ds_read_b64_tr_b16 v[92:93], v199 offset:0x2c00
	v_mfma_f32_32x32x16_f16 v[34:49], v[94:97], v[74:77], v[34:49]
	ds_read_b64_tr_b16 v[94:95], v198 offset:0x3400
	ds_read_b64_tr_b16 v[96:97], v199 offset:0x3c00
	s_waitcnt lgkmcnt(0)
	v_mfma_f32_32x32x16_f16 v[18:33], v[78:81], v[82:85], v[18:33]
	ds_read_b64_tr_b16 v[78:79], v198 offset:0x600
	ds_read_b64_tr_b16 v[80:81], v199 offset:0xe00
	v_max3_f32 v194, v194, v98, v99
	v_max3_f32 v194, v194, v100, v101
	v_max3_f32 v194, v194, v102, v103
	v_max3_f32 v194, v194, v104, v105
	v_mfma_f32_32x32x16_f16 v[18:33], v[86:89], v[66:69], v[18:33]
	ds_read_b64_tr_b16 v[86:87], v198 offset:0x1600
	ds_read_b64_tr_b16 v[88:89], v199 offset:0x1e00
	v_mfma_f32_32x32x16_f16 v[18:33], v[90:93], v[70:73], v[18:33]
	ds_read_b64_tr_b16 v[90:91], v198 offset:0x2600
	ds_read_b64_tr_b16 v[92:93], v199 offset:0x2e00
	v_mfma_f32_32x32x16_f16 v[18:33], v[94:97], v[74:77], v[18:33]
	ds_read_b64_tr_b16 v[94:95], v198 offset:0x3600
	ds_read_b64_tr_b16 v[96:97], v199 offset:0x3e00
	s_waitcnt lgkmcnt(0)
	v_mfma_f32_32x32x16_f16 v[2:17], v[78:81], v[82:85], v[2:17]
	v_mfma_f32_32x32x16_f16 v[2:17], v[86:89], v[66:69], v[2:17]
	v_max3_f32 v66, v194, v106, v107
	v_max3_f32 v66, v66, v108, v109
	v_max3_f32 v66, v66, v110, v111
	v_max3_f32 v66, v66, v112, v113
	v_mov_b32_e32 v67, v66
	s_nop 1
	v_permlane32_swap_b32_e32 v66, v67
	v_mfma_f32_32x32x16_f16 v[2:17], v[90:93], v[70:73], v[2:17]
	v_max_f32_e32 v67, v67, v67
	v_max_f32_e32 v66, v66, v66
	v_max_f32_e32 v66, v66, v67
	v_sub_f32_e32 v67, v66, v191
	v_cmp_ge_f32_e32 vcc, s73, v67
	s_cmp_eq_u64 vcc, exec
	v_mfma_f32_32x32x16_f16 v[2:17], v[94:97], v[74:77], v[2:17]
	s_cbranch_scc1 .LBB0_720
	v_max_f32_e32 v66, v66, v66
	v_max_f32_e32 v67, v191, v191
	v_max_f32_e32 v67, v67, v66
	v_sub_f32_e32 v66, v191, v67
	v_exp_f32_e32 v66, v66
	v_mov_b32_e32 v191, v67
	v_mul_f32_e32 v193, v193, v66
	v_pk_mul_f32 v[64:65], v[64:65], v[66:67] op_sel_hi:[1,0]
	v_pk_mul_f32 v[62:63], v[62:63], v[66:67] op_sel_hi:[1,0]
	v_pk_mul_f32 v[60:61], v[60:61], v[66:67] op_sel_hi:[1,0]
	v_pk_mul_f32 v[58:59], v[58:59], v[66:67] op_sel_hi:[1,0]
	v_pk_mul_f32 v[56:57], v[56:57], v[66:67] op_sel_hi:[1,0]
	v_pk_mul_f32 v[54:55], v[54:55], v[66:67] op_sel_hi:[1,0]
	v_pk_mul_f32 v[52:53], v[52:53], v[66:67] op_sel_hi:[1,0]
	v_pk_mul_f32 v[50:51], v[50:51], v[66:67] op_sel_hi:[1,0]
	v_pk_mul_f32 v[48:49], v[48:49], v[66:67] op_sel_hi:[1,0]
	v_pk_mul_f32 v[46:47], v[46:47], v[66:67] op_sel_hi:[1,0]
	v_pk_mul_f32 v[44:45], v[44:45], v[66:67] op_sel_hi:[1,0]
	v_pk_mul_f32 v[42:43], v[42:43], v[66:67] op_sel_hi:[1,0]
	v_pk_mul_f32 v[40:41], v[40:41], v[66:67] op_sel_hi:[1,0]
	v_pk_mul_f32 v[38:39], v[38:39], v[66:67] op_sel_hi:[1,0]
	v_pk_mul_f32 v[36:37], v[36:37], v[66:67] op_sel_hi:[1,0]
	v_pk_mul_f32 v[34:35], v[34:35], v[66:67] op_sel_hi:[1,0]
	v_pk_mul_f32 v[32:33], v[32:33], v[66:67] op_sel_hi:[1,0]
	v_pk_mul_f32 v[30:31], v[30:31], v[66:67] op_sel_hi:[1,0]
	v_pk_mul_f32 v[28:29], v[28:29], v[66:67] op_sel_hi:[1,0]
	v_pk_mul_f32 v[26:27], v[26:27], v[66:67] op_sel_hi:[1,0]
	v_pk_mul_f32 v[24:25], v[24:25], v[66:67] op_sel_hi:[1,0]
	v_pk_mul_f32 v[22:23], v[22:23], v[66:67] op_sel_hi:[1,0]
	v_pk_mul_f32 v[20:21], v[20:21], v[66:67] op_sel_hi:[1,0]
	v_pk_mul_f32 v[18:19], v[18:19], v[66:67] op_sel_hi:[1,0]
	v_pk_mul_f32 v[16:17], v[16:17], v[66:67] op_sel_hi:[1,0]
	v_pk_mul_f32 v[14:15], v[14:15], v[66:67] op_sel_hi:[1,0]
	v_pk_mul_f32 v[12:13], v[12:13], v[66:67] op_sel_hi:[1,0]
	v_pk_mul_f32 v[10:11], v[10:11], v[66:67] op_sel_hi:[1,0]
	v_pk_mul_f32 v[8:9], v[8:9], v[66:67] op_sel_hi:[1,0]
	v_pk_mul_f32 v[6:7], v[6:7], v[66:67] op_sel_hi:[1,0]
	v_pk_mul_f32 v[4:5], v[4:5], v[66:67] op_sel_hi:[1,0]
	v_pk_mul_f32 v[2:3], v[2:3], v[66:67] op_sel_hi:[1,0]

; #define MFMA(a, b, c) __builtin_amdgcn_mfma_f32_32x32x16_f16((a), (b), (c), 0, 0, 0)
; #define QK_LD(dst, s0) do { dst[0] = *(const f16x8*)(Kst + kbe + 512 * ((s0) >> 1)); dst[1] = *(const f16x8*)(Kst + kbe + 512 * ((s0) >> 1) + 8192); \
;     dst[2] = *(const f16x8*)(Kst + kbo + 512 * ((s0) >> 1)); dst[3] = *(const f16x8*)(Kst + kbo + 512 * ((s0) >> 1) + 8192); } while (0)
; #define QK_LD(dst, s0) do { dst[0] = *(const f16x8*)(Kst + kbe + 512 * ((s0) >> 1)); dst[1] = *(const f16x8*)(Kst + kbe + 512 * ((s0) >> 1) + 8192); \
;     dst[2] = *(const f16x8*)(Kst + kbo + 512 * ((s0) >> 1)); dst[3] = *(const f16x8*)(Kst + kbo + 512 * ((s0) >> 1) + 8192); } while (0)
; DI void qk_exp(f32x16& n0, f32x16& n1, const char* Kst, const f16x8 (&qf)[8], unsigned kbe, unsigned kbo, f32x16& c0, f32x16& c1, float me, float& ps) {
;     ...
;   float s_ = 0.f;
;   QK_LD(ka, 0);
;   n0 = MFMA(ka[0], qf[0], zero); n1 = MFMA(ka[1], qf[0], zero); n0 = MFMA(ka[2], qf[1], n0); n1 = MFMA(ka[3], qf[1], n1);
.LBB0_731:
	s_add_i32 s22, s5, 4
	s_cmp_le_i32 s20, s22
	s_cselect_b64 s[0:1], -1, 0
	s_cmp_lt_i32 s20, s12
	s_waitcnt lgkmcnt(0)
	s_barrier
	s_cselect_b64 s[24:25], -1, 0
	s_xor_b32 s100, s21, 0x10000
	v_add_u32_e32 v212, s100, v190
	ds_read_b128 v[66:69], v212
	ds_read_b128 v[82:85], v212 offset:8192
	v_add_u32_e32 v213, s100, v189
	ds_read_b128 v[194:197], v213
	ds_read_b128 v[198:201], v213 offset:8192
	s_and_b64 s[0:1], s[0:1], s[24:25]
	s_andn2_b64 vcc, exec, s[0:1]
	s_cbranch_vccnz .LBB0_742
	s_sub_i32 s0, s16, s20
	s_lshl_b32 s23, s0, 6
	s_sub_i32 s0, s15, s20
	s_lshl_b32 s24, s0, 6
	s_lshl_b32 s25, s20, 14
	s_lshl_b32 s26, s20, 15
	s_and_b32 s18, s26, 0x18000
	s_cmp_gt_i32 s20, 1
	s_mov_b64 s[0:1], -1
	s_cbranch_scc0 .LBB0_739
	s_branch .LBB0_734

.LBB0_734:
	s_cmp_ge_i32 s20, s14
	s_cbranch_scc0 .LBB0_736
	s_mul_i32 s1, s23, 0x3000
	s_mul_hi_i32 s0, s23, 0x3000
	s_add_u32 s27, s61, s1
	s_addc_u32 s29, s3, s0
	s_add_u32 s0, s27, s6
	s_addc_u32 s1, s29, 0
	s_add_u32 s28, s27, s7
	s_addc_u32 s29, s29, 0
	v_lshl_add_u64 v[218:219], s[0:1], 0, v[206:207]
	s_add_i32 s0, s18, s60
	s_mov_b32 m0, s0
	s_nop 0
	global_load_lds_dwordx4 v[218:219], off
	v_lshl_add_u64 v[218:219], v[218:219], 0, s[86:87]
	s_add_i32 m0, s0, 0x2000
	s_nop 0
	global_load_lds_dwordx4 v[218:219], off
	v_lshl_add_u64 v[218:219], s[28:29], 0, v[206:207]
	s_add_i32 m0, s0, 0x4000
	s_mov_b64 s[0:1], 0
	global_load_lds_dwordx4 v[218:219], off
	v_lshl_add_u64 v[218:219], v[218:219], 0, s[86:87]
.LBB0_736:
	s_andn2_b64 vcc, exec, s[0:1]
	s_cbranch_vccnz .LBB0_738
	s_mul_i32 s1, s24, 0x3000
	s_mul_hi_i32 s0, s24, 0x3000
	s_add_u32 s27, s61, s1
	s_addc_u32 s29, s3, s0
	s_add_u32 s0, s27, s8
	s_addc_u32 s1, s29, 0
	s_add_u32 s28, s27, s9
	s_addc_u32 s29, s29, 0
	v_lshl_add_u64 v[218:219], s[0:1], 0, v[206:207]
	s_add_i32 s0, s18, s60
	s_mov_b32 m0, s0
	s_nop 0
	global_load_lds_dwordx4 v[218:219], off
	v_lshl_add_u64 v[218:219], v[218:219], 0, s[86:87]
	s_add_i32 m0, s0, 0x2000
	s_nop 0
	global_load_lds_dwordx4 v[218:219], off
	v_lshl_add_u64 v[218:219], s[28:29], 0, v[206:207]
	s_add_i32 m0, s0, 0x4000
	s_nop 0
	global_load_lds_dwordx4 v[218:219], off
	v_lshl_add_u64 v[218:219], v[218:219], 0, s[86:87]

.LBB0_739:
	s_andn2_b64 vcc, exec, s[0:1]
	s_cbranch_vccnz .LBB0_741
	s_ashr_i32 s27, s25, 31
	s_add_u32 s0, s64, s25
	s_addc_u32 s1, s65, s27
	s_add_u32 s28, s80, s25
	s_addc_u32 s29, s81, s27
	v_lshl_add_u64 v[218:219], s[0:1], 0, v[162:163]
	s_add_i32 s0, s18, s60
	s_mov_b32 m0, s0
	s_nop 0
	global_load_lds_dwordx4 v[218:219], off
	v_lshl_add_u64 v[218:219], v[218:219], 0, s[34:35]
	s_add_i32 m0, s0, 0x2000
	s_nop 0
	global_load_lds_dwordx4 v[218:219], off
	v_lshl_add_u64 v[218:219], s[28:29], 0, v[162:163]
	s_add_i32 m0, s0, 0x4000
	s_nop 0
	global_load_lds_dwordx4 v[218:219], off
	v_lshl_add_u64 v[218:219], v[218:219], 0, s[34:35]
.LBB0_741:
	s_add_i32 s0, s18, s60
	s_add_i32 m0, s0, 0x6000
	s_add_i32 s18, s20, 1
	global_load_lds_dwordx4 v[218:219], off
	s_cmp_lt_i32 s20, s22
	s_cselect_b64 s[0:1], -1, 0
	s_cmp_lt_i32 s18, s12
	s_cselect_b64 s[28:29], -1, 0
	s_and_b64 s[0:1], s[0:1], s[28:29]
	s_sub_i32 s23, s23, 64
	s_sub_i32 s24, s24, 64
	s_addk_i32 s25, 0x4000
	s_add_i32 s26, s26, 0x8000
	s_and_b64 vcc, exec, s[0:1]
	s_cbranch_vccnz .LBB0_733
	s_branch .LBB0_743

; #define MFMA(a, b, c) __builtin_amdgcn_mfma_f32_32x32x16_f16((a), (b), (c), 0, 0, 0)
; #define QK_LD(dst, s0) do { dst[0] = *(const f16x8*)(Kst + kbe + 512 * ((s0) >> 1)); dst[1] = *(const f16x8*)(Kst + kbe + 512 * ((s0) >> 1) + 8192); \
;     dst[2] = *(const f16x8*)(Kst + kbo + 512 * ((s0) >> 1)); dst[3] = *(const f16x8*)(Kst + kbo + 512 * ((s0) >> 1) + 8192); } while (0)
; #define QK_LD(dst, s0) do { dst[0] = *(const f16x8*)(Kst + kbe + 512 * ((s0) >> 1)); dst[1] = *(const f16x8*)(Kst + kbe + 512 * ((s0) >> 1) + 8192); \
;     dst[2] = *(const f16x8*)(Kst + kbo + 512 * ((s0) >> 1)); dst[3] = *(const f16x8*)(Kst + kbo + 512 * ((s0) >> 1) + 8192); } while (0)
; #define EXP8(c, b0) do { _Pragma("unroll") for (int j_ = 0; j_ < 8; ++j_) { c[(b0) + j_] = fexp2(c[(b0) + j_] - me); s_ += c[(b0) + j_]; } } while (0)
; DI void qk_exp(f32x16& n0, f32x16& n1, const char* Kst, const f16x8 (&qf)[8], unsigned kbe, unsigned kbo, f32x16& c0, f32x16& c1, float me, float& ps) {
;   const f32x16 zero = {0.f, 0.f, 0.f, 0.f, 0.f, 0.f, 0.f, 0.f, 0.f, 0.f, 0.f, 0.f, 0.f, 0.f, 0.f, 0.f};
;   f16x8 ka[4], kb[4];
;     ...
;   float s_ = 0.f;
;   QK_LD(ka, 0);
;   n0 = MFMA(ka[0], qf[0], zero); n1 = MFMA(ka[1], qf[0], zero); n0 = MFMA(ka[2], qf[1], n0); n1 = MFMA(ka[3], qf[1], n1);
;   QK_LD(kb, 2);
;   EXP8(c0, 0);
;   n0 = MFMA(kb[0], qf[2], n0); n1 = MFMA(kb[1], qf[2], n1); n0 = MFMA(kb[2], qf[3], n0); n1 = MFMA(kb[3], qf[3], n1);
;   QK_LD(ka, 4);
;   EXP8(c0, 8);
;   n0 = MFMA(ka[0], qf[4], n0); n1 = MFMA(ka[1], qf[4], n1); n0 = MFMA(ka[2], qf[5], n0); n1 = MFMA(ka[3], qf[5], n1);
;   QK_LD(kb, 6);
;   EXP8(c1, 0);
;   n0 = MFMA(kb[0], qf[6], n0); n1 = MFMA(kb[1], qf[6], n1); n0 = MFMA(kb[2], qf[7], n0); n1 = MFMA(kb[3], qf[7], n1);
;   EXP8(c1, 8);
;   ps = s_;
;     ...
; }
; DI void pv_max(f32x16 (&o)[4], unsigned vb0, unsigned vb1, const f32x16& p0, const f32x16& p1, const f32x16& n0, const f32x16& n1, float& pm) {
;   f16x8 pb[4]; pb[0] = pack8(p0, 0); pb[1] = pack8(p0, 1); pb[2] = pack8(p1, 0); pb[3] = pack8(p1, 1);
;   VFrag fa;
;   float mx = n0[0];
;   pv_rd<0>(fa, vb0, vb1);
.LBB0_743:
	v_sub_f32_e32 v114, v114, v191
	s_waitcnt lgkmcnt(0)
	v_mfma_f32_32x32x16_f16 v[66:81], v[66:69], v[150:153], 0
	v_exp_f32_e32 v214, v114
	v_sub_f32_e32 v115, v115, v191
	v_exp_f32_e32 v215, v115
	v_sub_f32_e32 v115, v116, v191
	v_exp_f32_e32 v216, v115
	v_sub_f32_e32 v115, v117, v191
	v_exp_f32_e32 v217, v115
	v_mfma_f32_32x32x16_f16 v[82:97], v[82:85], v[150:153], 0
	v_sub_f32_e32 v115, v118, v191
	v_add_f32_e32 v114, 0, v214
	v_exp_f32_e32 v218, v115
	v_sub_f32_e32 v115, v119, v191
	v_add_f32_e32 v114, v215, v114
	v_exp_f32_e32 v219, v115
	v_sub_f32_e32 v115, v120, v191
	v_mfma_f32_32x32x16_f16 v[66:81], v[194:197], v[158:161], v[66:81]
	v_add_f32_e32 v114, v216, v114
	v_exp_f32_e32 v220, v115
	v_sub_f32_e32 v115, v121, v191
	v_add_f32_e32 v114, v217, v114
	v_exp_f32_e32 v221, v115
	v_add_f32_e32 v114, v218, v114
	v_add_f32_e32 v114, v219, v114
	v_mfma_f32_32x32x16_f16 v[82:97], v[198:201], v[158:161], v[82:97]
	ds_read_b128 v[194:197], v212 offset:512
	ds_read_b128 v[198:201], v212 offset:8704
	ds_read_b128 v[202:205], v213 offset:512
	ds_read_b128 v[208:211], v213 offset:8704
	v_add_f32_e32 v114, v220, v114
	v_add_f32_e32 v224, v221, v114
	v_sub_f32_e32 v122, v122, v191
	v_sub_f32_e32 v123, v123, v191
	v_sub_f32_e32 v98, v98, v191
	v_sub_f32_e32 v99, v99, v191
	s_waitcnt lgkmcnt(0)
	v_mfma_f32_32x32x16_f16 v[66:81], v[194:197], v[142:145], v[66:81]
	v_mfma_f32_32x32x16_f16 v[82:97], v[198:201], v[142:145], v[82:97]
	ds_read_b128 v[114:117], v212 offset:1024
	ds_read_b128 v[118:121], v212 offset:9216
	ds_read_b128 v[194:197], v213 offset:1024
	ds_read_b128 v[198:201], v213 offset:9216
	v_mfma_f32_32x32x16_f16 v[66:81], v[202:205], v[154:157], v[66:81]
	v_exp_f32_e32 v202, v122
	v_exp_f32_e32 v203, v123
	v_sub_f32_e32 v123, v124, v191
	v_exp_f32_e32 v204, v123
	v_sub_f32_e32 v123, v125, v191
	v_exp_f32_e32 v205, v123
	v_sub_f32_e32 v123, v126, v191
	v_mfma_f32_32x32x16_f16 v[82:97], v[208:211], v[154:157], v[82:97]
	v_add_f32_e32 v122, v202, v224
	v_exp_f32_e32 v208, v123
	v_sub_f32_e32 v123, v127, v191
	v_add_f32_e32 v122, v203, v122
	v_exp_f32_e32 v209, v123
	v_sub_f32_e32 v123, v128, v191
	v_add_f32_e32 v122, v204, v122
	s_waitcnt lgkmcnt(0)
	v_mfma_f32_32x32x16_f16 v[66:81], v[114:117], v[138:141], v[66:81]
	v_exp_f32_e32 v210, v123
	v_sub_f32_e32 v123, v129, v191
	v_add_f32_e32 v122, v205, v122
	v_exp_f32_e32 v211, v123
	v_add_f32_e32 v122, v208, v122
	v_add_f32_e32 v122, v209, v122
	v_add_f32_e32 v122, v210, v122
	v_mfma_f32_32x32x16_f16 v[82:97], v[118:121], v[138:141], v[82:97]
	v_add_f32_e32 v224, v211, v122
	ds_read_b128 v[114:117], v212 offset:1536
	ds_read_b128 v[118:121], v212 offset:9728
	ds_read_b128 v[122:125], v213 offset:1536
	ds_read_b128 v[126:129], v213 offset:9728
	v_add_u32_e32 v212, s19, v1
	v_add_u32_e32 v213, s19, v192
	v_mfma_f32_32x32x16_f16 v[66:81], v[194:197], v[146:149], v[66:81]
	v_exp_f32_e32 v194, v98
	v_exp_f32_e32 v195, v99
	v_sub_f32_e32 v99, v100, v191
	v_exp_f32_e32 v196, v99
	v_sub_f32_e32 v99, v101, v191
	v_exp_f32_e32 v197, v99
	v_sub_f32_e32 v99, v102, v191
	v_mfma_f32_32x32x16_f16 v[82:97], v[198:201], v[146:149], v[82:97]
	v_add_f32_e32 v98, v194, v224
	v_exp_f32_e32 v198, v99
	v_sub_f32_e32 v99, v103, v191
	v_add_f32_e32 v98, v195, v98
	v_exp_f32_e32 v199, v99
	v_sub_f32_e32 v99, v104, v191
	v_add_f32_e32 v98, v196, v98
	s_waitcnt lgkmcnt(0)
	v_mfma_f32_32x32x16_f16 v[66:81], v[114:117], v[130:133], v[66:81]
	v_exp_f32_e32 v200, v99
	v_sub_f32_e32 v99, v105, v191
	v_add_f32_e32 v98, v197, v98
	v_exp_f32_e32 v201, v99
	v_sub_f32_e32 v99, v106, v191
	v_add_f32_e32 v98, v198, v98
	v_add_f32_e32 v98, v199, v98
	v_mfma_f32_32x32x16_f16 v[82:97], v[118:121], v[130:133], v[82:97]
	v_exp_f32_e32 v118, v99
	v_sub_f32_e32 v99, v107, v191
	v_exp_f32_e32 v119, v99
	v_sub_f32_e32 v99, v108, v191
	v_add_f32_e32 v98, v200, v98
	v_exp_f32_e32 v120, v99
	v_sub_f32_e32 v99, v109, v191
	v_add_f32_e32 v98, v201, v98
	v_exp_f32_e32 v121, v99
	v_sub_f32_e32 v99, v110, v191
	v_mfma_f32_32x32x16_f16 v[66:81], v[122:125], v[134:137], v[66:81]
	v_add_f32_e32 v98, v118, v98
	v_exp_f32_e32 v122, v99
	v_sub_f32_e32 v99, v111, v191
	v_add_f32_e32 v98, v119, v98
	v_exp_f32_e32 v123, v99
	v_sub_f32_e32 v99, v112, v191
	v_add_f32_e32 v98, v120, v98
	v_exp_f32_e32 v124, v99
	v_sub_f32_e32 v99, v113, v191
	v_add_f32_e32 v98, v121, v98
	v_exp_f32_e32 v125, v99
	v_add_f32_e32 v98, v122, v98
	v_add_f32_e32 v98, v123, v98
	v_add_f32_e32 v98, v124, v98
	v_add_f32_e32 v98, v125, v98
	v_add_f32_e32 v193, v193, v98
	ds_read_b64_tr_b16 v[98:99], v212 offset:0
	ds_read_b64_tr_b16 v[100:101], v213 offset:0x800
	ds_read_b64_tr_b16 v[102:103], v212 offset:0x1000
	v_mfma_f32_32x32x16_f16 v[82:97], v[126:129], v[134:137], v[82:97]
	ds_read_b64_tr_b16 v[104:105], v213 offset:0x1800
	ds_read_b64_tr_b16 v[106:107], v212 offset:0x2000
	ds_read_b64_tr_b16 v[108:109], v213 offset:0x2800
	ds_read_b64_tr_b16 v[110:111], v212 offset:0x3000
	ds_read_b64_tr_b16 v[112:113], v213 offset:0x3800
	s_waitcnt lgkmcnt(0)
; #define SBAR() __builtin_amdgcn_sched_barrier(0)
; DI float fexp2(float x) { return __builtin_amdgcn_exp2f(x); }
; DI void pv_max(f32x16 (&o)[4], unsigned vb0, unsigned vb1, const f32x16& p0, const f32x16& p1, const f32x16& n0, const f32x16& n1, float& pm) {
;   f16x8 pb[4]; pb[0] = pack8(p0, 0); pb[1] = pack8(p0, 1); pb[2] = pack8(p1, 0); pb[3] = pack8(p1, 1);
;   VFrag fa;
;   float mx = n0[0];
;   pv_rd<0>(fa, vb0, vb1);
;   asm volatile("s_waitcnt lgkmcnt(0)" ::: "memory"); SBAR();
;   pv_mm(o[0], fa, pb);
;   pv_rd<1>(fa, vb0, vb1);
; #pragma unroll
;   for (int r = 1; r < 8; ++r) mx = fmaxf(mx, n0[r]);
;   asm volatile("s_waitcnt lgkmcnt(0)" ::: "memory"); SBAR();
;   pv_mm(o[1], fa, pb);
;   pv_rd<2>(fa, vb0, vb1);
; #pragma unroll
;   for (int r = 8; r < 16; ++r) mx = fmaxf(mx, n0[r]);
;   asm volatile("s_waitcnt lgkmcnt(0)" ::: "memory"); SBAR();
;   pv_mm(o[2], fa, pb);
;   pv_rd<3>(fa, vb0, vb1);
; #pragma unroll
;   for (int r = 0; r < 8; ++r) mx = fmaxf(mx, n1[r]);
;   asm volatile("s_waitcnt lgkmcnt(0)" ::: "memory"); SBAR();
;   pv_mm(o[3], fa, pb);
; #pragma unroll
;   for (int r = 8; r < 16; ++r) mx = fmaxf(mx, n1[r]);
;   pm = mx;
; }
; DI void osm_decide(float pmn, float& m, float& l, f32x16 (&o)[4]) {
;   if (!__all(pmn - m <= THR)) {
;     float mn = fmaxf(m, pmn); float alpha = fexp2(m - mn); m = mn; l *= alpha;
; #pragma unroll
;     for (int d = 0; d < 4; ++d)
; #pragma unroll
;       for (int r = 0; r < 16; ++r) o[d][r] *= alpha;
;   }
; }
	v_cvt_pk_f16_f32 v117, v220, v221
	v_cvt_pk_f16_f32 v116, v218, v219
	v_cvt_pk_f16_f32 v115, v216, v217
	v_cvt_pk_f16_f32 v114, v214, v215
	s_nop 1
	v_mfma_f32_32x32x16_f16 v[50:65], v[98:101], v[114:117], v[50:65]
	v_cvt_pk_f16_f32 v101, v210, v211
	v_cvt_pk_f16_f32 v100, v208, v209
	v_cvt_pk_f16_f32 v99, v204, v205
	v_cvt_pk_f16_f32 v98, v202, v203
	s_nop 1
	v_mfma_f32_32x32x16_f16 v[50:65], v[102:105], v[98:101], v[50:65]
	v_cvt_pk_f16_f32 v105, v200, v201
	v_cvt_pk_f16_f32 v104, v198, v199
	v_cvt_pk_f16_f32 v103, v196, v197
	v_cvt_pk_f16_f32 v102, v194, v195
	v_max_f32_e32 v194, v67, v67
	v_max_f32_e32 v195, v66, v66
	v_max_f32_e32 v194, v195, v194
	v_mfma_f32_32x32x16_f16 v[50:65], v[106:109], v[102:105], v[50:65]
	v_cvt_pk_f16_f32 v109, v124, v125
	v_cvt_pk_f16_f32 v108, v122, v123
	v_cvt_pk_f16_f32 v107, v120, v121
	v_cvt_pk_f16_f32 v106, v118, v119
	v_max3_f32 v194, v194, v68, v69
	v_max3_f32 v194, v194, v70, v71
	v_max3_f32 v194, v194, v72, v73
	v_mfma_f32_32x32x16_f16 v[50:65], v[110:113], v[106:109], v[50:65]
	ds_read_b64_tr_b16 v[110:111], v212 offset:0x200
	ds_read_b64_tr_b16 v[112:113], v213 offset:0xa00
	ds_read_b64_tr_b16 v[118:119], v212 offset:0x1200
	ds_read_b64_tr_b16 v[120:121], v213 offset:0x1a00
	ds_read_b64_tr_b16 v[122:123], v212 offset:0x2200
	ds_read_b64_tr_b16 v[124:125], v213 offset:0x2a00
	ds_read_b64_tr_b16 v[126:127], v212 offset:0x3200
	ds_read_b64_tr_b16 v[128:129], v213 offset:0x3a00
	s_waitcnt lgkmcnt(0)
	s_nop 0
	v_mfma_f32_32x32x16_f16 v[34:49], v[110:113], v[114:117], v[34:49]
	ds_read_b64_tr_b16 v[110:111], v212 offset:0x400
	ds_read_b64_tr_b16 v[112:113], v213 offset:0xc00
	v_max3_f32 v194, v194, v74, v75
	v_max3_f32 v194, v194, v76, v77
	v_max3_f32 v194, v194, v78, v79
	v_max3_f32 v194, v194, v80, v81
	v_mfma_f32_32x32x16_f16 v[34:49], v[118:121], v[98:101], v[34:49]
	ds_read_b64_tr_b16 v[118:119], v212 offset:0x1400
	ds_read_b64_tr_b16 v[120:121], v213 offset:0x1c00
	v_mfma_f32_32x32x16_f16 v[34:49], v[122:125], v[102:105], v[34:49]
	ds_read_b64_tr_b16 v[122:123], v212 offset:0x2400
	ds_read_b64_tr_b16 v[124:125], v213 offset:0x2c00
	v_mfma_f32_32x32x16_f16 v[34:49], v[126:129], v[106:109], v[34:49]
	ds_read_b64_tr_b16 v[126:127], v212 offset:0x3400
	ds_read_b64_tr_b16 v[128:129], v213 offset:0x3c00
	s_waitcnt lgkmcnt(0)
	v_mfma_f32_32x32x16_f16 v[18:33], v[110:113], v[114:117], v[18:33]
	ds_read_b64_tr_b16 v[110:111], v212 offset:0x600
	ds_read_b64_tr_b16 v[112:113], v213 offset:0xe00
	v_max3_f32 v194, v194, v82, v83
	v_max3_f32 v194, v194, v84, v85
	v_max3_f32 v194, v194, v86, v87
	v_max3_f32 v194, v194, v88, v89
	v_mfma_f32_32x32x16_f16 v[18:33], v[118:121], v[98:101], v[18:33]
	ds_read_b64_tr_b16 v[118:119], v212 offset:0x1600
	ds_read_b64_tr_b16 v[120:121], v213 offset:0x1e00
	v_mfma_f32_32x32x16_f16 v[18:33], v[122:125], v[102:105], v[18:33]
	ds_read_b64_tr_b16 v[122:123], v212 offset:0x2600
	ds_read_b64_tr_b16 v[124:125], v213 offset:0x2e00
	v_mfma_f32_32x32x16_f16 v[18:33], v[126:129], v[106:109], v[18:33]
	ds_read_b64_tr_b16 v[126:127], v212 offset:0x3600
	ds_read_b64_tr_b16 v[128:129], v213 offset:0x3e00
	s_waitcnt lgkmcnt(0)
	v_mfma_f32_32x32x16_f16 v[2:17], v[110:113], v[114:117], v[2:17]
	v_mfma_f32_32x32x16_f16 v[2:17], v[118:121], v[98:101], v[2:17]
	v_max3_f32 v98, v194, v90, v91
	v_max3_f32 v98, v98, v92, v93
	v_max3_f32 v98, v98, v94, v95
	v_max3_f32 v98, v98, v96, v97
	v_mov_b32_e32 v99, v98
	s_nop 1
	v_permlane32_swap_b32_e32 v98, v99
	v_mfma_f32_32x32x16_f16 v[2:17], v[122:125], v[102:105], v[2:17]
	v_max_f32_e32 v99, v99, v99
	v_max_f32_e32 v98, v98, v98
	v_max_f32_e32 v98, v98, v99
	v_sub_f32_e32 v99, v98, v191
	v_cmp_ge_f32_e32 vcc, s73, v99
	s_cmp_eq_u64 vcc, exec
	v_mfma_f32_32x32x16_f16 v[2:17], v[126:129], v[106:109], v[2:17]
	s_cbranch_scc1 .LBB0_694
	v_max_f32_e32 v98, v98, v98
	v_max_f32_e32 v99, v191, v191
	v_max_f32_e32 v99, v99, v98
	v_sub_f32_e32 v98, v191, v99
	v_exp_f32_e32 v98, v98
	v_mov_b32_e32 v191, v99
	v_mul_f32_e32 v193, v193, v98
	v_pk_mul_f32 v[64:65], v[64:65], v[98:99] op_sel_hi:[1,0]
	v_pk_mul_f32 v[62:63], v[62:63], v[98:99] op_sel_hi:[1,0]
	v_pk_mul_f32 v[60:61], v[60:61], v[98:99] op_sel_hi:[1,0]
	v_pk_mul_f32 v[58:59], v[58:59], v[98:99] op_sel_hi:[1,0]
	v_pk_mul_f32 v[56:57], v[56:57], v[98:99] op_sel_hi:[1,0]
	v_pk_mul_f32 v[54:55], v[54:55], v[98:99] op_sel_hi:[1,0]
	v_pk_mul_f32 v[52:53], v[52:53], v[98:99] op_sel_hi:[1,0]
	v_pk_mul_f32 v[50:51], v[50:51], v[98:99] op_sel_hi:[1,0]
	v_pk_mul_f32 v[48:49], v[48:49], v[98:99] op_sel_hi:[1,0]
	v_pk_mul_f32 v[46:47], v[46:47], v[98:99] op_sel_hi:[1,0]
	v_pk_mul_f32 v[44:45], v[44:45], v[98:99] op_sel_hi:[1,0]
	v_pk_mul_f32 v[42:43], v[42:43], v[98:99] op_sel_hi:[1,0]
	v_pk_mul_f32 v[40:41], v[40:41], v[98:99] op_sel_hi:[1,0]
	v_pk_mul_f32 v[38:39], v[38:39], v[98:99] op_sel_hi:[1,0]
	v_pk_mul_f32 v[36:37], v[36:37], v[98:99] op_sel_hi:[1,0]
	v_pk_mul_f32 v[34:35], v[34:35], v[98:99] op_sel_hi:[1,0]
	v_pk_mul_f32 v[32:33], v[32:33], v[98:99] op_sel_hi:[1,0]
	v_pk_mul_f32 v[30:31], v[30:31], v[98:99] op_sel_hi:[1,0]
	v_pk_mul_f32 v[28:29], v[28:29], v[98:99] op_sel_hi:[1,0]
	v_pk_mul_f32 v[26:27], v[26:27], v[98:99] op_sel_hi:[1,0]
	v_pk_mul_f32 v[24:25], v[24:25], v[98:99] op_sel_hi:[1,0]
	v_pk_mul_f32 v[22:23], v[22:23], v[98:99] op_sel_hi:[1,0]
	v_pk_mul_f32 v[20:21], v[20:21], v[98:99] op_sel_hi:[1,0]
	v_pk_mul_f32 v[18:19], v[18:19], v[98:99] op_sel_hi:[1,0]
	v_pk_mul_f32 v[16:17], v[16:17], v[98:99] op_sel_hi:[1,0]
	v_pk_mul_f32 v[14:15], v[14:15], v[98:99] op_sel_hi:[1,0]
	v_pk_mul_f32 v[12:13], v[12:13], v[98:99] op_sel_hi:[1,0]
	v_pk_mul_f32 v[10:11], v[10:11], v[98:99] op_sel_hi:[1,0]
	v_pk_mul_f32 v[8:9], v[8:9], v[98:99] op_sel_hi:[1,0]
	v_pk_mul_f32 v[6:7], v[6:7], v[98:99] op_sel_hi:[1,0]
	v_pk_mul_f32 v[4:5], v[4:5], v[98:99] op_sel_hi:[1,0]
	v_pk_mul_f32 v[2:3], v[2:3], v[98:99] op_sel_hi:[1,0]
	s_branch .LBB0_694

; template <int PH>
; __global__ void __launch_bounds__(512, 2) hybrid_kernel(Params p) {
;   __shared__ __attribute__((aligned(16))) char smem[LDS_BYTES];
	.amdhsa_kernel _Z13hybrid_kernelILin1EEv6Params
		.amdhsa_group_segment_fixed_size 147520
		.amdhsa_private_segment_fixed_size 0
		.amdhsa_kernarg_size 408
		.amdhsa_user_sgpr_count 2
		.amdhsa_user_sgpr_dispatch_ptr 0
		.amdhsa_user_sgpr_queue_ptr 0
		.amdhsa_user_sgpr_kernarg_segment_ptr 1
		.amdhsa_user_sgpr_dispatch_id 0
		.amdhsa_user_sgpr_kernarg_preload_length 0
		.amdhsa_user_sgpr_kernarg_preload_offset 0
		.amdhsa_user_sgpr_private_segment_size 0
		.amdhsa_uses_dynamic_stack 0
		.amdhsa_enable_private_segment 0
		.amdhsa_system_sgpr_workgroup_id_x 1
		.amdhsa_system_sgpr_workgroup_id_y 0
		.amdhsa_system_sgpr_workgroup_id_z 0
		.amdhsa_system_sgpr_workgroup_info 0
		.amdhsa_system_vgpr_workitem_id 0
		.amdhsa_next_free_vgpr 256
		.amdhsa_next_free_sgpr 101
		.amdhsa_accum_offset 256
		.amdhsa_reserve_vcc 1
		.amdhsa_float_round_mode_32 0
		.amdhsa_float_round_mode_16_64 0
		.amdhsa_float_denorm_mode_32 3
		.amdhsa_float_denorm_mode_16_64 3
		.amdhsa_dx10_clamp 1
		.amdhsa_ieee_mode 1
		.amdhsa_fp16_overflow 0
		.amdhsa_tg_split 0
		.amdhsa_exception_fp_ieee_invalid_op 0
		.amdhsa_exception_fp_denorm_src 0
		.amdhsa_exception_fp_ieee_div_zero 0
		.amdhsa_exception_fp_ieee_overflow 0
		.amdhsa_exception_fp_ieee_underflow 0
		.amdhsa_exception_fp_ieee_inexact 0
		.amdhsa_exception_int_div_zero 0
	.end_amdhsa_kernel

; template <int PH>
; __global__ void __launch_bounds__(512, 2) hybrid_kernel(Params p) {
amdhsa.kernels:
  - .agpr_count:     0
    .args:
      - .offset:         0
        .size:           152
        .value_kind:     by_value
      - .offset:         152
        .size:           4
        .value_kind:     hidden_block_count_x
      - .offset:         156
        .size:           4
        .value_kind:     hidden_block_count_y
      - .offset:         160
        .size:           4
        .value_kind:     hidden_block_count_z
      - .offset:         164
        .size:           2
        .value_kind:     hidden_group_size_x
      - .offset:         166
        .size:           2
        .value_kind:     hidden_group_size_y
      - .offset:         168
        .size:           2
        .value_kind:     hidden_group_size_z
      - .offset:         170
        .size:           2
        .value_kind:     hidden_remainder_x
      - .offset:         172
        .size:           2
        .value_kind:     hidden_remainder_y
      - .offset:         174
        .size:           2
        .value_kind:     hidden_remainder_z
      - .offset:         192
        .size:           8
        .value_kind:     hidden_global_offset_x
      - .offset:         200
        .size:           8
        .value_kind:     hidden_global_offset_y
      - .offset:         208
        .size:           8
        .value_kind:     hidden_global_offset_z
      - .offset:         216
        .size:           2
        .value_kind:     hidden_grid_dims
    .group_segment_fixed_size: 147520
    .kernarg_segment_align: 8
    .kernarg_segment_size: 408
    .language:       OpenCL C
    .language_version:
      - 2
      - 0
    .max_flat_workgroup_size: 512
    .name:           _Z13hybrid_kernelILin1EEv6Params
    .private_segment_fixed_size: 0
    .sgpr_count:     107
    .sgpr_spill_count: 42
    .symbol:         _Z13hybrid_kernelILin1EEv6Params.kd
    .uniform_work_group_size: 1
    .uses_dynamic_stack: false
    .vgpr_count:     256
    .vgpr_spill_count: 0
    .wavefront_size: 64
